# v30 + page-loop top waits made precise for the back-edge queue order (P1 and both P2 page loops), preheader drains fully
# baseline (speedup 1.0000x reference)
.LBB0_234:
	v_mov_b32_e32 v131, v0
	v_readlane_b32 s16, v245, 9
	v_readfirstlane_b32 s0, v131
	s_ashr_i32 s69, s0, 6
	s_add_u32 s0, s96, 0xce00000
	v_readlane_b32 s17, v245, 10
	s_addc_u32 s1, s97, 0
	s_ashr_i32 s7, s6, 31
	v_readlane_b32 s18, v245, 11
	v_readlane_b32 s19, v245, 12
	s_mov_b64 s[8:9], s[16:17]
	s_lshl_b64 s[2:3], s[6:7], 2
	s_mov_b64 s[10:11], s[18:19]
	s_add_u32 s2, s10, s2
	s_addc_u32 s3, s11, s3
	v_mov_b32_e32 v187, 0
	global_load_dwordx2 v[18:19], v187, s[2:3]
	v_readlane_b32 s20, v245, 13
	v_readlane_b32 s24, v245, 17
	v_readlane_b32 s30, v245, 23
	s_lshl_b32 s12, s69, 4
	v_readlane_b32 s21, v245, 14
	v_readlane_b32 s25, v245, 18
	v_readlane_b32 s31, v245, 24
	s_ashr_i32 s2, s6, 4
	s_or_b32 s10, s12, 1
	s_or_b32 s20, s12, 2
	s_or_b32 s24, s12, 3
	s_or_b32 s30, s12, 4
	s_or_b32 s36, s12, 5
	s_or_b32 s58, s12, 6
	s_or_b32 s4, s12, 7
	s_ashr_i32 s13, s12, 31
	s_ashr_i32 s3, s2, 31
	s_ashr_i32 s11, s10, 31
	s_ashr_i32 s21, s20, 31
	s_ashr_i32 s25, s24, 31
	s_ashr_i32 s31, s30, 31
	s_ashr_i32 s37, s36, 31
	s_ashr_i32 s59, s58, 31
	s_ashr_i32 s5, s4, 31
	s_lshl_b64 s[38:39], s[12:13], 9
	s_lshl_b64 s[2:3], s[2:3], 10
	s_lshl_b64 s[40:41], s[10:11], 9
	s_lshl_b64 s[42:43], s[20:21], 9
	s_lshl_b64 s[44:45], s[24:25], 9
	s_lshl_b64 s[46:47], s[30:31], 9
	s_lshl_b64 s[48:49], s[36:37], 9
	s_lshl_b64 s[50:51], s[58:59], 9
	s_lshl_b64 s[56:57], s[4:5], 9
	v_and_b32_e32 v130, 63, v131
	s_add_u32 s2, s0, s2
	v_lshlrev_b32_e32 v186, 3, v130
	s_addc_u32 s3, s1, s3
	v_lshl_add_u64 v[10:11], s[2:3], 0, v[186:187]
	v_readlane_b32 s26, v245, 19
	v_readlane_b32 s27, v245, 20
	v_lshlrev_b32_e32 v138, 4, v130
	v_readlane_b32 s22, v245, 15
	v_readlane_b32 s23, v245, 16
	v_readlane_b32 s28, v245, 21
	v_readlane_b32 s29, v245, 22
	s_mov_b32 s87, 0x1000000
	v_add_co_u32_e32 v12, vcc, s87, v10
	v_bfe_u32 v132, v131, 2, 4
	s_nop 0
	v_addc_co_u32_e32 v13, vcc, 0, v11, vcc
	v_ashrrev_i32_e32 v136, 6, v131
	v_bfe_u32 v139, v131, 5, 1
	v_ashrrev_i32_e32 v137, 7, v131
	v_and_b32_e32 v134, 31, v131
	v_lshl_add_u32 v216, v131, 2, 0
	v_lshl_add_u64 v[188:189], s[0:1], 0, v[186:187]
	v_lshlrev_b32_e32 v186, 4, v134
	v_cmp_eq_u32_e32 vcc, 0, v134
	v_lshl_add_u32 v140, v136, 10, 0
	v_mov_b32_e32 v133, v187
	s_mov_b32 s89, 0xff800000
	v_add_u32_e32 v217, v140, v138
	s_waitcnt vmcnt(0)
	v_readfirstlane_b32 s2, v18
	s_ashr_i32 s3, s2, 31
	s_lshl_b64 s[2:3], s[2:3], 18
	s_add_u32 s26, s80, s2
	s_addc_u32 s27, s81, s3
	s_lshl_b64 s[4:5], s[4:5], 11
	s_add_u32 s8, s26, s4
	s_addc_u32 s9, s27, s5
	global_load_dwordx4 v[6:9], v138, s[8:9] offset:1024 nt
	global_load_dwordx4 v[2:5], v138, s[8:9] nt
	s_add_u32 s8, s78, s2
	s_addc_u32 s9, s79, s3
	s_add_u32 s16, s8, s4
	s_addc_u32 s17, s9, s5
	s_lshl_b64 s[4:5], s[12:13], 11
	s_add_u32 s2, s8, s4
	s_addc_u32 s3, s9, s5
	s_lshl_b64 s[18:19], s[10:11], 11
	global_load_dwordx4 v[42:45], v138, s[16:17] offset:1024 nt
	global_load_dwordx4 v[46:49], v138, s[16:17] nt
	s_add_u32 s16, s8, s18
	s_addc_u32 s17, s9, s19
	s_lshl_b64 s[22:23], s[20:21], 11
	s_add_u32 s20, s8, s22
	s_addc_u32 s21, s9, s23
	s_lshl_b64 s[28:29], s[24:25], 11
	s_add_u32 s24, s8, s28
	s_addc_u32 s25, s9, s29
	s_lshl_b64 s[30:31], s[30:31], 11
	s_add_u32 s10, s8, s30
	s_addc_u32 s11, s9, s31
	s_lshl_b64 s[36:37], s[36:37], 11
	global_load_dwordx4 v[86:89], v138, s[10:11] nt
	global_load_dwordx4 v[82:85], v138, s[10:11] offset:1024 nt
	s_add_u32 s10, s8, s36
	s_addc_u32 s11, s9, s37
	s_lshl_b64 s[58:59], s[58:59], 11
	global_load_dwordx4 v[78:81], v138, s[10:11] nt
	global_load_dwordx4 v[74:77], v138, s[10:11] offset:1024 nt
	s_add_u32 s10, s8, s58
	s_addc_u32 s11, s9, s59
	global_load_dwordx4 v[70:73], v138, s[10:11] nt
	global_load_dwordx4 v[66:69], v138, s[10:11] offset:1024 nt
	s_mov_b64 s[10:11], 0x1000000
	s_add_u32 s58, s26, s58
	v_lshl_add_u64 v[10:11], v[10:11], 0, s[10:11]
	s_addc_u32 s59, s27, s59
	global_load_dwordx2 v[20:21], v[10:11], off offset:512
	global_load_dwordx2 v[22:23], v[12:13], off
	global_load_dwordx4 v[14:17], v138, s[58:59] offset:1024 nt
	s_nop 0
	global_load_dwordx4 v[10:13], v138, s[58:59] nt
	s_add_u32 s36, s26, s36
	s_addc_u32 s37, s27, s37
	s_add_u32 s30, s26, s30
	s_addc_u32 s31, s27, s31
	s_add_u32 s28, s26, s28
	s_addc_u32 s29, s27, s29
	s_add_u32 s22, s26, s22
	s_addc_u32 s23, s27, s23
	s_add_u32 s18, s26, s18
	s_addc_u32 s19, s27, s19
	s_add_u32 s4, s26, s4
	s_addc_u32 s5, s27, s5
	v_readfirstlane_b32 s68, v19
	s_add_i32 s88, s33, -2
	s_waitcnt vmcnt(3)
	v_lshlrev_b32_e32 v219, 16, v20
	v_and_b32_e32 v220, 0xffff0000, v20
	v_lshlrev_b32_e32 v198, 16, v21
	v_and_b32_e32 v199, 0xffff0000, v21
	s_waitcnt vmcnt(2)
	v_lshlrev_b32_e32 v221, 16, v22
	v_and_b32_e32 v222, 0xffff0000, v22
	v_lshlrev_b32_e32 v200, 16, v23
	v_and_b32_e32 v201, 0xffff0000, v23
	global_load_dwordx4 v[22:25], v138, s[36:37] offset:1024 nt
	global_load_dwordx4 v[18:21], v138, s[36:37] nt
	global_load_dwordx4 v[90:93], v138, s[30:31] offset:1024 nt
	global_load_dwordx4 v[94:97], v138, s[30:31] nt
	global_load_dwordx4 v[50:53], v138, s[28:29] offset:1024 nt
	global_load_dwordx4 v[26:29], v138, s[28:29] nt
	global_load_dwordx4 v[102:105], v138, s[24:25] nt
	global_load_dwordx4 v[98:101], v138, s[24:25] offset:1024 nt
	global_load_dwordx4 v[54:57], v138, s[22:23] offset:1024 nt
	global_load_dwordx4 v[38:41], v138, s[22:23] nt
	global_load_dwordx4 v[110:113], v138, s[20:21] nt
	global_load_dwordx4 v[106:109], v138, s[20:21] offset:1024 nt
	global_load_dwordx4 v[58:61], v138, s[18:19] offset:1024 nt
	global_load_dwordx4 v[34:37], v138, s[18:19] nt
	global_load_dwordx4 v[118:121], v138, s[16:17] nt
	global_load_dwordx4 v[114:117], v138, s[16:17] offset:1024 nt
	global_load_dwordx4 v[62:65], v138, s[4:5] offset:1024 nt
	global_load_dwordx4 v[30:33], v138, s[4:5] nt
	global_load_dwordx4 v[126:129], v138, s[2:3] nt
	global_load_dwordx4 v[122:125], v138, s[2:3] offset:1024 nt
	s_lshl_b32 s2, s69, 12
	s_add_i32 s2, s2, 0
	s_mulk_i32 s69, 0xf020
	v_add_u32_e32 v1, s2, v138
	s_add_i32 s2, s2, s69
	s_or_b32 s16, s12, 8
	v_add_u32_e32 v214, s2, v132
	v_lshlrev_b32_e32 v132, 1, v136
	v_and_or_b32 v132, v132, 2, v139
	s_ashr_i32 s17, s16, 31
	v_lshl_add_u32 v132, v132, 1, v137
	s_lshl_b64 s[18:19], s[16:17], 9
	s_or_b32 s16, s12, 9
	s_movk_i32 s4, 0x100
	v_lshl_add_u32 v215, v132, 2, 0
	v_and_b32_e32 v132, -8, v131
	s_movk_i32 s69, 0x88
	s_ashr_i32 s17, s16, 31
	v_cmp_gt_i32_e64 s[2:3], s4, v131
	v_cmp_eq_u32_e64 s[4:5], s4, v132
	v_mul_lo_u32 v132, v131, s69
	s_lshl_b64 s[22:23], s[16:17], 9
	s_or_b32 s16, s12, 10
	v_mov_b32_e32 v131, 0x1100
	s_ashr_i32 s17, s16, 31
	v_mad_i64_i32 v[134:135], s[0:1], s6, v131, v[186:187]
	v_lshlrev_b32_e32 v131, 2, v136
	s_lshl_b64 s[24:25], s[16:17], 9
	s_or_b32 s16, s12, 11
	v_and_b32_e32 v131, 4, v131
	v_lshlrev_b32_e32 v136, 1, v139
	s_ashr_i32 s17, s16, 31
	v_add3_u32 v131, v137, v131, v136
	s_lshl_b64 s[28:29], s[16:17], 9
	s_or_b32 s16, s12, 13
	v_mul_lo_u32 v136, v131, s69
	s_ashr_i32 s17, s16, 31
	v_ashrrev_i32_e32 v137, 31, v136
	s_or_b32 s20, s12, 12
	s_lshl_b64 s[36:37], s[16:17], 9
	s_or_b32 s16, s12, 14
	s_or_b32 s12, s12, 15
	v_lshl_add_u64 v[134:135], v[136:137], 2, v[134:135]
	s_ashr_i32 s21, s20, 31
	s_ashr_i32 s17, s16, 31
	s_ashr_i32 s13, s12, 31
	v_lshl_add_u64 v[134:135], s[96:97], 0, v[134:135]
	s_mov_b64 s[0:1], 0x23200020
	s_lshl_b64 s[30:31], s[20:21], 9
	s_lshl_b64 s[58:59], s[16:17], 9
	s_lshl_b64 s[84:85], s[12:13], 9
	v_lshl_add_u64 v[190:191], v[134:135], 0, s[0:1]
	s_mul_i32 s0, s6, 0x1100
	s_mul_hi_i32 s12, s6, 0x1100
	s_add_u32 s0, s96, s0
	v_add_u32_e32 v132, 0xffff7800, v132
	s_addc_u32 s1, s97, s12
	v_lshl_add_u64 v[132:133], v[132:133], 2, s[0:1]
	s_mov_b64 s[0:1], 0x23200000
	v_lshl_add_u64 v[192:193], v[132:133], 0, s[0:1]
	s_mov_b64 s[16:17], 0
	s_lshl_b64 s[12:13], s[18:19], 2
	v_lshlrev_b32_e32 v186, 4, v130
	s_lshl_b64 s[18:19], s[22:23], 2
	s_lshl_b64 s[20:21], s[24:25], 2
	s_lshl_b64 s[22:23], s[28:29], 2
	s_lshl_b64 s[24:25], s[30:31], 2
	s_lshl_b64 s[28:29], s[36:37], 2
	s_lshl_b64 s[30:31], s[58:59], 2
	s_lshl_b64 s[36:37], s[84:85], 2
	s_lshl_b64 s[38:39], s[38:39], 2
	s_lshl_b64 s[40:41], s[40:41], 2
	s_lshl_b64 s[42:43], s[42:43], 2
	s_lshl_b64 s[44:45], s[44:45], 2
	s_lshl_b64 s[46:47], s[46:47], 2
	s_lshl_b64 s[48:49], s[48:49], 2
	s_lshl_b64 s[50:51], s[50:51], 2
	s_lshl_b64 s[14:15], s[56:57], 2
	s_mov_b64 s[96:97], 0x1100
	s_waitcnt vmcnt(0)
	s_branch .LBB0_236

.LBB0_236:
	s_mov_b64 s[0:1], s[16:17]
	s_add_i32 s84, s6, s0
	s_add_u32 s16, s0, 1
	s_addc_u32 s17, s1, 0
	s_add_i32 s85, s84, 1
	s_cmp_lt_u32 s0, s88
	s_cselect_b32 s94, 2, 0
	s_ashr_i32 s69, s68, 31
	s_add_u32 s0, s6, s0
	s_addc_u32 s1, s7, s1
	s_add_u32 s0, s0, s94
	s_addc_u32 s1, s1, 0
	v_readlane_b32 s52, v245, 9
	s_lshl_b64 s[0:1], s[0:1], 2
	v_readlane_b32 s54, v245, 11
	v_readlane_b32 s55, v245, 12
	s_add_u32 s0, s54, s0
	s_addc_u32 s1, s55, s1
	s_cmp_lt_u32 s16, s33
	global_load_dword v218, v187, s[0:1]
	s_cselect_b32 s0, s85, s84
	s_ashr_i32 s0, s0, 4
	s_ashr_i32 s1, s0, 31
	s_lshl_b64 s[0:1], s[0:1], 10
	v_lshl_add_u64 v[130:131], v[188:189], 0, s[0:1]
	v_lshl_add_u64 v[132:133], v[130:131], 0, s[10:11]
	v_add_co_u32_e64 v130, s[0:1], s87, v130
	v_readlane_b32 s53, v245, 10
	s_nop 0
	v_addc_co_u32_e64 v131, s[0:1], 0, v131, s[0:1]
	global_load_dwordx2 v[196:197], v[130:131], off
	global_load_dwordx2 v[194:195], v[132:133], off offset:512
	s_mov_b64 s[0:1], s[26:27]
	v_readlane_b32 s56, v245, 13
	v_readlane_b32 s57, v245, 14
	v_readlane_b32 s58, v245, 15
	v_readlane_b32 s59, v245, 16
	v_readlane_b32 s60, v245, 17
	v_readlane_b32 s61, v245, 18
	v_readlane_b32 s62, v245, 19
	v_readlane_b32 s63, v245, 20
	v_readlane_b32 s64, v245, 21
	v_readlane_b32 s65, v245, 22
	v_readlane_b32 s66, v245, 23
	v_readlane_b32 s67, v245, 24
	s_mov_b64 s[84:85], s[8:9]
	s_waitcnt vmcnt(34)
	v_mul_f32_e32 v130, v222, v127
	v_fmac_f32_e32 v130, v221, v126
	v_pk_mul_f32 v[126:127], v[200:201], v[128:129]
	s_lshl_b64 s[60:61], s[68:69], 18
	v_add_f32_e32 v126, v126, v130
	v_add_f32_e32 v126, v127, v126
	s_waitcnt vmcnt(33)
	v_mul_f32_e32 v127, v123, v220
	v_fmac_f32_e32 v127, v122, v219
	v_pk_mul_f32 v[122:123], v[124:125], v[198:199]
	s_add_u32 s8, s78, s60
	v_add_f32_e32 v122, v122, v127
	v_add_f32_e32 v122, v123, v122
	v_add_f32_dpp v123, v126, v126 quad_perm:[1,0,3,2] row_mask:0xf bank_mask:0xf bound_ctrl:1
	s_waitcnt vmcnt(30)
	v_mul_f32_e32 v126, v222, v119
	v_fmac_f32_e32 v126, v221, v118
	v_pk_mul_f32 v[118:119], v[200:201], v[120:121]
	v_add_f32_dpp v123, v123, v123 quad_perm:[2,3,0,1] row_mask:0xf bank_mask:0xf bound_ctrl:1
	v_add_f32_e32 v118, v118, v126
	v_add_f32_e32 v118, v119, v118
	s_waitcnt vmcnt(29)
	v_mul_f32_e32 v119, v115, v220
	v_fmac_f32_e32 v119, v114, v219
	v_pk_mul_f32 v[114:115], v[116:117], v[198:199]
	v_add_f32_dpp v122, v122, v122 quad_perm:[1,0,3,2] row_mask:0xf bank_mask:0xf bound_ctrl:1
	v_add_f32_e32 v114, v114, v119
	v_add_f32_e32 v114, v115, v114
	v_add_f32_dpp v115, v118, v118 quad_perm:[1,0,3,2] row_mask:0xf bank_mask:0xf bound_ctrl:1
	s_waitcnt vmcnt(26)
	v_mul_f32_e32 v118, v222, v111
	v_fmac_f32_e32 v118, v221, v110
	v_pk_mul_f32 v[110:111], v[200:201], v[112:113]
	v_add_f32_dpp v115, v115, v115 quad_perm:[2,3,0,1] row_mask:0xf bank_mask:0xf bound_ctrl:1
	v_add_f32_e32 v110, v110, v118
	v_add_f32_e32 v110, v111, v110
	s_waitcnt vmcnt(25)
	v_mul_f32_e32 v111, v107, v220
	v_fmac_f32_e32 v111, v106, v219
	v_pk_mul_f32 v[106:107], v[108:109], v[198:199]
	v_add_f32_dpp v114, v114, v114 quad_perm:[1,0,3,2] row_mask:0xf bank_mask:0xf bound_ctrl:1
	v_add_f32_e32 v106, v106, v111
	v_add_f32_e32 v106, v107, v106
	v_add_f32_dpp v107, v110, v110 quad_perm:[1,0,3,2] row_mask:0xf bank_mask:0xf bound_ctrl:1
	s_waitcnt vmcnt(22)
	v_mul_f32_e32 v110, v222, v103
	v_fmac_f32_e32 v110, v221, v102
	v_pk_mul_f32 v[102:103], v[200:201], v[104:105]
	v_add_f32_dpp v123, v123, v123 row_ror:4 row_mask:0xf bank_mask:0xf bound_ctrl:1
	v_add_f32_e32 v102, v102, v110
	v_add_f32_e32 v102, v103, v102
	s_waitcnt vmcnt(21)
	v_mul_f32_e32 v103, v99, v220
	v_fmac_f32_e32 v103, v98, v219
	v_pk_mul_f32 v[98:99], v[100:101], v[198:199]
	v_add_f32_dpp v122, v122, v122 quad_perm:[2,3,0,1] row_mask:0xf bank_mask:0xf bound_ctrl:1
	v_add_f32_e32 v98, v98, v103
	v_add_f32_e32 v98, v99, v98
	v_add_f32_dpp v99, v102, v102 quad_perm:[1,0,3,2] row_mask:0xf bank_mask:0xf bound_ctrl:1
	v_add_f32_dpp v115, v115, v115 row_ror:4 row_mask:0xf bank_mask:0xf bound_ctrl:1
	v_add_f32_dpp v114, v114, v114 quad_perm:[2,3,0,1] row_mask:0xf bank_mask:0xf bound_ctrl:1
	v_add_f32_dpp v107, v107, v107 quad_perm:[2,3,0,1] row_mask:0xf bank_mask:0xf bound_ctrl:1
	v_add_f32_dpp v106, v106, v106 quad_perm:[1,0,3,2] row_mask:0xf bank_mask:0xf bound_ctrl:1
	v_add_f32_dpp v99, v99, v99 quad_perm:[2,3,0,1] row_mask:0xf bank_mask:0xf bound_ctrl:1
	v_add_f32_dpp v98, v98, v98 quad_perm:[1,0,3,2] row_mask:0xf bank_mask:0xf bound_ctrl:1
	v_add_f32_dpp v123, v123, v123 row_ror:8 row_mask:0xf bank_mask:0xf bound_ctrl:1
	v_add_f32_dpp v122, v122, v122 row_ror:4 row_mask:0xf bank_mask:0xf bound_ctrl:1
	v_add_f32_dpp v115, v115, v115 row_ror:8 row_mask:0xf bank_mask:0xf bound_ctrl:1
	v_add_f32_dpp v114, v114, v114 row_ror:4 row_mask:0xf bank_mask:0xf bound_ctrl:1
	v_add_f32_dpp v107, v107, v107 row_ror:4 row_mask:0xf bank_mask:0xf bound_ctrl:1
	v_add_f32_dpp v106, v106, v106 quad_perm:[2,3,0,1] row_mask:0xf bank_mask:0xf bound_ctrl:1
	v_add_f32_dpp v99, v99, v99 row_ror:4 row_mask:0xf bank_mask:0xf bound_ctrl:1
	v_add_f32_dpp v98, v98, v98 quad_perm:[2,3,0,1] row_mask:0xf bank_mask:0xf bound_ctrl:1
	v_add_f32_dpp v122, v122, v122 row_ror:8 row_mask:0xf bank_mask:0xf bound_ctrl:1
	v_mov_b32_e32 v124, v123
	v_add_f32_dpp v114, v114, v114 row_ror:8 row_mask:0xf bank_mask:0xf bound_ctrl:1
	v_mov_b32_e32 v116, v115
	v_add_f32_dpp v107, v107, v107 row_ror:8 row_mask:0xf bank_mask:0xf bound_ctrl:1
	v_add_f32_dpp v106, v106, v106 row_ror:4 row_mask:0xf bank_mask:0xf bound_ctrl:1
	v_add_f32_dpp v104, v99, v99 row_ror:8 row_mask:0xf bank_mask:0xf bound_ctrl:1
	v_add_f32_dpp v98, v98, v98 row_ror:4 row_mask:0xf bank_mask:0xf bound_ctrl:1
	v_permlane16_swap_b32_e32 v123, v124
	v_mov_b32_e32 v125, v122
	v_permlane16_swap_b32_e32 v115, v116
	v_mov_b32_e32 v117, v114
	v_add_f32_dpp v106, v106, v106 row_ror:8 row_mask:0xf bank_mask:0xf bound_ctrl:1
	v_mov_b32_e32 v108, v107
	v_add_f32_dpp v105, v98, v98 row_ror:8 row_mask:0xf bank_mask:0xf bound_ctrl:1
	v_mov_b32_e32 v110, v104
	v_permlane16_swap_b32_e32 v122, v125
	v_permlane16_swap_b32_e32 v114, v117
	v_permlane16_swap_b32_e32 v107, v108
	v_mov_b32_e32 v109, v106
	v_permlane16_swap_b32_e32 v104, v110
	v_mov_b32_e32 v111, v105
	v_max3_f32 v98, v123, s89, v115
	v_permlane16_swap_b32_e32 v106, v109
	v_permlane16_swap_b32_e32 v105, v111
	v_max3_f32 v99, v124, s89, v116
	v_max3_f32 v100, v122, s89, v114
	v_max3_f32 v155, v98, v107, v104
	v_max3_f32 v157, v99, v108, v110
	v_max3_f32 v159, v100, v106, v105
	v_sub_f32_e32 v98, 0xff800000, v155
	v_sub_f32_e32 v100, v123, v155
	v_max3_f32 v101, v125, s89, v117
	v_exp_f32_e32 v99, v98
	v_sub_f32_e32 v98, 0xff800000, v157
	v_exp_f32_e32 v164, v100
	v_sub_f32_e32 v100, v124, v157
	v_max3_f32 v165, v101, v109, v111
	v_exp_f32_e32 v101, v98
	v_sub_f32_e32 v98, 0xff800000, v159
	v_exp_f32_e32 v156, v100
	v_sub_f32_e32 v100, v122, v159
	v_exp_f32_e32 v102, v98
	v_sub_f32_e32 v98, 0xff800000, v165
	v_exp_f32_e32 v166, v100
	v_sub_f32_e32 v100, v125, v165
	v_exp_f32_e32 v103, v98
	v_exp_f32_e32 v100, v100
	v_mul_f32_e32 v154, 0, v101
	v_fma_f32 v101, 0, v101, v156
	v_mul_f32_e32 v98, 0, v103
	v_mov_b32_e32 v118, v100
	v_mul_f32_e32 v160, 0, v99
	v_mul_f32_e32 v162, 0, v102
	v_fma_f32 v112, 0, v99, v164
	v_fma_f32 v113, 0, v102, v166
	v_fmac_f32_e32 v118, 0, v103
	v_pk_fma_f32 v[102:103], v[62:63], v[100:101], v[98:99] op_sel_hi:[1,0,0]
	v_pk_fma_f32 v[98:99], v[64:65], v[100:101], v[98:99] op_sel_hi:[1,0,0]
	v_sub_f32_e32 v100, v115, v155
	v_exp_f32_e32 v168, v100
	v_sub_f32_e32 v100, v116, v157
	v_exp_f32_e32 v158, v100
	v_sub_f32_e32 v100, v114, v159
	v_exp_f32_e32 v170, v100
	v_sub_f32_e32 v100, v117, v165
	v_exp_f32_e32 v100, v100
	v_add_f32_e32 v114, v158, v101
	v_add_f32_e32 v112, v168, v112
	v_add_f32_e32 v113, v170, v113
	v_add_f32_e32 v115, v100, v118
	v_pk_fma_f32 v[98:99], v[60:61], v[100:101], v[98:99] op_sel_hi:[1,0,1]
	v_pk_fma_f32 v[100:101], v[58:59], v[100:101], v[102:103] op_sel_hi:[1,0,1]
	v_sub_f32_e32 v102, v107, v155
	v_exp_f32_e32 v172, v102
	v_sub_f32_e32 v102, v108, v157
	v_exp_f32_e32 v174, v102
	v_sub_f32_e32 v102, v106, v159
	v_exp_f32_e32 v176, v102
	v_sub_f32_e32 v102, v109, v165
	v_exp_f32_e32 v102, v102
	v_add_f32_e32 v103, v172, v112
	v_add_f32_e32 v106, v174, v114
	v_add_f32_e32 v107, v176, v113
	v_add_f32_e32 v108, v102, v115
	v_pk_fma_f32 v[100:101], v[54:55], v[102:103], v[100:101] op_sel_hi:[1,0,1]
	v_pk_fma_f32 v[98:99], v[56:57], v[102:103], v[98:99] op_sel_hi:[1,0,1]
	v_sub_f32_e32 v102, v104, v155
	v_exp_f32_e32 v206, v102
	v_sub_f32_e32 v102, v110, v157
	v_exp_f32_e32 v208, v102
	v_sub_f32_e32 v102, v105, v159
	v_exp_f32_e32 v210, v102
	v_sub_f32_e32 v102, v111, v165
	v_exp_f32_e32 v102, v102
	s_addc_u32 s9, s79, s61
	v_add_f32_e32 v167, v206, v103
	v_add_f32_e32 v169, v208, v106
	v_add_f32_e32 v171, v210, v107
	v_add_f32_e32 v173, v102, v108
	s_waitcnt vmcnt(19)
	v_pk_fma_f32 v[202:203], v[52:53], v[102:103], v[98:99] op_sel_hi:[1,0,1]
	v_pk_fma_f32 v[204:205], v[50:51], v[102:103], v[100:101] op_sel_hi:[1,0,1]
	s_add_u32 s68, s84, s12
	s_addc_u32 s69, s85, s13
	global_load_dwordx4 v[182:185], v186, s[68:69] nt
	global_load_dwordx4 v[178:181], v186, s[68:69] offset:1024 nt
	s_add_u32 s68, s0, s12
	s_addc_u32 s69, s1, s13
	global_load_dwordx4 v[102:105], v186, s[68:69] nt
	global_load_dwordx4 v[98:101], v186, s[68:69] offset:1024 nt
	s_add_u32 s68, s84, s18
	s_addc_u32 s69, s85, s19
	global_load_dwordx4 v[126:129], v186, s[68:69] nt
	global_load_dwordx4 v[122:125], v186, s[68:69] offset:1024 nt
	s_add_u32 s68, s0, s18
	s_addc_u32 s69, s1, s19
	global_load_dwordx4 v[130:133], v186, s[68:69] nt
	global_load_dwordx4 v[142:145], v186, s[68:69] offset:1024 nt
	s_add_u32 s68, s84, s20
	s_addc_u32 s69, s85, s21
	global_load_dwordx4 v[118:121], v186, s[68:69] nt
	global_load_dwordx4 v[114:117], v186, s[68:69] offset:1024 nt
	s_add_u32 s68, s0, s20
	s_addc_u32 s69, s1, s21
	global_load_dwordx4 v[134:137], v186, s[68:69] nt
	global_load_dwordx4 v[146:149], v186, s[68:69] offset:1024 nt
	s_add_u32 s68, s84, s22
	s_addc_u32 s69, s85, s23
	global_load_dwordx4 v[110:113], v186, s[68:69] nt
	global_load_dwordx4 v[106:109], v186, s[68:69] offset:1024 nt
	s_add_u32 s68, s0, s22
	s_addc_u32 s69, s1, s23
	global_load_dwordx4 v[138:141], v186, s[68:69] nt
	global_load_dwordx4 v[150:153], v186, s[68:69] offset:1024 nt
	v_pk_fma_f32 v[212:213], v[30:31], v[164:165], v[160:161] op_sel_hi:[1,0,0]
	v_pk_fma_f32 v[160:161], v[32:33], v[164:165], v[160:161] op_sel_hi:[1,0,0]
	v_pk_fma_f32 v[62:63], v[62:63], v[166:167], v[162:163] op_sel_hi:[1,0,0]
	v_pk_fma_f32 v[64:65], v[64:65], v[166:167], v[162:163] op_sel_hi:[1,0,0]
	v_pk_fma_f32 v[160:161], v[36:37], v[168:169], v[160:161] op_sel_hi:[1,0,1]
	v_pk_fma_f32 v[162:163], v[34:35], v[168:169], v[212:213] op_sel_hi:[1,0,1]
	v_pk_fma_f32 v[60:61], v[60:61], v[170:171], v[64:65] op_sel_hi:[1,0,1]
	v_pk_fma_f32 v[58:59], v[58:59], v[170:171], v[62:63] op_sel_hi:[1,0,1]
	v_pk_fma_f32 v[62:63], v[38:39], v[172:173], v[162:163] op_sel_hi:[1,0,1]
	v_pk_fma_f32 v[64:65], v[40:41], v[172:173], v[160:161] op_sel_hi:[1,0,1]
	v_pk_fma_f32 v[58:59], v[54:55], v[176:177], v[58:59] op_sel_hi:[1,0,1]
	v_pk_fma_f32 v[60:61], v[56:57], v[176:177], v[60:61] op_sel_hi:[1,0,1]
	v_pk_fma_f32 v[54:55], v[28:29], v[206:207], v[64:65] op_sel_hi:[1,0,1]
	v_pk_fma_f32 v[56:57], v[26:27], v[206:207], v[62:63] op_sel_hi:[1,0,1]
	v_pk_fma_f32 v[52:53], v[52:53], v[210:211], v[60:61] op_sel_hi:[1,0,1]
	v_pk_fma_f32 v[50:51], v[50:51], v[210:211], v[58:59] op_sel_hi:[1,0,1]
	s_waitcnt vmcnt(34)
	v_mul_f32_e32 v60, v222, v87
	v_fmac_f32_e32 v60, v221, v86
	v_pk_mul_f32 v[58:59], v[200:201], v[88:89]
	s_waitcnt vmcnt(33)
	v_mul_f32_e32 v61, v83, v220
	v_add_f32_e32 v58, v58, v60
	v_add_f32_e32 v60, v59, v58
	v_fmac_f32_e32 v61, v82, v219
	v_pk_mul_f32 v[58:59], v[84:85], v[198:199]
	s_waitcnt vmcnt(29)
	v_mul_f32_e32 v65, v75, v220
	v_add_f32_e32 v58, v58, v61
	v_add_f32_e32 v58, v59, v58
	v_add_f32_dpp v59, v60, v60 quad_perm:[1,0,3,2] row_mask:0xf bank_mask:0xf bound_ctrl:1
	v_mul_f32_e32 v60, v222, v79
	v_add_f32_dpp v58, v58, v58 quad_perm:[1,0,3,2] row_mask:0xf bank_mask:0xf bound_ctrl:1
	v_add_f32_dpp v59, v59, v59 quad_perm:[2,3,0,1] row_mask:0xf bank_mask:0xf bound_ctrl:1
	v_fmac_f32_e32 v60, v221, v78
	v_add_f32_dpp v58, v58, v58 quad_perm:[2,3,0,1] row_mask:0xf bank_mask:0xf bound_ctrl:1
	v_add_f32_dpp v59, v59, v59 row_ror:4 row_mask:0xf bank_mask:0xf bound_ctrl:1
	v_fmac_f32_e32 v65, v74, v219
	v_add_f32_dpp v58, v58, v58 row_ror:4 row_mask:0xf bank_mask:0xf bound_ctrl:1
	v_add_f32_dpp v61, v59, v59 row_ror:8 row_mask:0xf bank_mask:0xf bound_ctrl:1
	v_pk_fma_f32 v[30:31], v[30:31], v[156:157], v[154:155] op_sel_hi:[1,0,0]
	v_add_f32_dpp v62, v58, v58 row_ror:8 row_mask:0xf bank_mask:0xf bound_ctrl:1
	v_pk_mul_f32 v[58:59], v[200:201], v[80:81]
	v_mov_b32_e32 v64, v62
	v_add_f32_e32 v58, v58, v60
	v_add_f32_e32 v60, v59, v58
	v_pk_mul_f32 v[58:59], v[76:77], v[198:199]
	v_permlane16_swap_b32_e32 v62, v64
	v_add_f32_e32 v58, v58, v65
	v_add_f32_e32 v58, v59, v58
	v_add_f32_dpp v59, v60, v60 quad_perm:[1,0,3,2] row_mask:0xf bank_mask:0xf bound_ctrl:1
	s_waitcnt vmcnt(26)
	v_mul_f32_e32 v60, v222, v71
	v_add_f32_dpp v58, v58, v58 quad_perm:[1,0,3,2] row_mask:0xf bank_mask:0xf bound_ctrl:1
	v_add_f32_dpp v59, v59, v59 quad_perm:[2,3,0,1] row_mask:0xf bank_mask:0xf bound_ctrl:1
	v_fmac_f32_e32 v60, v221, v70
	v_add_f32_dpp v58, v58, v58 quad_perm:[2,3,0,1] row_mask:0xf bank_mask:0xf bound_ctrl:1
	v_add_f32_dpp v59, v59, v59 row_ror:4 row_mask:0xf bank_mask:0xf bound_ctrl:1
	s_waitcnt vmcnt(25)
	v_mul_f32_e32 v65, v67, v220
	v_add_f32_dpp v58, v58, v58 row_ror:4 row_mask:0xf bank_mask:0xf bound_ctrl:1
	v_add_f32_dpp v74, v59, v59 row_ror:8 row_mask:0xf bank_mask:0xf bound_ctrl:1
	v_fmac_f32_e32 v65, v66, v219
	v_add_f32_dpp v75, v58, v58 row_ror:8 row_mask:0xf bank_mask:0xf bound_ctrl:1
	v_pk_mul_f32 v[58:59], v[200:201], v[72:73]
	v_mov_b32_e32 v77, v75
	v_add_f32_e32 v58, v58, v60
	v_add_f32_e32 v60, v59, v58
	v_pk_mul_f32 v[58:59], v[68:69], v[198:199]
	v_permlane16_swap_b32_e32 v75, v77
	v_add_f32_e32 v58, v58, v65
	v_add_f32_e32 v58, v59, v58
	v_add_f32_dpp v59, v60, v60 quad_perm:[1,0,3,2] row_mask:0xf bank_mask:0xf bound_ctrl:1
	v_pk_fma_f32 v[32:33], v[32:33], v[156:157], v[154:155] op_sel_hi:[1,0,0]
	v_add_f32_dpp v58, v58, v58 quad_perm:[1,0,3,2] row_mask:0xf bank_mask:0xf bound_ctrl:1
	v_add_f32_dpp v59, v59, v59 quad_perm:[2,3,0,1] row_mask:0xf bank_mask:0xf bound_ctrl:1
	v_mov_b32_e32 v63, v61
	v_add_f32_dpp v58, v58, v58 quad_perm:[2,3,0,1] row_mask:0xf bank_mask:0xf bound_ctrl:1
	v_add_f32_dpp v59, v59, v59 row_ror:4 row_mask:0xf bank_mask:0xf bound_ctrl:1
	v_mov_b32_e32 v76, v74
	v_add_f32_dpp v58, v58, v58 row_ror:4 row_mask:0xf bank_mask:0xf bound_ctrl:1
	v_add_f32_dpp v59, v59, v59 row_ror:8 row_mask:0xf bank_mask:0xf bound_ctrl:1
	v_pk_fma_f32 v[32:33], v[36:37], v[158:159], v[32:33] op_sel_hi:[1,0,1]
	v_add_f32_dpp v66, v58, v58 row_ror:8 row_mask:0xf bank_mask:0xf bound_ctrl:1
	s_waitcnt vmcnt(22)
	v_mul_f32_e32 v58, v222, v47
	v_fmac_f32_e32 v58, v221, v46
	v_pk_mul_f32 v[46:47], v[200:201], v[48:49]
	v_mov_b32_e32 v68, v66
	v_add_f32_e32 v46, v46, v58
	v_add_f32_e32 v46, v47, v46
	s_waitcnt vmcnt(21)
	v_mul_f32_e32 v47, v43, v220
	v_fmac_f32_e32 v47, v42, v219
	v_pk_mul_f32 v[42:43], v[44:45], v[198:199]
	v_permlane16_swap_b32_e32 v66, v68
	v_add_f32_e32 v42, v42, v47
	v_add_f32_e32 v42, v43, v42
	v_add_f32_dpp v43, v46, v46 quad_perm:[1,0,3,2] row_mask:0xf bank_mask:0xf bound_ctrl:1
	v_pk_fma_f32 v[30:31], v[34:35], v[158:159], v[30:31] op_sel_hi:[1,0,1]
	v_add_f32_dpp v42, v42, v42 quad_perm:[1,0,3,2] row_mask:0xf bank_mask:0xf bound_ctrl:1
	v_add_f32_dpp v43, v43, v43 quad_perm:[2,3,0,1] row_mask:0xf bank_mask:0xf bound_ctrl:1
	v_max3_f32 v36, v159, v62, v75
	v_add_f32_dpp v42, v42, v42 quad_perm:[2,3,0,1] row_mask:0xf bank_mask:0xf bound_ctrl:1
	v_add_f32_dpp v43, v43, v43 row_ror:4 row_mask:0xf bank_mask:0xf bound_ctrl:1
	v_permlane16_swap_b32_e32 v61, v63
	v_add_f32_dpp v42, v42, v42 row_ror:4 row_mask:0xf bank_mask:0xf bound_ctrl:1
	v_add_f32_dpp v43, v43, v43 row_ror:8 row_mask:0xf bank_mask:0xf bound_ctrl:1
	v_permlane16_swap_b32_e32 v74, v76
	v_add_f32_dpp v42, v42, v42 row_ror:8 row_mask:0xf bank_mask:0xf bound_ctrl:1
	v_mov_b32_e32 v45, v42
	s_nop 1
	v_permlane16_swap_b32_e32 v42, v45
	v_mov_b32_e32 v67, v59
	v_mov_b32_e32 v44, v43
	v_pk_fma_f32 v[30:31], v[38:39], v[174:175], v[30:31] op_sel_hi:[1,0,1]
	v_max3_f32 v37, v165, v64, v77
	v_max3_f32 v223, v36, v66, v42
	v_permlane16_swap_b32_e32 v59, v67
	v_permlane16_swap_b32_e32 v43, v44
	v_max3_f32 v34, v155, v61, v74
	v_max3_f32 v229, v37, v68, v45
	v_pk_fma_f32 v[26:27], v[26:27], v[208:209], v[30:31] op_sel_hi:[1,0,1]
	v_sub_f32_e32 v31, v159, v223
	v_pk_fma_f32 v[32:33], v[40:41], v[174:175], v[32:33] op_sel_hi:[1,0,1]
	v_max3_f32 v35, v157, v63, v76
	v_max3_f32 v39, v34, v59, v43
	v_exp_f32_e32 v60, v31
	v_sub_f32_e32 v31, v165, v229
	v_max3_f32 v41, v35, v67, v44
	v_pk_fma_f32 v[28:29], v[28:29], v[208:209], v[32:33] op_sel_hi:[1,0,1]
	v_exp_f32_e32 v32, v31
	v_sub_f32_e32 v31, v61, v39
	v_exp_f32_e32 v34, v31
	v_sub_f32_e32 v31, v63, v41
	v_exp_f32_e32 v36, v31
	v_sub_f32_e32 v31, v62, v223
	v_sub_f32_e32 v33, v64, v229
	v_exp_f32_e32 v40, v31
	v_exp_f32_e32 v38, v33
	v_sub_f32_e32 v30, v155, v39
	v_exp_f32_e32 v58, v30
	v_mov_b32_e32 v47, v40
	v_pk_mul_f32 v[206:207], v[92:93], v[40:41] op_sel_hi:[1,0]
	v_pk_mul_f32 v[208:209], v[90:91], v[40:41] op_sel_hi:[1,0]
	v_sub_f32_e32 v40, v75, v223
	v_sub_f32_e32 v30, v157, v41
	v_fma_f32 v31, v173, v32, v38
	v_pk_mul_f32 v[224:225], v[92:93], v[38:39] op_sel_hi:[1,0]
	v_pk_mul_f32 v[226:227], v[90:91], v[38:39] op_sel_hi:[1,0]
	v_sub_f32_e32 v38, v74, v39
	v_exp_f32_e32 v212, v40
	v_sub_f32_e32 v40, v77, v229
	v_exp_f32_e32 v30, v30
	v_exp_f32_e32 v210, v38
	v_sub_f32_e32 v38, v76, v41
	v_exp_f32_e32 v228, v40
	v_sub_f32_e32 v40, v59, v39
	v_sub_f32_e32 v48, v66, v223
	v_exp_f32_e32 v38, v38
	v_exp_f32_e32 v230, v40
	v_sub_f32_e32 v40, v67, v41
	v_exp_f32_e32 v232, v48
	v_sub_f32_e32 v48, v68, v229
	v_sub_f32_e32 v43, v43, v39
	v_sub_f32_e32 v42, v42, v223
	v_exp_f32_e32 v40, v40
	v_exp_f32_e32 v234, v48
	v_exp_f32_e32 v236, v43
	v_sub_f32_e32 v43, v44, v41
	v_exp_f32_e32 v240, v42
	v_sub_f32_e32 v42, v45, v229
	v_mov_b32_e32 v33, v34
	v_mov_b32_e32 v46, v36
	v_exp_f32_e32 v238, v43
	v_exp_f32_e32 v242, v42
	v_fmac_f32_e32 v33, v167, v58
	v_fmac_f32_e32 v46, v169, v30
	v_fmac_f32_e32 v47, v171, v60
	v_add_f32_e32 v33, v210, v33
	v_add_f32_e32 v46, v38, v46
	v_add_f32_e32 v47, v212, v47
	v_add_f32_e32 v31, v228, v31
	s_add_u32 s26, s80, s60
	v_add_f32_e32 v33, v230, v33
	v_add_f32_e32 v46, v40, v46
	v_add_f32_e32 v47, v232, v47
	v_add_f32_e32 v31, v234, v31
	s_addc_u32 s27, s81, s61
	v_pk_mul_f32 v[62:63], v[96:97], v[34:35] op_sel_hi:[1,0]
	v_pk_mul_f32 v[64:65], v[94:95], v[34:35] op_sel_hi:[1,0]
	v_pk_mul_f32 v[34:35], v[96:97], v[36:37] op_sel_hi:[1,0]
	v_pk_mul_f32 v[36:37], v[94:95], v[36:37] op_sel_hi:[1,0]
	v_add_f32_e32 v59, v236, v33
	v_add_f32_e32 v61, v238, v46
	v_add_f32_e32 v231, v240, v47
	v_add_f32_e32 v31, v242, v31
	s_add_u32 s68, s84, s24
	s_addc_u32 s69, s85, s25
	global_load_dwordx4 v[94:97], v186, s[68:69] nt
	global_load_dwordx4 v[90:93], v186, s[68:69] offset:1024 nt
	s_add_u32 s68, s0, s24
	s_addc_u32 s69, s1, s25
	global_load_dwordx4 v[46:49], v186, s[68:69] nt
	global_load_dwordx4 v[42:45], v186, s[68:69] offset:1024 nt
	s_add_u32 s68, s84, s28
	s_addc_u32 s69, s85, s29
	global_load_dwordx4 v[86:89], v186, s[68:69] nt
	global_load_dwordx4 v[82:85], v186, s[68:69] offset:1024 nt
	s_add_u32 s68, s0, s28
	s_addc_u32 s69, s1, s29
	global_load_dwordx4 v[174:177], v186, s[68:69] nt
	global_load_dwordx4 v[166:169], v186, s[68:69] offset:1024 nt
	s_add_u32 s68, s84, s30
	s_addc_u32 s69, s85, s31
	global_load_dwordx4 v[78:81], v186, s[68:69] nt
	global_load_dwordx4 v[74:77], v186, s[68:69] offset:1024 nt
	s_add_u32 s68, s0, s30
	s_addc_u32 s69, s1, s31
	global_load_dwordx4 v[170:173], v186, s[68:69] nt
	global_load_dwordx4 v[158:161], v186, s[68:69] offset:1024 nt
	s_add_u32 s68, s84, s36
	s_addc_u32 s69, s85, s37
	s_add_u32 s0, s0, s36
	s_addc_u32 s1, s1, s37
	global_load_dwordx4 v[70:73], v186, s[68:69] nt
	global_load_dwordx4 v[66:69], v186, s[68:69] offset:1024 nt
	global_load_dwordx4 v[162:165], v186, s[0:1] nt
	global_load_dwordx4 v[154:157], v186, s[0:1] offset:1024 nt
	v_pk_fma_f32 v[56:57], v[56:57], v[58:59], v[64:65] op_sel_hi:[1,0,1]
	v_pk_fma_f32 v[54:55], v[54:55], v[58:59], v[62:63] op_sel_hi:[1,0,1]
	v_pk_fma_f32 v[50:51], v[50:51], v[60:61], v[208:209] op_sel_hi:[1,0,1]
	v_pk_fma_f32 v[52:53], v[52:53], v[60:61], v[206:207] op_sel_hi:[1,0,1]
	v_pk_fma_f32 v[54:55], v[20:21], v[210:211], v[54:55] op_sel_hi:[1,0,1]
	v_pk_fma_f32 v[56:57], v[18:19], v[210:211], v[56:57] op_sel_hi:[1,0,1]
	v_pk_fma_f32 v[52:53], v[24:25], v[212:213], v[52:53] op_sel_hi:[1,0,1]
	v_pk_fma_f32 v[50:51], v[22:23], v[212:213], v[50:51] op_sel_hi:[1,0,1]
	v_pk_fma_f32 v[56:57], v[10:11], v[230:231], v[56:57] op_sel_hi:[1,0,1]
	v_pk_fma_f32 v[54:55], v[12:13], v[230:231], v[54:55] op_sel_hi:[1,0,1]
	v_pk_fma_f32 v[50:51], v[14:15], v[232:233], v[50:51] op_sel_hi:[1,0,1]
	v_pk_fma_f32 v[52:53], v[16:17], v[232:233], v[52:53] op_sel_hi:[1,0,1]
	s_waitcnt vmcnt(36)
	v_pk_fma_f32 v[206:207], v[4:5], v[236:237], v[54:55] op_sel_hi:[1,0,1]
	v_pk_fma_f32 v[208:209], v[2:3], v[236:237], v[56:57] op_sel_hi:[1,0,1]
	s_waitcnt vmcnt(35)
	v_pk_fma_f32 v[210:211], v[8:9], v[240:241], v[52:53] op_sel_hi:[1,0,1]
	v_pk_fma_f32 v[212:213], v[6:7], v[240:241], v[50:51] op_sel_hi:[1,0,1]
	s_waitcnt vmcnt(31)
	v_mul_f32_e32 v33, v222, v183
	v_fmac_f32_e32 v33, v221, v182
	v_pk_mul_f32 v[50:51], v[184:185], v[200:201]
	s_waitcnt vmcnt(30)
	v_mul_f32_e32 v52, v220, v179
	v_add_f32_e32 v33, v50, v33
	v_add_f32_e32 v33, v51, v33
	v_fmac_f32_e32 v52, v219, v178
	v_pk_mul_f32 v[50:51], v[180:181], v[198:199]
	v_add_f32_dpp v33, v33, v33 quad_perm:[1,0,3,2] row_mask:0xf bank_mask:0xf bound_ctrl:1
	v_add_f32_e32 v50, v50, v52
	v_add_f32_e32 v50, v51, v50
	v_add_f32_dpp v33, v33, v33 quad_perm:[2,3,0,1] row_mask:0xf bank_mask:0xf bound_ctrl:1
	s_waitcnt vmcnt(26)
	v_mul_f32_e32 v56, v220, v123
	v_fmac_f32_e32 v56, v219, v122
	v_add_f32_dpp v33, v33, v33 row_ror:4 row_mask:0xf bank_mask:0xf bound_ctrl:1
	s_waitcnt vmcnt(22)
	v_mul_f32_e32 v62, v220, v115
	v_fmac_f32_e32 v62, v219, v114
	v_add_f32_dpp v52, v33, v33 row_ror:8 row_mask:0xf bank_mask:0xf bound_ctrl:1
	v_add_f32_dpp v33, v50, v50 quad_perm:[1,0,3,2] row_mask:0xf bank_mask:0xf bound_ctrl:1
	v_pk_mul_f32 v[50:51], v[128:129], v[200:201]
	s_waitcnt vmcnt(18)
	v_mul_f32_e32 v107, v220, v107
	v_add_f32_dpp v33, v33, v33 quad_perm:[2,3,0,1] row_mask:0xf bank_mask:0xf bound_ctrl:1
	v_fmac_f32_e32 v107, v219, v106
	v_mov_b32_e32 v54, v52
	v_add_f32_dpp v33, v33, v33 row_ror:4 row_mask:0xf bank_mask:0xf bound_ctrl:1
	s_nop 0
	v_permlane16_swap_b32_e32 v52, v54
	v_add_f32_dpp v53, v33, v33 row_ror:8 row_mask:0xf bank_mask:0xf bound_ctrl:1
	v_mul_f32_e32 v33, v222, v127
	v_fmac_f32_e32 v33, v221, v126
	v_add_f32_e32 v33, v50, v33
	v_add_f32_e32 v33, v51, v33
	v_pk_mul_f32 v[50:51], v[124:125], v[198:199]
	v_mov_b32_e32 v55, v53
	v_add_f32_dpp v33, v33, v33 quad_perm:[1,0,3,2] row_mask:0xf bank_mask:0xf bound_ctrl:1
	v_add_f32_e32 v50, v50, v56
	v_add_f32_e32 v50, v51, v50
	v_add_f32_dpp v33, v33, v33 quad_perm:[2,3,0,1] row_mask:0xf bank_mask:0xf bound_ctrl:1
	v_permlane16_swap_b32_e32 v53, v55
	s_nop 0
	v_add_f32_dpp v33, v33, v33 row_ror:4 row_mask:0xf bank_mask:0xf bound_ctrl:1
	s_nop 1
	v_add_f32_dpp v56, v33, v33 row_ror:8 row_mask:0xf bank_mask:0xf bound_ctrl:1
	v_add_f32_dpp v33, v50, v50 quad_perm:[1,0,3,2] row_mask:0xf bank_mask:0xf bound_ctrl:1
	v_pk_mul_f32 v[50:51], v[120:121], v[200:201]
	v_mov_b32_e32 v58, v56
	v_add_f32_dpp v33, v33, v33 quad_perm:[2,3,0,1] row_mask:0xf bank_mask:0xf bound_ctrl:1
	s_nop 0
	v_permlane16_swap_b32_e32 v56, v58
	v_add_f32_dpp v33, v33, v33 row_ror:4 row_mask:0xf bank_mask:0xf bound_ctrl:1
	s_nop 1
	v_add_f32_dpp v57, v33, v33 row_ror:8 row_mask:0xf bank_mask:0xf bound_ctrl:1
	v_mul_f32_e32 v33, v222, v119
	v_fmac_f32_e32 v33, v221, v118
	v_add_f32_e32 v33, v50, v33
	v_add_f32_e32 v33, v51, v33
	v_pk_mul_f32 v[50:51], v[116:117], v[198:199]
	v_mov_b32_e32 v60, v57
	v_add_f32_dpp v33, v33, v33 quad_perm:[1,0,3,2] row_mask:0xf bank_mask:0xf bound_ctrl:1
	v_add_f32_e32 v50, v50, v62
	v_add_f32_e32 v50, v51, v50
	v_add_f32_dpp v33, v33, v33 quad_perm:[2,3,0,1] row_mask:0xf bank_mask:0xf bound_ctrl:1
	v_permlane16_swap_b32_e32 v57, v60
	s_nop 0
	v_add_f32_dpp v33, v33, v33 row_ror:4 row_mask:0xf bank_mask:0xf bound_ctrl:1
	s_nop 1
	v_add_f32_dpp v62, v33, v33 row_ror:8 row_mask:0xf bank_mask:0xf bound_ctrl:1
	v_add_f32_dpp v33, v50, v50 quad_perm:[1,0,3,2] row_mask:0xf bank_mask:0xf bound_ctrl:1
	v_pk_mul_f32 v[50:51], v[112:113], v[200:201]
	v_mov_b32_e32 v64, v62
	v_add_f32_dpp v33, v33, v33 quad_perm:[2,3,0,1] row_mask:0xf bank_mask:0xf bound_ctrl:1
	s_nop 0
	v_permlane16_swap_b32_e32 v62, v64
	v_add_f32_dpp v33, v33, v33 row_ror:4 row_mask:0xf bank_mask:0xf bound_ctrl:1
	s_nop 1
	v_add_f32_dpp v63, v33, v33 row_ror:8 row_mask:0xf bank_mask:0xf bound_ctrl:1
	v_mul_f32_e32 v33, v222, v111
	v_fmac_f32_e32 v33, v221, v110
	v_add_f32_e32 v33, v50, v33
	v_add_f32_e32 v33, v51, v33
	v_pk_mul_f32 v[50:51], v[108:109], v[198:199]
	v_mov_b32_e32 v65, v63
	v_add_f32_dpp v33, v33, v33 quad_perm:[1,0,3,2] row_mask:0xf bank_mask:0xf bound_ctrl:1
	v_add_f32_e32 v50, v50, v107
	v_add_f32_e32 v50, v51, v50
	v_add_f32_dpp v33, v33, v33 quad_perm:[2,3,0,1] row_mask:0xf bank_mask:0xf bound_ctrl:1
	v_permlane16_swap_b32_e32 v63, v65
	s_nop 0
	v_add_f32_dpp v33, v33, v33 row_ror:4 row_mask:0xf bank_mask:0xf bound_ctrl:1
	s_nop 1
	v_add_f32_dpp v106, v33, v33 row_ror:8 row_mask:0xf bank_mask:0xf bound_ctrl:1
	v_add_f32_dpp v33, v50, v50 quad_perm:[1,0,3,2] row_mask:0xf bank_mask:0xf bound_ctrl:1
	v_mov_b32_e32 v108, v106
	s_nop 1
	v_permlane16_swap_b32_e32 v106, v108
	v_add_f32_dpp v33, v33, v33 quad_perm:[2,3,0,1] row_mask:0xf bank_mask:0xf bound_ctrl:1
	s_nop 1
	v_add_f32_dpp v33, v33, v33 row_ror:4 row_mask:0xf bank_mask:0xf bound_ctrl:1
	v_pk_fma_f32 v[50:51], v[204:205], v[32:33], v[226:227] op_sel_hi:[1,0,1]
	s_nop 0
	v_pk_fma_f32 v[22:23], v[22:23], v[228:229], v[50:51] op_sel_hi:[1,0,1]
	v_add_f32_dpp v107, v33, v33 row_ror:8 row_mask:0xf bank_mask:0xf bound_ctrl:1
	v_pk_fma_f32 v[32:33], v[202:203], v[32:33], v[224:225] op_sel_hi:[1,0,1]
	v_pk_fma_f32 v[14:15], v[14:15], v[234:235], v[22:23] op_sel_hi:[1,0,1]
	v_pk_fma_f32 v[24:25], v[24:25], v[228:229], v[32:33] op_sel_hi:[1,0,1]
	v_pk_fma_f32 v[6:7], v[6:7], v[242:243], v[14:15] op_sel_hi:[1,0,1]
	v_max3_f32 v14, v39, v52, v56
	v_max3_f32 v15, v41, v54, v58
	v_mov_b32_e32 v109, v107
	v_pk_fma_f32 v[16:17], v[16:17], v[234:235], v[24:25] op_sel_hi:[1,0,1]
	v_max3_f32 v225, v14, v62, v106
	v_max3_f32 v227, v15, v64, v108
	v_pk_fma_f32 v[14:15], v[26:27], v[30:31], v[36:37] op_sel_hi:[1,0,1]
	v_permlane16_swap_b32_e32 v107, v109
	v_pk_fma_f32 v[8:9], v[8:9], v[242:243], v[16:17] op_sel_hi:[1,0,1]
	v_max3_f32 v16, v223, v53, v57
	v_max3_f32 v17, v229, v55, v60
	v_pk_fma_f32 v[14:15], v[18:19], v[38:39], v[14:15] op_sel_hi:[1,0,1]
	v_max3_f32 v233, v16, v63, v107
	v_max3_f32 v235, v17, v65, v109
	v_pk_fma_f32 v[16:17], v[28:29], v[30:31], v[34:35] op_sel_hi:[1,0,1]
	v_pk_fma_f32 v[10:11], v[10:11], v[40:41], v[14:15] op_sel_hi:[1,0,1]
	v_pk_fma_f32 v[16:17], v[20:21], v[38:39], v[16:17] op_sel_hi:[1,0,1]
	v_pk_fma_f32 v[2:3], v[2:3], v[238:239], v[10:11] op_sel_hi:[1,0,1]
	v_sub_f32_e32 v11, v223, v233
	v_pk_fma_f32 v[12:13], v[12:13], v[40:41], v[16:17] op_sel_hi:[1,0,1]
	v_exp_f32_e32 v24, v11
	v_sub_f32_e32 v11, v229, v235
	v_pk_fma_f32 v[4:5], v[4:5], v[238:239], v[12:13] op_sel_hi:[1,0,1]
	v_exp_f32_e32 v12, v11
	v_sub_f32_e32 v11, v52, v225
	v_exp_f32_e32 v14, v11
	v_sub_f32_e32 v11, v54, v227
	v_exp_f32_e32 v16, v11
	v_sub_f32_e32 v11, v53, v233
	v_sub_f32_e32 v10, v39, v225
	v_exp_f32_e32 v20, v11
	v_exp_f32_e32 v22, v10
	v_sub_f32_e32 v10, v41, v227
	v_exp_f32_e32 v10, v10
	v_sub_f32_e32 v13, v55, v235
	v_exp_f32_e32 v18, v13
	v_mov_b32_e32 v21, v20
	v_mov_b32_e32 v19, v16
	v_fmac_f32_e32 v21, v231, v24
	v_sub_f32_e32 v23, v63, v233
	v_fmac_f32_e32 v19, v61, v10
	v_pk_mul_f32 v[182:183], v[100:101], v[20:21] op_sel_hi:[1,0]
	v_pk_mul_f32 v[184:185], v[98:99], v[20:21] op_sel_hi:[1,0]
	v_sub_f32_e32 v20, v57, v233
	v_exp_f32_e32 v232, v23
	v_sub_f32_e32 v23, v65, v235
	v_fma_f32 v11, v31, v12, v18
	v_pk_mul_f32 v[202:203], v[100:101], v[18:19] op_sel_hi:[1,0]
	v_pk_mul_f32 v[204:205], v[98:99], v[18:19] op_sel_hi:[1,0]
	v_sub_f32_e32 v18, v56, v225
	v_exp_f32_e32 v226, v20
	v_sub_f32_e32 v20, v60, v235
	v_exp_f32_e32 v234, v23
	v_sub_f32_e32 v23, v106, v225
	v_exp_f32_e32 v224, v18
	v_sub_f32_e32 v18, v58, v227
	v_exp_f32_e32 v228, v20
	v_sub_f32_e32 v20, v62, v225
	v_exp_f32_e32 v236, v23
	v_sub_f32_e32 v23, v108, v227
	v_exp_f32_e32 v18, v18
	v_exp_f32_e32 v230, v20
	v_sub_f32_e32 v20, v64, v227
	v_exp_f32_e32 v238, v23
	v_sub_f32_e32 v23, v107, v233
	v_exp_f32_e32 v20, v20
	v_exp_f32_e32 v240, v23
	v_sub_f32_e32 v23, v109, v235
	v_mov_b32_e32 v13, v14
	v_exp_f32_e32 v242, v23
	v_fmac_f32_e32 v13, v59, v22
	v_add_f32_e32 v13, v224, v13
	v_add_f32_e32 v19, v18, v19
	v_add_f32_e32 v21, v226, v21
	v_add_f32_e32 v11, v228, v11
	v_add_f32_e32 v13, v230, v13
	v_add_f32_e32 v19, v20, v19
	v_add_f32_e32 v21, v232, v21
	v_add_f32_e32 v11, v234, v11
	v_pk_mul_f32 v[178:179], v[104:105], v[14:15] op_sel_hi:[1,0]
	v_pk_mul_f32 v[180:181], v[102:103], v[14:15] op_sel_hi:[1,0]
	v_pk_mul_f32 v[14:15], v[104:105], v[16:17] op_sel_hi:[1,0]
	v_pk_mul_f32 v[16:17], v[102:103], v[16:17] op_sel_hi:[1,0]
	v_add_f32_e32 v13, v236, v13
	v_add_f32_e32 v19, v238, v19
	v_add_f32_e32 v21, v240, v21
	v_add_f32_e32 v11, v242, v11
	s_add_u32 s0, s8, s38
	s_addc_u32 s1, s9, s39
	global_load_dwordx4 v[126:129], v186, s[0:1] nt
	global_load_dwordx4 v[122:125], v186, s[0:1] offset:1024 nt
	s_add_u32 s0, s26, s38
	s_addc_u32 s1, s27, s39
	global_load_dwordx4 v[30:33], v186, s[0:1] nt
	global_load_dwordx4 v[62:65], v186, s[0:1] offset:1024 nt
	s_add_u32 s0, s8, s40
	s_addc_u32 s1, s9, s41
	global_load_dwordx4 v[118:121], v186, s[0:1] nt
	global_load_dwordx4 v[114:117], v186, s[0:1] offset:1024 nt
	s_add_u32 s0, s26, s40
	s_addc_u32 s1, s27, s41
	global_load_dwordx4 v[34:37], v186, s[0:1] nt
	global_load_dwordx4 v[58:61], v186, s[0:1] offset:1024 nt
	s_add_u32 s0, s8, s42
	s_addc_u32 s1, s9, s43
	global_load_dwordx4 v[110:113], v186, s[0:1] nt
	global_load_dwordx4 v[106:109], v186, s[0:1] offset:1024 nt
	s_add_u32 s0, s26, s42
	s_addc_u32 s1, s27, s43
	global_load_dwordx4 v[38:41], v186, s[0:1] nt
	global_load_dwordx4 v[54:57], v186, s[0:1] offset:1024 nt
	s_add_u32 s0, s8, s44
	s_addc_u32 s1, s9, s45
	global_load_dwordx4 v[102:105], v186, s[0:1] nt
	global_load_dwordx4 v[98:101], v186, s[0:1] offset:1024 nt
	s_add_u32 s0, s26, s44
	s_addc_u32 s1, s27, s45
	global_load_dwordx4 v[26:29], v186, s[0:1] nt
	global_load_dwordx4 v[50:53], v186, s[0:1] offset:1024 nt
	v_pk_fma_f32 v[180:181], v[208:209], v[22:23], v[180:181] op_sel_hi:[1,0,1]
	v_pk_fma_f32 v[22:23], v[206:207], v[22:23], v[178:179] op_sel_hi:[1,0,1]
	v_pk_fma_f32 v[178:179], v[212:213], v[24:25], v[184:185] op_sel_hi:[1,0,1]
	v_pk_fma_f32 v[24:25], v[210:211], v[24:25], v[182:183] op_sel_hi:[1,0,1]
	v_pk_fma_f32 v[22:23], v[132:133], v[224:225], v[22:23] op_sel_hi:[1,0,1]
	v_pk_fma_f32 v[180:181], v[130:131], v[224:225], v[180:181] op_sel_hi:[1,0,1]
	v_pk_fma_f32 v[24:25], v[144:145], v[226:227], v[24:25] op_sel_hi:[1,0,1]
	v_pk_fma_f32 v[178:179], v[142:143], v[226:227], v[178:179] op_sel_hi:[1,0,1]
	v_pk_fma_f32 v[182:183], v[134:135], v[230:231], v[180:181] op_sel_hi:[1,0,1]
	v_pk_fma_f32 v[22:23], v[136:137], v[230:231], v[22:23] op_sel_hi:[1,0,1]
	v_pk_fma_f32 v[206:207], v[146:147], v[232:233], v[178:179] op_sel_hi:[1,0,1]
	v_pk_fma_f32 v[24:25], v[148:149], v[232:233], v[24:25] op_sel_hi:[1,0,1]
	s_waitcnt vmcnt(33)
	v_pk_fma_f32 v[180:181], v[140:141], v[236:237], v[22:23] op_sel_hi:[1,0,1]
	v_pk_fma_f32 v[184:185], v[138:139], v[236:237], v[182:183] op_sel_hi:[1,0,1]
	s_waitcnt vmcnt(32)
	v_pk_fma_f32 v[178:179], v[152:153], v[240:241], v[24:25] op_sel_hi:[1,0,1]
	v_pk_fma_f32 v[182:183], v[150:151], v[240:241], v[206:207] op_sel_hi:[1,0,1]
	s_waitcnt vmcnt(31)
	v_mul_f32_e32 v24, v222, v95
	v_fmac_f32_e32 v24, v221, v94
	v_pk_mul_f32 v[22:23], v[96:97], v[200:201]
	s_waitcnt vmcnt(30)
	v_mul_f32_e32 v25, v220, v91
	v_add_f32_e32 v22, v22, v24
	v_add_f32_e32 v24, v23, v22
	v_fmac_f32_e32 v25, v219, v90
	v_pk_mul_f32 v[22:23], v[92:93], v[198:199]
	s_waitcnt vmcnt(27)
	v_mul_f32_e32 v87, v222, v87
	v_add_f32_e32 v22, v22, v25
	v_add_f32_e32 v22, v23, v22
	v_add_f32_dpp v23, v24, v24 quad_perm:[1,0,3,2] row_mask:0xf bank_mask:0xf bound_ctrl:1
	v_fmac_f32_e32 v87, v221, v86
	v_add_f32_dpp v22, v22, v22 quad_perm:[1,0,3,2] row_mask:0xf bank_mask:0xf bound_ctrl:1
	v_add_f32_dpp v23, v23, v23 quad_perm:[2,3,0,1] row_mask:0xf bank_mask:0xf bound_ctrl:1
	s_waitcnt vmcnt(26)
	v_mul_f32_e32 v83, v220, v83
	v_add_f32_dpp v22, v22, v22 quad_perm:[2,3,0,1] row_mask:0xf bank_mask:0xf bound_ctrl:1
	v_add_f32_dpp v23, v23, v23 row_ror:4 row_mask:0xf bank_mask:0xf bound_ctrl:1
	v_fmac_f32_e32 v83, v219, v82
	v_add_f32_dpp v22, v22, v22 row_ror:4 row_mask:0xf bank_mask:0xf bound_ctrl:1
	v_add_f32_dpp v24, v23, v23 row_ror:8 row_mask:0xf bank_mask:0xf bound_ctrl:1
	s_waitcnt vmcnt(23)
	v_mul_f32_e32 v79, v222, v79
	v_add_f32_dpp v25, v22, v22 row_ror:8 row_mask:0xf bank_mask:0xf bound_ctrl:1
	v_pk_mul_f32 v[22:23], v[88:89], v[200:201]
	v_fmac_f32_e32 v79, v221, v78
	v_add_f32_e32 v22, v22, v87
	v_add_f32_e32 v86, v23, v22
	v_pk_mul_f32 v[22:23], v[84:85], v[198:199]
	s_waitcnt vmcnt(22)
	v_mul_f32_e32 v75, v220, v75
	v_add_f32_e32 v22, v22, v83
	v_add_f32_e32 v22, v23, v22
	v_add_f32_dpp v23, v86, v86 quad_perm:[1,0,3,2] row_mask:0xf bank_mask:0xf bound_ctrl:1
	v_fmac_f32_e32 v75, v219, v74
	v_add_f32_dpp v22, v22, v22 quad_perm:[1,0,3,2] row_mask:0xf bank_mask:0xf bound_ctrl:1
	v_add_f32_dpp v23, v23, v23 quad_perm:[2,3,0,1] row_mask:0xf bank_mask:0xf bound_ctrl:1
	s_waitcnt vmcnt(19)
	v_mul_f32_e32 v71, v222, v71
	v_add_f32_dpp v22, v22, v22 quad_perm:[2,3,0,1] row_mask:0xf bank_mask:0xf bound_ctrl:1
	v_add_f32_dpp v23, v23, v23 row_ror:4 row_mask:0xf bank_mask:0xf bound_ctrl:1
	v_fmac_f32_e32 v71, v221, v70
	v_add_f32_dpp v22, v22, v22 row_ror:4 row_mask:0xf bank_mask:0xf bound_ctrl:1
	v_add_f32_dpp v82, v23, v23 row_ror:8 row_mask:0xf bank_mask:0xf bound_ctrl:1
	s_waitcnt vmcnt(18)
	v_mul_f32_e32 v67, v220, v67
	v_add_f32_dpp v83, v22, v22 row_ror:8 row_mask:0xf bank_mask:0xf bound_ctrl:1
	v_pk_mul_f32 v[22:23], v[80:81], v[200:201]
	v_fmac_f32_e32 v67, v219, v66
	v_add_f32_e32 v22, v22, v79
	v_add_f32_e32 v78, v23, v22
	v_pk_mul_f32 v[22:23], v[76:77], v[198:199]
	v_pk_fma_f32 v[6:7], v[6:7], v[12:13], v[204:205] op_sel_hi:[1,0,1]
	v_add_f32_e32 v22, v22, v75
	v_add_f32_e32 v22, v23, v22
	v_add_f32_dpp v23, v78, v78 quad_perm:[1,0,3,2] row_mask:0xf bank_mask:0xf bound_ctrl:1
	v_mov_b32_e32 v90, v24
	v_add_f32_dpp v22, v22, v22 quad_perm:[1,0,3,2] row_mask:0xf bank_mask:0xf bound_ctrl:1
	v_add_f32_dpp v23, v23, v23 quad_perm:[2,3,0,1] row_mask:0xf bank_mask:0xf bound_ctrl:1
	v_mov_b32_e32 v84, v82
	v_add_f32_dpp v22, v22, v22 quad_perm:[2,3,0,1] row_mask:0xf bank_mask:0xf bound_ctrl:1
	v_add_f32_dpp v23, v23, v23 row_ror:4 row_mask:0xf bank_mask:0xf bound_ctrl:1
	v_pk_fma_f32 v[8:9], v[8:9], v[12:13], v[202:203] op_sel_hi:[1,0,1]
	v_add_f32_dpp v22, v22, v22 row_ror:4 row_mask:0xf bank_mask:0xf bound_ctrl:1
	v_add_f32_dpp v74, v23, v23 row_ror:8 row_mask:0xf bank_mask:0xf bound_ctrl:1
	v_pk_fma_f32 v[6:7], v[142:143], v[228:229], v[6:7] op_sel_hi:[1,0,1]
	v_add_f32_dpp v75, v22, v22 row_ror:8 row_mask:0xf bank_mask:0xf bound_ctrl:1
	v_pk_mul_f32 v[22:23], v[72:73], v[200:201]
	v_permlane16_swap_b32_e32 v24, v90
	v_add_f32_e32 v22, v22, v71
	v_add_f32_e32 v70, v23, v22
	v_pk_mul_f32 v[22:23], v[68:69], v[198:199]
	v_permlane16_swap_b32_e32 v82, v84
	v_add_f32_e32 v22, v22, v67
	v_add_f32_e32 v22, v23, v22
	v_add_f32_dpp v23, v70, v70 quad_perm:[1,0,3,2] row_mask:0xf bank_mask:0xf bound_ctrl:1
	v_mov_b32_e32 v76, v74
	v_add_f32_dpp v22, v22, v22 quad_perm:[1,0,3,2] row_mask:0xf bank_mask:0xf bound_ctrl:1
	v_add_f32_dpp v23, v23, v23 quad_perm:[2,3,0,1] row_mask:0xf bank_mask:0xf bound_ctrl:1
	v_pk_fma_f32 v[8:9], v[144:145], v[228:229], v[8:9] op_sel_hi:[1,0,1]
	v_add_f32_dpp v22, v22, v22 quad_perm:[2,3,0,1] row_mask:0xf bank_mask:0xf bound_ctrl:1
	v_add_f32_dpp v23, v23, v23 row_ror:4 row_mask:0xf bank_mask:0xf bound_ctrl:1
	v_pk_fma_f32 v[6:7], v[146:147], v[234:235], v[6:7] op_sel_hi:[1,0,1]
	v_add_f32_dpp v22, v22, v22 row_ror:4 row_mask:0xf bank_mask:0xf bound_ctrl:1
	v_add_f32_dpp v23, v23, v23 row_ror:8 row_mask:0xf bank_mask:0xf bound_ctrl:1
	v_mov_b32_e32 v66, v23
	v_pk_fma_f32 v[2:3], v[2:3], v[10:11], v[16:17] op_sel_hi:[1,0,1]
	v_mov_b32_e32 v91, v25
	v_mov_b32_e32 v85, v83
	v_permlane16_swap_b32_e32 v74, v76
	v_add_f32_dpp v22, v22, v22 row_ror:8 row_mask:0xf bank_mask:0xf bound_ctrl:1
	v_permlane16_swap_b32_e32 v23, v66
	v_pk_fma_f32 v[8:9], v[148:149], v[234:235], v[8:9] op_sel_hi:[1,0,1]
	v_pk_fma_f32 v[148:149], v[150:151], v[242:243], v[6:7] op_sel_hi:[1,0,1]
	v_max3_f32 v6, v225, v24, v82
	v_pk_fma_f32 v[4:5], v[4:5], v[10:11], v[14:15] op_sel_hi:[1,0,1]
	v_pk_fma_f32 v[2:3], v[130:131], v[18:19], v[2:3] op_sel_hi:[1,0,1]
	v_permlane16_swap_b32_e32 v25, v91
	v_permlane16_swap_b32_e32 v83, v85
	v_mov_b32_e32 v77, v75
	v_mov_b32_e32 v67, v22
	v_max3_f32 v7, v227, v90, v84
	v_max3_f32 v142, v6, v74, v23
	v_pk_fma_f32 v[4:5], v[132:133], v[18:19], v[4:5] op_sel_hi:[1,0,1]
	v_pk_fma_f32 v[2:3], v[134:135], v[20:21], v[2:3] op_sel_hi:[1,0,1]
	v_permlane16_swap_b32_e32 v75, v77
	v_permlane16_swap_b32_e32 v22, v67
	v_pk_fma_f32 v[146:147], v[152:153], v[242:243], v[8:9] op_sel_hi:[1,0,1]
	v_max3_f32 v8, v233, v25, v83
	v_max3_f32 v144, v7, v76, v66
	v_pk_fma_f32 v[4:5], v[136:137], v[20:21], v[4:5] op_sel_hi:[1,0,1]
	v_pk_fma_f32 v[136:137], v[138:139], v[238:239], v[2:3] op_sel_hi:[1,0,1]
	v_sub_f32_e32 v2, v225, v142
	v_max3_f32 v9, v235, v91, v85
	v_max3_f32 v143, v8, v75, v22
	v_exp_f32_e32 v138, v2
	v_sub_f32_e32 v2, v227, v144
	v_max3_f32 v145, v9, v77, v67
	v_pk_fma_f32 v[134:135], v[140:141], v[238:239], v[4:5] op_sel_hi:[1,0,1]
	v_exp_f32_e32 v140, v2
	v_sub_f32_e32 v2, v233, v143
	v_exp_f32_e32 v150, v2
	v_sub_f32_e32 v2, v235, v145
	v_exp_f32_e32 v152, v2
	v_sub_f32_e32 v2, v24, v142
	v_exp_f32_e32 v2, v2
	v_sub_f32_e32 v4, v91, v145
	v_exp_f32_e32 v4, v4
	v_sub_f32_e32 v3, v90, v144
	v_mov_b32_e32 v5, v2
	v_exp_f32_e32 v6, v3
	v_sub_f32_e32 v3, v25, v143
	v_fmac_f32_e32 v5, v13, v138
	v_exp_f32_e32 v8, v3
	v_fma_f32 v3, v11, v152, v4
	v_pk_mul_f32 v[210:211], v[44:45], v[4:5] op_sel_hi:[1,0]
	v_pk_mul_f32 v[212:213], v[42:43], v[4:5] op_sel_hi:[1,0]
	v_sub_f32_e32 v4, v82, v142
	v_exp_f32_e32 v220, v4
	v_sub_f32_e32 v4, v84, v144
	v_exp_f32_e32 v222, v4
	v_sub_f32_e32 v4, v83, v143
	v_exp_f32_e32 v224, v4
	v_pk_mul_f32 v[198:199], v[48:49], v[2:3] op_sel_hi:[1,0]
	v_pk_mul_f32 v[200:201], v[46:47], v[2:3] op_sel_hi:[1,0]
	v_mov_b32_e32 v2, v6
	v_pk_mul_f32 v[202:203], v[48:49], v[6:7] op_sel_hi:[1,0]
	v_pk_mul_f32 v[204:205], v[46:47], v[6:7] op_sel_hi:[1,0]
	v_mov_b32_e32 v6, v8
	v_fmac_f32_e32 v6, v21, v150
	v_sub_f32_e32 v4, v85, v145
	v_exp_f32_e32 v226, v4
	v_add_f32_e32 v4, v220, v5
	v_add_f32_e32 v5, v224, v6
	v_sub_f32_e32 v6, v74, v142
	v_exp_f32_e32 v228, v6
	v_sub_f32_e32 v6, v76, v144
	v_exp_f32_e32 v230, v6
	v_sub_f32_e32 v6, v75, v143
	v_exp_f32_e32 v232, v6
	v_sub_f32_e32 v6, v77, v145
	v_exp_f32_e32 v234, v6
	v_sub_f32_e32 v6, v23, v142
	v_exp_f32_e32 v236, v6
	v_sub_f32_e32 v6, v66, v144
	v_exp_f32_e32 v238, v6
	v_sub_f32_e32 v6, v22, v143
	v_exp_f32_e32 v240, v6
	v_sub_f32_e32 v6, v67, v145
	v_exp_f32_e32 v242, v6
	v_fmac_f32_e32 v2, v19, v140
	v_add_f32_e32 v2, v222, v2
	v_add_f32_e32 v3, v226, v3
	v_add_f32_e32 v4, v228, v4
	v_add_f32_e32 v2, v230, v2
	v_add_f32_e32 v5, v232, v5
	v_add_f32_e32 v3, v234, v3
	v_add_f32_e32 v130, v236, v4
	v_add_f32_e32 v132, v238, v2
	v_add_f32_e32 v131, v240, v5
	v_add_f32_e32 v133, v242, v3
	v_pk_mul_f32 v[206:207], v[44:45], v[8:9] op_sel_hi:[1,0]
	v_pk_mul_f32 v[208:209], v[42:43], v[8:9] op_sel_hi:[1,0]
	s_add_u32 s0, s8, s46
	s_addc_u32 s1, s9, s47
	global_load_dwordx4 v[86:89], v186, s[0:1] nt
	global_load_dwordx4 v[82:85], v186, s[0:1] offset:1024 nt
	s_add_u32 s0, s26, s46
	s_addc_u32 s1, s27, s47
	global_load_dwordx4 v[94:97], v186, s[0:1] nt
	global_load_dwordx4 v[90:93], v186, s[0:1] offset:1024 nt
	s_add_u32 s0, s8, s48
	s_addc_u32 s1, s9, s49
	global_load_dwordx4 v[78:81], v186, s[0:1] nt
	global_load_dwordx4 v[74:77], v186, s[0:1] offset:1024 nt
	s_add_u32 s0, s26, s48
	s_addc_u32 s1, s27, s49
	global_load_dwordx4 v[18:21], v186, s[0:1] nt
	global_load_dwordx4 v[22:25], v186, s[0:1] offset:1024 nt
	s_add_u32 s0, s8, s50
	s_addc_u32 s1, s9, s51
	global_load_dwordx4 v[70:73], v186, s[0:1] nt
	global_load_dwordx4 v[66:69], v186, s[0:1] offset:1024 nt
	s_add_u32 s0, s26, s50
	s_addc_u32 s1, s27, s51
	global_load_dwordx4 v[10:13], v186, s[0:1] nt
	global_load_dwordx4 v[14:17], v186, s[0:1] offset:1024 nt
	s_add_u32 s0, s8, s14
	s_addc_u32 s1, s9, s15
	global_load_dwordx4 v[46:49], v186, s[0:1] nt
	global_load_dwordx4 v[42:45], v186, s[0:1] offset:1024 nt
	s_add_u32 s0, s26, s14
	s_addc_u32 s1, s27, s15
	global_load_dwordx4 v[2:5], v186, s[0:1] nt
	global_load_dwordx4 v[6:9], v186, s[0:1] offset:1024 nt
	v_pk_fma_f32 v[184:185], v[184:185], v[138:139], v[200:201] op_sel_hi:[1,0,1]
	v_pk_fma_f32 v[138:139], v[180:181], v[138:139], v[198:199] op_sel_hi:[1,0,1]
	v_pk_fma_f32 v[136:137], v[136:137], v[140:141], v[204:205] op_sel_hi:[1,0,1]
	v_pk_fma_f32 v[134:135], v[134:135], v[140:141], v[202:203] op_sel_hi:[1,0,1]
	v_pk_fma_f32 v[140:141], v[182:183], v[150:151], v[208:209] op_sel_hi:[1,0,1]
	v_pk_fma_f32 v[150:151], v[178:179], v[150:151], v[206:207] op_sel_hi:[1,0,1]
	v_pk_fma_f32 v[148:149], v[148:149], v[152:153], v[212:213] op_sel_hi:[1,0,1]
	v_pk_fma_f32 v[146:147], v[146:147], v[152:153], v[210:211] op_sel_hi:[1,0,1]
	v_pk_fma_f32 v[138:139], v[176:177], v[220:221], v[138:139] op_sel_hi:[1,0,1]
	v_pk_fma_f32 v[152:153], v[174:175], v[220:221], v[184:185] op_sel_hi:[1,0,1]
	v_pk_fma_f32 v[134:135], v[176:177], v[222:223], v[134:135] op_sel_hi:[1,0,1]
	v_pk_fma_f32 v[136:137], v[174:175], v[222:223], v[136:137] op_sel_hi:[1,0,1]
	v_pk_fma_f32 v[150:151], v[168:169], v[224:225], v[150:151] op_sel_hi:[1,0,1]
	v_pk_fma_f32 v[140:141], v[166:167], v[224:225], v[140:141] op_sel_hi:[1,0,1]
	v_pk_fma_f32 v[146:147], v[168:169], v[226:227], v[146:147] op_sel_hi:[1,0,1]
	v_pk_fma_f32 v[148:149], v[166:167], v[226:227], v[148:149] op_sel_hi:[1,0,1]
	v_pk_fma_f32 v[152:153], v[170:171], v[228:229], v[152:153] op_sel_hi:[1,0,1]
	v_pk_fma_f32 v[138:139], v[172:173], v[228:229], v[138:139] op_sel_hi:[1,0,1]
	v_pk_fma_f32 v[166:167], v[170:171], v[230:231], v[136:137] op_sel_hi:[1,0,1]
	v_pk_fma_f32 v[168:169], v[172:173], v[230:231], v[134:135] op_sel_hi:[1,0,1]
	v_pk_fma_f32 v[170:171], v[158:159], v[232:233], v[140:141] op_sel_hi:[1,0,1]
	v_pk_fma_f32 v[150:151], v[160:161], v[232:233], v[150:151] op_sel_hi:[1,0,1]
	v_pk_fma_f32 v[158:159], v[158:159], v[234:235], v[148:149] op_sel_hi:[1,0,1]
	v_pk_fma_f32 v[160:161], v[160:161], v[234:235], v[146:147] op_sel_hi:[1,0,1]
	s_waitcnt vmcnt(33)
	v_pk_fma_f32 v[136:137], v[164:165], v[236:237], v[138:139] op_sel_hi:[1,0,1]
	v_pk_fma_f32 v[134:135], v[162:163], v[236:237], v[152:153] op_sel_hi:[1,0,1]
	v_pk_fma_f32 v[140:141], v[164:165], v[238:239], v[168:169] op_sel_hi:[1,0,1]
	v_pk_fma_f32 v[138:139], v[162:163], v[238:239], v[166:167] op_sel_hi:[1,0,1]
	s_waitcnt vmcnt(32)
	v_pk_fma_f32 v[148:149], v[156:157], v[240:241], v[150:151] op_sel_hi:[1,0,1]
	v_pk_fma_f32 v[146:147], v[154:155], v[240:241], v[170:171] op_sel_hi:[1,0,1]
	v_pk_fma_f32 v[152:153], v[156:157], v[242:243], v[160:161] op_sel_hi:[1,0,1]
	v_pk_fma_f32 v[150:151], v[154:155], v[242:243], v[158:159] op_sel_hi:[1,0,1]
	ds_write_b128 v1, v[134:137]
	ds_write_b128 v1, v[146:149] offset:1024
	ds_write_b128 v1, v[138:141] offset:2048
	ds_write_b128 v1, v[150:153] offset:3072
	s_and_saveexec_b64 s[0:1], vcc
	s_cbranch_execz .LBB0_238
	v_add_u32_e32 v134, 0x8000, v214
	ds_write2_b32 v134, v142, v144 offset1:1
	v_add_u32_e32 v134, 0x8010, v214
	ds_write2_b32 v134, v143, v145 offset1:1
	v_add_u32_e32 v134, 0x8100, v214
	ds_write2_b32 v134, v130, v132 offset1:1
	v_add_u32_e32 v130, 0x8110, v214
	ds_write2_b32 v130, v131, v133 offset1:1

.LBB0_624:
	v_readlane_b32 s4, v245, 2
	v_readlane_b32 s7, v245, 5
	s_bitcmp0_b32 s7, 5
	v_readlane_b32 s5, v245, 3
	v_readlane_b32 s6, v245, 4
	s_cbranch_scc1 .LBB0_635
	s_and_b32 s33, s95, -2
	s_ashr_i32 s1, s95, 31
	s_add_i32 s0, s33, s1
	s_xor_b32 s2, s0, s1
	v_cvt_f32_u32_e32 v1, s2
	v_readlane_b32 s0, v245, 54
	s_lshl_b32 s0, s0, 1
	s_sub_i32 s3, s33, s0
	v_rcp_iflag_f32_e32 v1, v1
	s_addk_i32 s3, 0x6ef
	s_ashr_i32 s4, s3, 31
	s_sub_i32 s5, 0, s2
	v_mul_f32_e32 v1, 0x4f7ffffe, v1
	v_cvt_u32_f32_e32 v1, v1
	s_xor_b32 s56, s4, s1
	s_abs_i32 s3, s3
	v_mov_b32_e32 v131, v0
	v_readfirstlane_b32 s1, v1
	s_mul_i32 s5, s5, s1
	s_mul_hi_u32 s4, s1, s5
	s_add_i32 s1, s1, s4
	s_mul_hi_u32 s1, s3, s1
	s_mul_i32 s4, s1, s2
	s_sub_i32 s3, s3, s4
	s_add_i32 s5, s1, 1
	s_sub_i32 s4, s3, s2
	s_cmp_ge_u32 s3, s2
	s_cselect_b32 s1, s5, s1
	s_cselect_b32 s3, s4, s3
	s_add_i32 s4, s1, 1
	s_cmp_ge_u32 s3, s2
	s_cselect_b32 s1, s4, s1
	s_xor_b32 s57, s1, s56
	s_sub_i32 s68, s57, s56
	s_cmp_lt_i32 s68, 1
	v_readfirstlane_b32 s1, v131
	s_cbranch_scc1 .LBB0_635
	s_add_u32 s2, s96, 0xce00000
	s_addc_u32 s3, s97, 0
	s_ashr_i32 s58, s1, 6
	s_ashr_i32 s1, s0, 31
	v_readlane_b32 s8, v245, 9
	s_add_i32 s6, s0, 0x110
	s_lshl_b64 s[0:1], s[0:1], 2
	v_readlane_b32 s10, v245, 11
	v_readlane_b32 s11, v245, 12
	s_add_u32 s0, s10, s0
	s_addc_u32 s1, s11, s1
	v_mov_b32_e32 v187, 0
	global_load_dword v1, v187, s[0:1] offset:1088
	s_cmp_lg_u32 s68, 1
	s_cselect_b32 s4, s33, 0
	s_ashr_i32 s5, s4, 31
	s_lshl_b64 s[4:5], s[4:5], 2
	s_add_u32 s0, s0, s4
	v_readlane_b32 s16, v245, 17
	v_readlane_b32 s20, v245, 21
	s_addc_u32 s1, s1, s5
	s_lshl_b32 s4, s58, 4
	v_readlane_b32 s9, v245, 10
	v_readlane_b32 s17, v245, 18
	v_readlane_b32 s21, v245, 22
	s_ashr_i32 s8, s6, 4
	global_load_dword v133, v187, s[0:1] offset:1088
	s_or_b32 s16, s4, 1
	s_or_b32 s20, s4, 2
	s_or_b32 s24, s4, 3
	s_or_b32 s30, s4, 4
	s_or_b32 s36, s4, 5
	s_or_b32 s60, s4, 6
	s_or_b32 s0, s4, 7
	s_ashr_i32 s5, s4, 31
	s_ashr_i32 s9, s8, 31
	s_ashr_i32 s17, s16, 31
	s_ashr_i32 s21, s20, 31
	s_ashr_i32 s25, s24, 31
	s_ashr_i32 s31, s30, 31
	s_ashr_i32 s37, s36, 31
	s_ashr_i32 s61, s60, 31
	s_ashr_i32 s1, s0, 31
	s_lshl_b64 s[6:7], s[4:5], 9
	s_lshl_b64 s[8:9], s[8:9], 10
	s_lshl_b64 s[38:39], s[16:17], 9
	s_lshl_b64 s[40:41], s[20:21], 9
	s_lshl_b64 s[42:43], s[24:25], 9
	s_lshl_b64 s[44:45], s[30:31], 9
	s_lshl_b64 s[46:47], s[36:37], 9
	s_lshl_b64 s[48:49], s[60:61], 9
	s_lshl_b64 s[50:51], s[0:1], 9
	v_and_b32_e32 v130, 63, v131
	s_add_u32 s8, s2, s8
	v_lshlrev_b32_e32 v186, 3, v130
	s_addc_u32 s9, s3, s9
	s_waitcnt vmcnt(0)
	v_lshl_add_u64 v[34:35], s[8:9], 0, v[186:187]
	v_readlane_b32 s12, v245, 13
	v_readlane_b32 s13, v245, 14
	v_lshlrev_b32_e32 v132, 4, v130
	v_readlane_b32 s14, v245, 15
	v_readlane_b32 s15, v245, 16
	v_readlane_b32 s18, v245, 19
	v_readlane_b32 s19, v245, 20
	v_readlane_b32 s22, v245, 23
	v_readlane_b32 s23, v245, 24
	s_mov_b32 s94, s85
	s_mov_b32 s69, 0x1000000
	v_add_co_u32_e32 v36, vcc, s69, v34
	v_bfe_u32 v134, v131, 2, 4
	s_nop 0
	v_addc_co_u32_e32 v37, vcc, 0, v35, vcc
	v_ashrrev_i32_e32 v137, 6, v131
	v_bfe_u32 v139, v131, 5, 1
	v_ashrrev_i32_e32 v138, 7, v131
	v_lshlrev_b32_e32 v135, 1, v139
	v_and_b32_e32 v136, 31, v131
	v_lshl_add_u64 v[188:189], s[2:3], 0, v[186:187]
	v_lshlrev_b32_e32 v186, 4, v136
	s_mov_b64 s[2:3], 0x23200020
	v_lshl_add_u32 v215, v131, 2, 0
	v_lshlrev_b32_e32 v216, 4, v130
	s_mov_b32 s90, 0xff800000
	v_readfirstlane_b32 s8, v1
	s_ashr_i32 s9, s8, 31
	s_lshl_b64 s[8:9], s[8:9], 18
	s_add_u32 s10, s80, s8
	s_addc_u32 s11, s81, s9
	s_lshl_b64 s[12:13], s[0:1], 11
	s_add_u32 s0, s10, s12
	s_addc_u32 s1, s11, s13
	global_load_dwordx4 v[6:9], v132, s[0:1] offset:1024 nt
	global_load_dwordx4 v[2:5], v132, s[0:1] nt
	s_add_u32 s0, s78, s8
	s_addc_u32 s1, s79, s9
	s_add_u32 s8, s0, s12
	s_addc_u32 s9, s1, s13
	s_lshl_b64 s[14:15], s[4:5], 11
	s_add_u32 s12, s0, s14
	s_addc_u32 s13, s1, s15
	s_lshl_b64 s[18:19], s[16:17], 11
	s_add_u32 s16, s0, s18
	s_addc_u32 s17, s1, s19
	s_lshl_b64 s[22:23], s[20:21], 11
	s_add_u32 s20, s0, s22
	s_addc_u32 s21, s1, s23
	s_lshl_b64 s[28:29], s[24:25], 11
	s_add_u32 s24, s0, s28
	global_load_dwordx4 v[26:29], v132, s[8:9] offset:1024 nt
	global_load_dwordx4 v[30:33], v132, s[8:9] nt
	s_addc_u32 s25, s1, s29
	s_lshl_b64 s[8:9], s[30:31], 11
	s_add_u32 s30, s0, s8
	s_addc_u32 s31, s1, s9
	s_lshl_b64 s[36:37], s[36:37], 11
	s_add_u32 s84, s0, s36
	s_addc_u32 s85, s1, s37
	s_lshl_b64 s[60:61], s[60:61], 11
	global_load_dwordx4 v[62:65], v132, s[84:85] nt
	global_load_dwordx4 v[58:61], v132, s[84:85] offset:1024 nt
	s_add_u32 s84, s0, s60
	s_addc_u32 s85, s1, s61
	s_add_u32 s60, s10, s60
	s_addc_u32 s61, s11, s61
	s_add_u32 s36, s10, s36
	s_addc_u32 s37, s11, s37
	global_load_dwordx4 v[54:57], v132, s[84:85] nt
	global_load_dwordx4 v[50:53], v132, s[84:85] offset:1024 nt
	global_load_dwordx4 v[22:25], v132, s[60:61] offset:1024 nt
	global_load_dwordx4 v[14:17], v132, s[60:61] nt
	global_load_dwordx4 v[18:21], v132, s[36:37] offset:1024 nt
	global_load_dwordx4 v[10:13], v132, s[36:37] nt
	s_add_u32 s36, s10, s8
	s_addc_u32 s37, s11, s9
	s_mov_b64 s[8:9], 0x1000000
	v_lshl_add_u64 v[34:35], v[34:35], 0, s[8:9]
	global_load_dwordx2 v[34:35], v[34:35], off offset:512
	s_nop 0
	global_load_dwordx2 v[36:37], v[36:37], off
	s_nop 0
	global_load_dwordx4 v[66:69], v132, s[36:37] offset:1024 nt
	global_load_dwordx4 v[70:73], v132, s[36:37] nt
	s_add_u32 s28, s10, s28
	s_addc_u32 s29, s11, s29
	s_add_u32 s22, s10, s22
	s_addc_u32 s23, s11, s23
	s_add_u32 s18, s10, s18
	s_addc_u32 s19, s11, s19
	s_add_u32 s14, s10, s14
	s_addc_u32 s15, s11, s15
	global_load_dwordx4 v[118:121], v132, s[30:31] nt
	global_load_dwordx4 v[114:117], v132, s[30:31] offset:1024 nt
	s_lshl_b32 s5, s58, 12
	s_add_i32 s5, s5, 0
	s_mulk_i32 s58, 0xf020
	v_add_u32_e32 v1, s5, v132
	s_add_i32 s5, s5, s58
	v_add_u32_e32 v214, s5, v134
	v_lshlrev_b32_e32 v134, 2, v137
	v_and_b32_e32 v134, 4, v134
	s_movk_i32 s37, 0x88
	v_add3_u32 v134, v138, v134, v135
	v_mul_lo_u32 v134, v134, s37
	v_ashrrev_i32_e32 v135, 31, v134
	v_lshl_add_u64 v[134:135], v[134:135], 2, v[186:187]
	v_lshl_add_u64 v[190:191], v[134:135], 0, s[2:3]
	v_readlane_b32 s2, v245, 51
	s_lshl_b32 s2, s2, 1
	v_readlane_b32 s3, v245, 52
	s_andn2_b32 s2, s2, 63
	s_lshl_b32 s3, s3, 1
	v_lshlrev_b32_e32 v134, 1, v137
	s_or_b32 s2, s2, s3
	v_and_or_b32 v134, v134, 2, v139
	s_add_i32 s86, s2, 0x110
	v_lshl_add_u32 v134, v134, 1, v138
	s_lshl_b32 s85, s33, 1
	s_movk_i32 s36, 0x100
	v_mul_lo_u32 v140, v131, s37
	s_ashr_i32 s87, s86, 31
	s_mul_i32 s3, s86, 0x1100
	v_lshl_add_u32 v186, v134, 2, 0
	v_and_b32_e32 v134, -8, v131
	s_mul_hi_i32 s2, s86, 0x1100
	v_lshl_add_u32 v137, v137, 10, 0
	v_mov_b32_e32 v135, v187
	s_mov_b32 s84, 2
	v_add_u32_e32 v217, v137, v132
	v_readfirstlane_b32 s26, v133
	s_waitcnt vmcnt(5)
	v_lshlrev_b32_e32 v219, 16, v34
	v_and_b32_e32 v220, 0xffff0000, v34
	v_lshlrev_b32_e32 v198, 16, v35
	v_and_b32_e32 v199, 0xffff0000, v35
	s_waitcnt vmcnt(4)
	v_lshlrev_b32_e32 v221, 16, v36
	v_and_b32_e32 v222, 0xffff0000, v36
	v_lshlrev_b32_e32 v200, 16, v37
	v_and_b32_e32 v201, 0xffff0000, v37
	global_load_dwordx4 v[74:77], v132, s[28:29] offset:1024 nt
	global_load_dwordx4 v[34:37], v132, s[28:29] nt
	global_load_dwordx4 v[94:97], v132, s[24:25] nt
	global_load_dwordx4 v[90:93], v132, s[24:25] offset:1024 nt
	global_load_dwordx4 v[78:81], v132, s[22:23] offset:1024 nt
	global_load_dwordx4 v[46:49], v132, s[22:23] nt
	global_load_dwordx4 v[102:105], v132, s[20:21] nt
	global_load_dwordx4 v[98:101], v132, s[20:21] offset:1024 nt
	global_load_dwordx4 v[82:85], v132, s[18:19] offset:1024 nt
	global_load_dwordx4 v[42:45], v132, s[18:19] nt
	global_load_dwordx4 v[110:113], v132, s[16:17] nt
	global_load_dwordx4 v[106:109], v132, s[16:17] offset:1024 nt
	global_load_dwordx4 v[86:89], v132, s[14:15] offset:1024 nt
	global_load_dwordx4 v[38:41], v132, s[14:15] nt
	global_load_dwordx4 v[126:129], v132, s[12:13] nt
	global_load_dwordx4 v[122:125], v132, s[12:13] offset:1024 nt
	s_or_b32 s12, s4, 8
	s_ashr_i32 s13, s12, 31
	s_lshl_b64 s[14:15], s[12:13], 9
	s_or_b32 s12, s4, 9
	s_ashr_i32 s13, s12, 31
	s_lshl_b64 s[16:17], s[12:13], 9
	s_or_b32 s12, s4, 10
	s_ashr_i32 s13, s12, 31
	s_lshl_b64 s[18:19], s[12:13], 9
	s_or_b32 s12, s4, 11
	s_ashr_i32 s13, s12, 31
	s_lshl_b64 s[20:21], s[12:13], 9
	s_or_b32 s12, s4, 13
	s_ashr_i32 s13, s12, 31
	s_or_b32 s22, s4, 12
	s_lshl_b64 s[24:25], s[12:13], 9
	s_or_b32 s12, s4, 14
	s_or_b32 s4, s4, 15
	s_ashr_i32 s23, s22, 31
	s_ashr_i32 s13, s12, 31
	s_ashr_i32 s5, s4, 31
	s_lshl_b64 s[22:23], s[22:23], 9
	s_lshl_b64 s[28:29], s[12:13], 9
	s_lshl_b64 s[30:31], s[4:5], 9
	s_add_u32 s12, s96, s3
	v_cmp_eq_u32_e64 s[4:5], s36, v134
	v_add_u32_e32 v134, 0xffff7800, v140
	s_addc_u32 s13, s97, s2
	v_cmp_gt_i32_e64 s[2:3], s36, v131
	s_sub_i32 s88, s56, s57
	v_lshlrev_b64 v[192:193], 2, v[134:135]
	s_lshl_b64 s[14:15], s[14:15], 2
	s_lshl_b64 s[16:17], s[16:17], 2
	s_lshl_b64 s[18:19], s[18:19], 2
	s_lshl_b64 s[20:21], s[20:21], 2
	s_lshl_b64 s[22:23], s[22:23], 2
	s_lshl_b64 s[24:25], s[24:25], 2
	s_lshl_b64 s[28:29], s[28:29], 2
	s_lshl_b64 s[30:31], s[30:31], 2
	s_lshl_b64 s[36:37], s[6:7], 2
	s_lshl_b64 s[38:39], s[38:39], 2
	s_lshl_b64 s[40:41], s[40:41], 2
	s_lshl_b64 s[42:43], s[42:43], 2
	s_lshl_b64 s[44:45], s[44:45], 2
	s_lshl_b64 s[46:47], s[46:47], 2
	s_lshl_b64 s[48:49], s[48:49], 2
	s_lshl_b64 s[50:51], s[50:51], 2
	s_ashr_i32 s89, s33, 31
	v_cmp_eq_u32_e64 s[6:7], 0, v136
	s_waitcnt vmcnt(0)
	s_branch .LBB0_628

.LBB0_628:
	s_add_i32 s91, s84, -1
	s_add_i32 s93, s33, s86
	s_cmp_lt_i32 s84, s68
	s_cselect_b32 s56, s85, 0
	s_ashr_i32 s27, s26, 31
	s_ashr_i32 s57, s56, 31
	s_add_u32 s56, s86, s56
	s_addc_u32 s57, s87, s57
	s_lshl_b64 s[96:97], s[56:57], 2
	v_readlane_b32 s52, v245, 9
	v_readlane_b32 s54, v245, 11
	v_readlane_b32 s56, v245, 13
	v_readlane_b32 s55, v245, 12
	v_readlane_b32 s57, v245, 14
	s_add_u32 s56, s54, s96
	s_addc_u32 s57, s55, s97
	s_cmp_lt_i32 s91, s68
	v_readlane_b32 s58, v245, 15
	v_readlane_b32 s59, v245, 16
	global_load_dword v218, v187, s[56:57]
	s_cselect_b32 s56, s93, s86
	s_ashr_i32 s56, s56, 4
	s_ashr_i32 s57, s56, 31
	s_lshl_b64 s[56:57], s[56:57], 10
	v_lshl_add_u64 v[130:131], v[188:189], 0, s[56:57]
	v_lshl_add_u64 v[132:133], v[130:131], 0, s[8:9]
	v_add_co_u32_e32 v130, vcc, s69, v130
	s_mov_b64 s[56:57], s[10:11]
	s_nop 0
	v_addc_co_u32_e32 v131, vcc, 0, v131, vcc
	global_load_dwordx2 v[196:197], v[130:131], off
	global_load_dwordx2 v[194:195], v[132:133], off offset:512
	v_readlane_b32 s53, v245, 10
	v_readlane_b32 s60, v245, 17
	v_readlane_b32 s61, v245, 18
	v_readlane_b32 s62, v245, 19
	v_readlane_b32 s63, v245, 20
	v_readlane_b32 s64, v245, 21
	v_readlane_b32 s65, v245, 22
	v_readlane_b32 s66, v245, 23
	v_readlane_b32 s67, v245, 24
	s_mov_b64 s[58:59], s[0:1]
	s_waitcnt vmcnt(34)
	v_mul_f32_e32 v130, v222, v127
	v_fmac_f32_e32 v130, v221, v126
	v_pk_mul_f32 v[126:127], v[200:201], v[128:129]
	s_lshl_b64 s[10:11], s[26:27], 18
	v_add_f32_e32 v126, v126, v130
	v_add_f32_e32 v126, v127, v126
	s_waitcnt vmcnt(33)
	v_mul_f32_e32 v127, v123, v220
	v_fmac_f32_e32 v127, v122, v219
	v_pk_mul_f32 v[122:123], v[124:125], v[198:199]
	s_add_u32 s0, s78, s10
	v_add_f32_e32 v122, v122, v127
	v_add_f32_e32 v122, v123, v122
	v_add_f32_dpp v123, v126, v126 quad_perm:[1,0,3,2] row_mask:0xf bank_mask:0xf bound_ctrl:1
	s_waitcnt vmcnt(30)
	v_mul_f32_e32 v126, v222, v111
	v_fmac_f32_e32 v126, v221, v110
	v_pk_mul_f32 v[110:111], v[200:201], v[112:113]
	v_add_f32_dpp v123, v123, v123 quad_perm:[2,3,0,1] row_mask:0xf bank_mask:0xf bound_ctrl:1
	v_add_f32_e32 v110, v110, v126
	v_add_f32_e32 v110, v111, v110
	s_waitcnt vmcnt(29)
	v_mul_f32_e32 v111, v107, v220
	v_fmac_f32_e32 v111, v106, v219
	v_pk_mul_f32 v[106:107], v[108:109], v[198:199]
	v_add_f32_dpp v122, v122, v122 quad_perm:[1,0,3,2] row_mask:0xf bank_mask:0xf bound_ctrl:1
	v_add_f32_e32 v106, v106, v111
	v_add_f32_e32 v106, v107, v106
	v_add_f32_dpp v107, v110, v110 quad_perm:[1,0,3,2] row_mask:0xf bank_mask:0xf bound_ctrl:1
	s_waitcnt vmcnt(26)
	v_mul_f32_e32 v110, v222, v103
	v_fmac_f32_e32 v110, v221, v102
	v_pk_mul_f32 v[102:103], v[200:201], v[104:105]
	v_add_f32_dpp v107, v107, v107 quad_perm:[2,3,0,1] row_mask:0xf bank_mask:0xf bound_ctrl:1
	v_add_f32_e32 v102, v102, v110
	v_add_f32_e32 v102, v103, v102
	s_waitcnt vmcnt(25)
	v_mul_f32_e32 v103, v99, v220
	v_fmac_f32_e32 v103, v98, v219
	v_pk_mul_f32 v[98:99], v[100:101], v[198:199]
	v_add_f32_dpp v106, v106, v106 quad_perm:[1,0,3,2] row_mask:0xf bank_mask:0xf bound_ctrl:1
	v_add_f32_e32 v98, v98, v103
	v_add_f32_e32 v98, v99, v98
	v_add_f32_dpp v99, v102, v102 quad_perm:[1,0,3,2] row_mask:0xf bank_mask:0xf bound_ctrl:1
	s_waitcnt vmcnt(22)
	v_mul_f32_e32 v102, v222, v95
	v_fmac_f32_e32 v102, v221, v94
	v_pk_mul_f32 v[94:95], v[200:201], v[96:97]
	v_add_f32_dpp v123, v123, v123 row_ror:4 row_mask:0xf bank_mask:0xf bound_ctrl:1
	v_add_f32_e32 v94, v94, v102
	v_add_f32_e32 v94, v95, v94
	s_waitcnt vmcnt(21)
	v_mul_f32_e32 v95, v91, v220
	v_fmac_f32_e32 v95, v90, v219
	v_pk_mul_f32 v[90:91], v[92:93], v[198:199]
	v_add_f32_dpp v122, v122, v122 quad_perm:[2,3,0,1] row_mask:0xf bank_mask:0xf bound_ctrl:1
	v_add_f32_e32 v90, v90, v95
	v_add_f32_e32 v90, v91, v90
	v_add_f32_dpp v91, v94, v94 quad_perm:[1,0,3,2] row_mask:0xf bank_mask:0xf bound_ctrl:1
	v_add_f32_dpp v107, v107, v107 row_ror:4 row_mask:0xf bank_mask:0xf bound_ctrl:1
	v_add_f32_dpp v106, v106, v106 quad_perm:[2,3,0,1] row_mask:0xf bank_mask:0xf bound_ctrl:1
	v_add_f32_dpp v99, v99, v99 quad_perm:[2,3,0,1] row_mask:0xf bank_mask:0xf bound_ctrl:1
	v_add_f32_dpp v98, v98, v98 quad_perm:[1,0,3,2] row_mask:0xf bank_mask:0xf bound_ctrl:1
	v_add_f32_dpp v91, v91, v91 quad_perm:[2,3,0,1] row_mask:0xf bank_mask:0xf bound_ctrl:1
	v_add_f32_dpp v90, v90, v90 quad_perm:[1,0,3,2] row_mask:0xf bank_mask:0xf bound_ctrl:1
	v_add_f32_dpp v123, v123, v123 row_ror:8 row_mask:0xf bank_mask:0xf bound_ctrl:1
	v_add_f32_dpp v122, v122, v122 row_ror:4 row_mask:0xf bank_mask:0xf bound_ctrl:1
	v_add_f32_dpp v107, v107, v107 row_ror:8 row_mask:0xf bank_mask:0xf bound_ctrl:1
	v_add_f32_dpp v106, v106, v106 row_ror:4 row_mask:0xf bank_mask:0xf bound_ctrl:1
	v_add_f32_dpp v99, v99, v99 row_ror:4 row_mask:0xf bank_mask:0xf bound_ctrl:1
	v_add_f32_dpp v98, v98, v98 quad_perm:[2,3,0,1] row_mask:0xf bank_mask:0xf bound_ctrl:1
	v_add_f32_dpp v91, v91, v91 row_ror:4 row_mask:0xf bank_mask:0xf bound_ctrl:1
	v_add_f32_dpp v90, v90, v90 quad_perm:[2,3,0,1] row_mask:0xf bank_mask:0xf bound_ctrl:1
	v_add_f32_dpp v122, v122, v122 row_ror:8 row_mask:0xf bank_mask:0xf bound_ctrl:1
	v_mov_b32_e32 v124, v123
	v_add_f32_dpp v106, v106, v106 row_ror:8 row_mask:0xf bank_mask:0xf bound_ctrl:1
	v_mov_b32_e32 v108, v107
	v_add_f32_dpp v99, v99, v99 row_ror:8 row_mask:0xf bank_mask:0xf bound_ctrl:1
	v_add_f32_dpp v98, v98, v98 row_ror:4 row_mask:0xf bank_mask:0xf bound_ctrl:1
	v_add_f32_dpp v96, v91, v91 row_ror:8 row_mask:0xf bank_mask:0xf bound_ctrl:1
	v_add_f32_dpp v90, v90, v90 row_ror:4 row_mask:0xf bank_mask:0xf bound_ctrl:1
	v_permlane16_swap_b32_e32 v123, v124
	v_mov_b32_e32 v125, v122
	v_permlane16_swap_b32_e32 v107, v108
	v_mov_b32_e32 v109, v106
	v_add_f32_dpp v98, v98, v98 row_ror:8 row_mask:0xf bank_mask:0xf bound_ctrl:1
	v_mov_b32_e32 v100, v99
	v_add_f32_dpp v97, v90, v90 row_ror:8 row_mask:0xf bank_mask:0xf bound_ctrl:1
	v_mov_b32_e32 v102, v96
	v_permlane16_swap_b32_e32 v122, v125
	v_permlane16_swap_b32_e32 v106, v109
	v_permlane16_swap_b32_e32 v99, v100
	v_mov_b32_e32 v101, v98
	v_permlane16_swap_b32_e32 v96, v102
	v_mov_b32_e32 v103, v97
	v_max3_f32 v90, v123, s90, v107
	v_permlane16_swap_b32_e32 v98, v101
	v_permlane16_swap_b32_e32 v97, v103
	v_max3_f32 v91, v124, s90, v108
	v_max3_f32 v92, v122, s90, v106
	v_max3_f32 v155, v90, v99, v96
	v_max3_f32 v157, v91, v100, v102
	v_max3_f32 v159, v92, v98, v97
	v_sub_f32_e32 v90, 0xff800000, v155
	v_sub_f32_e32 v92, v123, v155
	v_max3_f32 v93, v125, s90, v109
	v_exp_f32_e32 v91, v90
	v_sub_f32_e32 v90, 0xff800000, v157
	v_exp_f32_e32 v164, v92
	v_sub_f32_e32 v92, v124, v157
	v_max3_f32 v165, v93, v101, v103
	v_exp_f32_e32 v93, v90
	v_sub_f32_e32 v90, 0xff800000, v159
	v_exp_f32_e32 v156, v92
	v_sub_f32_e32 v92, v122, v159
	v_exp_f32_e32 v94, v90
	v_sub_f32_e32 v90, 0xff800000, v165
	v_exp_f32_e32 v166, v92
	v_sub_f32_e32 v92, v125, v165
	v_exp_f32_e32 v95, v90
	v_exp_f32_e32 v92, v92
	v_mul_f32_e32 v154, 0, v93
	v_fma_f32 v93, 0, v93, v156
	v_mul_f32_e32 v90, 0, v95
	v_mov_b32_e32 v110, v92
	v_mul_f32_e32 v160, 0, v91
	v_mul_f32_e32 v162, 0, v94
	v_fma_f32 v104, 0, v91, v164
	v_fma_f32 v105, 0, v94, v166
	v_fmac_f32_e32 v110, 0, v95
	v_pk_fma_f32 v[94:95], v[86:87], v[92:93], v[90:91] op_sel_hi:[1,0,0]
	v_pk_fma_f32 v[90:91], v[88:89], v[92:93], v[90:91] op_sel_hi:[1,0,0]
	v_sub_f32_e32 v92, v107, v155
	v_exp_f32_e32 v168, v92
	v_sub_f32_e32 v92, v108, v157
	v_exp_f32_e32 v158, v92
	v_sub_f32_e32 v92, v106, v159
	v_exp_f32_e32 v170, v92
	v_sub_f32_e32 v92, v109, v165
	v_exp_f32_e32 v92, v92
	v_add_f32_e32 v106, v158, v93
	v_add_f32_e32 v104, v168, v104
	v_add_f32_e32 v105, v170, v105
	v_add_f32_e32 v107, v92, v110
	v_pk_fma_f32 v[90:91], v[84:85], v[92:93], v[90:91] op_sel_hi:[1,0,1]
	v_pk_fma_f32 v[92:93], v[82:83], v[92:93], v[94:95] op_sel_hi:[1,0,1]
	v_sub_f32_e32 v94, v99, v155
	v_exp_f32_e32 v172, v94
	v_sub_f32_e32 v94, v100, v157
	v_exp_f32_e32 v174, v94
	v_sub_f32_e32 v94, v98, v159
	v_exp_f32_e32 v176, v94
	v_sub_f32_e32 v94, v101, v165
	v_exp_f32_e32 v94, v94
	v_add_f32_e32 v95, v172, v104
	v_add_f32_e32 v98, v174, v106
	v_add_f32_e32 v99, v176, v105
	v_add_f32_e32 v100, v94, v107
	v_pk_fma_f32 v[92:93], v[78:79], v[94:95], v[92:93] op_sel_hi:[1,0,1]
	v_pk_fma_f32 v[90:91], v[80:81], v[94:95], v[90:91] op_sel_hi:[1,0,1]
	v_sub_f32_e32 v94, v96, v155
	v_exp_f32_e32 v206, v94
	v_sub_f32_e32 v94, v102, v157
	v_exp_f32_e32 v208, v94
	v_sub_f32_e32 v94, v97, v159
	v_exp_f32_e32 v210, v94
	v_sub_f32_e32 v94, v103, v165
	v_exp_f32_e32 v94, v94
	s_addc_u32 s1, s79, s11
	v_add_f32_e32 v167, v206, v95
	v_add_f32_e32 v169, v208, v98
	v_add_f32_e32 v171, v210, v99
	v_add_f32_e32 v173, v94, v100
	s_waitcnt vmcnt(19)
	v_pk_fma_f32 v[202:203], v[76:77], v[94:95], v[90:91] op_sel_hi:[1,0,1]
	v_pk_fma_f32 v[204:205], v[74:75], v[94:95], v[92:93] op_sel_hi:[1,0,1]
	s_add_u32 s60, s58, s14
	s_addc_u32 s61, s59, s15
	global_load_dwordx4 v[182:185], v216, s[60:61] nt
	global_load_dwordx4 v[178:181], v216, s[60:61] offset:1024 nt
	s_add_u32 s60, s56, s14
	s_addc_u32 s61, s57, s15
	global_load_dwordx4 v[94:97], v216, s[60:61] nt
	global_load_dwordx4 v[90:93], v216, s[60:61] offset:1024 nt
	s_add_u32 s60, s58, s16
	s_addc_u32 s61, s59, s17
	global_load_dwordx4 v[126:129], v216, s[60:61] nt
	global_load_dwordx4 v[122:125], v216, s[60:61] offset:1024 nt
	s_add_u32 s60, s56, s16
	s_addc_u32 s61, s57, s17
	global_load_dwordx4 v[130:133], v216, s[60:61] nt
	global_load_dwordx4 v[142:145], v216, s[60:61] offset:1024 nt
	s_add_u32 s60, s58, s18
	s_addc_u32 s61, s59, s19
	global_load_dwordx4 v[110:113], v216, s[60:61] nt
	global_load_dwordx4 v[106:109], v216, s[60:61] offset:1024 nt
	s_add_u32 s60, s56, s18
	s_addc_u32 s61, s57, s19
	global_load_dwordx4 v[134:137], v216, s[60:61] nt
	global_load_dwordx4 v[146:149], v216, s[60:61] offset:1024 nt
	s_add_u32 s60, s58, s20
	s_addc_u32 s61, s59, s21
	global_load_dwordx4 v[102:105], v216, s[60:61] nt
	global_load_dwordx4 v[98:101], v216, s[60:61] offset:1024 nt
	s_add_u32 s60, s56, s20
	s_addc_u32 s61, s57, s21
	global_load_dwordx4 v[138:141], v216, s[60:61] nt
	global_load_dwordx4 v[150:153], v216, s[60:61] offset:1024 nt
	v_pk_fma_f32 v[212:213], v[38:39], v[164:165], v[160:161] op_sel_hi:[1,0,0]
	v_pk_fma_f32 v[160:161], v[40:41], v[164:165], v[160:161] op_sel_hi:[1,0,0]
	v_pk_fma_f32 v[86:87], v[86:87], v[166:167], v[162:163] op_sel_hi:[1,0,0]
	v_pk_fma_f32 v[88:89], v[88:89], v[166:167], v[162:163] op_sel_hi:[1,0,0]
	v_pk_fma_f32 v[160:161], v[44:45], v[168:169], v[160:161] op_sel_hi:[1,0,1]
	v_pk_fma_f32 v[162:163], v[42:43], v[168:169], v[212:213] op_sel_hi:[1,0,1]
	v_pk_fma_f32 v[84:85], v[84:85], v[170:171], v[88:89] op_sel_hi:[1,0,1]
	v_pk_fma_f32 v[82:83], v[82:83], v[170:171], v[86:87] op_sel_hi:[1,0,1]
	v_pk_fma_f32 v[86:87], v[46:47], v[172:173], v[162:163] op_sel_hi:[1,0,1]
	v_pk_fma_f32 v[88:89], v[48:49], v[172:173], v[160:161] op_sel_hi:[1,0,1]
	v_pk_fma_f32 v[82:83], v[78:79], v[176:177], v[82:83] op_sel_hi:[1,0,1]
	v_pk_fma_f32 v[84:85], v[80:81], v[176:177], v[84:85] op_sel_hi:[1,0,1]
	v_pk_fma_f32 v[78:79], v[36:37], v[206:207], v[88:89] op_sel_hi:[1,0,1]
	v_pk_fma_f32 v[80:81], v[34:35], v[206:207], v[86:87] op_sel_hi:[1,0,1]
	v_pk_fma_f32 v[76:77], v[76:77], v[210:211], v[84:85] op_sel_hi:[1,0,1]
	v_pk_fma_f32 v[74:75], v[74:75], v[210:211], v[82:83] op_sel_hi:[1,0,1]
	s_waitcnt vmcnt(34)
	v_mul_f32_e32 v84, v222, v119
	v_fmac_f32_e32 v84, v221, v118
	v_pk_mul_f32 v[82:83], v[200:201], v[120:121]
	s_waitcnt vmcnt(33)
	v_mul_f32_e32 v85, v115, v220
	v_add_f32_e32 v82, v82, v84
	v_add_f32_e32 v84, v83, v82
	v_fmac_f32_e32 v85, v114, v219
	v_pk_mul_f32 v[82:83], v[116:117], v[198:199]
	s_add_u32 s10, s80, s10
	v_add_f32_e32 v82, v82, v85
	v_add_f32_e32 v82, v83, v82
	v_add_f32_dpp v83, v84, v84 quad_perm:[1,0,3,2] row_mask:0xf bank_mask:0xf bound_ctrl:1
	s_addc_u32 s11, s81, s11
	v_add_f32_dpp v82, v82, v82 quad_perm:[1,0,3,2] row_mask:0xf bank_mask:0xf bound_ctrl:1
	v_add_f32_dpp v83, v83, v83 quad_perm:[2,3,0,1] row_mask:0xf bank_mask:0xf bound_ctrl:1
	s_nop 0
	v_add_f32_dpp v82, v82, v82 quad_perm:[2,3,0,1] row_mask:0xf bank_mask:0xf bound_ctrl:1
	v_add_f32_dpp v83, v83, v83 row_ror:4 row_mask:0xf bank_mask:0xf bound_ctrl:1
	s_nop 0
	v_add_f32_dpp v82, v82, v82 row_ror:4 row_mask:0xf bank_mask:0xf bound_ctrl:1
	v_add_f32_dpp v83, v83, v83 row_ror:8 row_mask:0xf bank_mask:0xf bound_ctrl:1
	v_mov_b32_e32 v86, v83
	v_add_f32_dpp v85, v82, v82 row_ror:8 row_mask:0xf bank_mask:0xf bound_ctrl:1
	s_waitcnt vmcnt(30)
	v_mul_f32_e32 v82, v222, v63
	v_fmac_f32_e32 v82, v221, v62
	v_pk_mul_f32 v[62:63], v[200:201], v[64:65]
	v_permlane16_swap_b32_e32 v83, v86
	v_add_f32_e32 v62, v62, v82
	v_add_f32_e32 v62, v63, v62
	s_waitcnt vmcnt(29)
	v_mul_f32_e32 v63, v59, v220
	v_fmac_f32_e32 v63, v58, v219
	v_pk_mul_f32 v[58:59], v[60:61], v[198:199]
	v_mov_b32_e32 v87, v85
	v_add_f32_e32 v58, v58, v63
	v_add_f32_e32 v58, v59, v58
	v_add_f32_dpp v59, v62, v62 quad_perm:[1,0,3,2] row_mask:0xf bank_mask:0xf bound_ctrl:1
	s_waitcnt vmcnt(26)
	v_mul_f32_e32 v62, v222, v55
	v_fmac_f32_e32 v62, v221, v54
	v_pk_mul_f32 v[54:55], v[200:201], v[56:57]
	v_add_f32_dpp v59, v59, v59 quad_perm:[2,3,0,1] row_mask:0xf bank_mask:0xf bound_ctrl:1
	v_add_f32_e32 v54, v54, v62
	v_add_f32_e32 v54, v55, v54
	s_waitcnt vmcnt(25)
	v_mul_f32_e32 v55, v51, v220
	v_fmac_f32_e32 v55, v50, v219
	v_pk_mul_f32 v[50:51], v[52:53], v[198:199]
	v_add_f32_dpp v59, v59, v59 row_ror:4 row_mask:0xf bank_mask:0xf bound_ctrl:1
	v_add_f32_e32 v50, v50, v55
	v_add_f32_e32 v50, v51, v50
	v_add_f32_dpp v51, v54, v54 quad_perm:[1,0,3,2] row_mask:0xf bank_mask:0xf bound_ctrl:1
	s_waitcnt vmcnt(22)
	v_mul_f32_e32 v54, v222, v31
	v_fmac_f32_e32 v54, v221, v30
	v_pk_mul_f32 v[30:31], v[200:201], v[32:33]
	v_add_f32_dpp v58, v58, v58 quad_perm:[1,0,3,2] row_mask:0xf bank_mask:0xf bound_ctrl:1
	v_add_f32_e32 v30, v30, v54
	v_add_f32_e32 v30, v31, v30
	s_waitcnt vmcnt(21)
	v_mul_f32_e32 v31, v27, v220
	v_fmac_f32_e32 v31, v26, v219
	v_pk_mul_f32 v[26:27], v[28:29], v[198:199]
	v_add_f32_dpp v51, v51, v51 quad_perm:[2,3,0,1] row_mask:0xf bank_mask:0xf bound_ctrl:1
	v_add_f32_e32 v26, v26, v31
	v_add_f32_e32 v26, v27, v26
	v_add_f32_dpp v27, v30, v30 quad_perm:[1,0,3,2] row_mask:0xf bank_mask:0xf bound_ctrl:1
	v_add_f32_dpp v59, v59, v59 row_ror:8 row_mask:0xf bank_mask:0xf bound_ctrl:1
	v_add_f32_dpp v26, v26, v26 quad_perm:[1,0,3,2] row_mask:0xf bank_mask:0xf bound_ctrl:1
	v_add_f32_dpp v27, v27, v27 quad_perm:[2,3,0,1] row_mask:0xf bank_mask:0xf bound_ctrl:1
	v_add_f32_dpp v58, v58, v58 quad_perm:[2,3,0,1] row_mask:0xf bank_mask:0xf bound_ctrl:1
	v_add_f32_dpp v51, v51, v51 row_ror:4 row_mask:0xf bank_mask:0xf bound_ctrl:1
	v_add_f32_dpp v50, v50, v50 quad_perm:[1,0,3,2] row_mask:0xf bank_mask:0xf bound_ctrl:1
	v_add_f32_dpp v27, v27, v27 row_ror:4 row_mask:0xf bank_mask:0xf bound_ctrl:1
	v_add_f32_dpp v26, v26, v26 quad_perm:[2,3,0,1] row_mask:0xf bank_mask:0xf bound_ctrl:1
	v_add_f32_dpp v58, v58, v58 row_ror:4 row_mask:0xf bank_mask:0xf bound_ctrl:1
	v_mov_b32_e32 v60, v59
	v_add_f32_dpp v51, v51, v51 row_ror:8 row_mask:0xf bank_mask:0xf bound_ctrl:1
	v_add_f32_dpp v50, v50, v50 quad_perm:[2,3,0,1] row_mask:0xf bank_mask:0xf bound_ctrl:1
	v_add_f32_dpp v31, v27, v27 row_ror:8 row_mask:0xf bank_mask:0xf bound_ctrl:1
	v_add_f32_dpp v26, v26, v26 row_ror:4 row_mask:0xf bank_mask:0xf bound_ctrl:1
	v_add_f32_dpp v58, v58, v58 row_ror:8 row_mask:0xf bank_mask:0xf bound_ctrl:1
	v_permlane16_swap_b32_e32 v59, v60
	v_add_f32_dpp v50, v50, v50 row_ror:4 row_mask:0xf bank_mask:0xf bound_ctrl:1
	v_mov_b32_e32 v52, v51
	v_add_f32_dpp v33, v26, v26 row_ror:8 row_mask:0xf bank_mask:0xf bound_ctrl:1
	v_mov_b32_e32 v54, v31
	v_pk_fma_f32 v[26:27], v[38:39], v[156:157], v[154:155] op_sel_hi:[1,0,0]
	v_mov_b32_e32 v61, v58
	v_add_f32_dpp v50, v50, v50 row_ror:8 row_mask:0xf bank_mask:0xf bound_ctrl:1
	v_permlane16_swap_b32_e32 v51, v52
	v_permlane16_swap_b32_e32 v31, v54
	v_pk_fma_f32 v[28:29], v[40:41], v[156:157], v[154:155] op_sel_hi:[1,0,0]
	v_pk_fma_f32 v[26:27], v[42:43], v[158:159], v[26:27] op_sel_hi:[1,0,1]
	v_max3_f32 v30, v155, v83, v59
	v_permlane16_swap_b32_e32 v85, v87
	v_permlane16_swap_b32_e32 v58, v61
	v_mov_b32_e32 v53, v50
	v_mov_b32_e32 v55, v33
	v_pk_fma_f32 v[28:29], v[44:45], v[158:159], v[28:29] op_sel_hi:[1,0,1]
	v_pk_fma_f32 v[26:27], v[46:47], v[174:175], v[26:27] op_sel_hi:[1,0,1]
	v_max3_f32 v32, v157, v86, v60
	v_max3_f32 v47, v30, v51, v31
	v_permlane16_swap_b32_e32 v50, v53
	v_permlane16_swap_b32_e32 v33, v55
	v_pk_fma_f32 v[28:29], v[48:49], v[174:175], v[28:29] op_sel_hi:[1,0,1]
	v_max3_f32 v38, v159, v85, v58
	v_max3_f32 v49, v32, v52, v54
	v_pk_fma_f32 v[34:35], v[34:35], v[208:209], v[26:27] op_sel_hi:[1,0,1]
	v_sub_f32_e32 v26, v155, v47
	v_max3_f32 v39, v165, v87, v61
	v_max3_f32 v223, v38, v50, v33
	v_exp_f32_e32 v82, v26
	v_sub_f32_e32 v26, v157, v49
	v_max3_f32 v39, v39, v53, v55
	v_exp_f32_e32 v38, v26
	v_sub_f32_e32 v26, v159, v223
	v_exp_f32_e32 v84, v26
	v_sub_f32_e32 v26, v165, v39
	v_exp_f32_e32 v40, v26
	v_sub_f32_e32 v26, v83, v47
	v_exp_f32_e32 v26, v26
	v_pk_fma_f32 v[36:37], v[36:37], v[208:209], v[28:29] op_sel_hi:[1,0,1]
	v_sub_f32_e32 v28, v87, v39
	v_exp_f32_e32 v28, v28
	v_sub_f32_e32 v27, v86, v49
	v_mov_b32_e32 v29, v26
	v_exp_f32_e32 v30, v27
	v_sub_f32_e32 v27, v85, v223
	v_fmac_f32_e32 v29, v167, v82
	v_exp_f32_e32 v32, v27
	v_fma_f32 v27, v173, v40, v28
	v_pk_mul_f32 v[224:225], v[68:69], v[28:29] op_sel_hi:[1,0]
	v_pk_mul_f32 v[226:227], v[66:67], v[28:29] op_sel_hi:[1,0]
	v_sub_f32_e32 v28, v59, v47
	v_exp_f32_e32 v210, v28
	v_sub_f32_e32 v28, v60, v49
	v_exp_f32_e32 v46, v28
	v_sub_f32_e32 v28, v58, v223
	v_exp_f32_e32 v212, v28
	v_pk_mul_f32 v[86:87], v[72:73], v[26:27] op_sel_hi:[1,0]
	v_pk_mul_f32 v[88:89], v[70:71], v[26:27] op_sel_hi:[1,0]
	v_mov_b32_e32 v26, v30
	v_pk_mul_f32 v[42:43], v[72:73], v[30:31] op_sel_hi:[1,0]
	v_pk_mul_f32 v[44:45], v[70:71], v[30:31] op_sel_hi:[1,0]
	v_mov_b32_e32 v30, v32
	v_fmac_f32_e32 v30, v171, v84
	v_sub_f32_e32 v28, v61, v39
	v_exp_f32_e32 v228, v28
	v_add_f32_e32 v28, v210, v29
	v_add_f32_e32 v29, v212, v30
	v_sub_f32_e32 v30, v51, v47
	v_exp_f32_e32 v230, v30
	v_sub_f32_e32 v30, v52, v49
	v_exp_f32_e32 v48, v30
	v_sub_f32_e32 v30, v50, v223
	v_exp_f32_e32 v232, v30
	v_sub_f32_e32 v30, v53, v39
	v_exp_f32_e32 v234, v30
	v_sub_f32_e32 v30, v31, v47
	v_exp_f32_e32 v236, v30
	v_sub_f32_e32 v30, v54, v49
	v_exp_f32_e32 v238, v30
	v_sub_f32_e32 v30, v33, v223
	v_exp_f32_e32 v240, v30
	v_sub_f32_e32 v30, v55, v39
	v_exp_f32_e32 v242, v30
	v_fmac_f32_e32 v26, v169, v38
	v_add_f32_e32 v26, v46, v26
	v_add_f32_e32 v27, v228, v27
	v_add_f32_e32 v28, v230, v28
	v_add_f32_e32 v26, v48, v26
	v_add_f32_e32 v29, v232, v29
	v_add_f32_e32 v27, v234, v27
	v_add_f32_e32 v83, v236, v28
	v_add_f32_e32 v85, v238, v26
	v_add_f32_e32 v229, v240, v29
	v_add_f32_e32 v231, v242, v27
	v_pk_mul_f32 v[206:207], v[68:69], v[32:33] op_sel_hi:[1,0]
	v_pk_mul_f32 v[208:209], v[66:67], v[32:33] op_sel_hi:[1,0]
	s_add_u32 s60, s58, s22
	s_addc_u32 s61, s59, s23
	global_load_dwordx4 v[118:121], v216, s[60:61] nt
	global_load_dwordx4 v[114:117], v216, s[60:61] offset:1024 nt
	s_add_u32 s60, s56, s22
	s_addc_u32 s61, s57, s23
	global_load_dwordx4 v[30:33], v216, s[60:61] nt
	global_load_dwordx4 v[26:29], v216, s[60:61] offset:1024 nt
	s_add_u32 s60, s58, s24
	s_addc_u32 s61, s59, s25
	global_load_dwordx4 v[70:73], v216, s[60:61] nt
	global_load_dwordx4 v[66:69], v216, s[60:61] offset:1024 nt
	s_add_u32 s60, s56, s24
	s_addc_u32 s61, s57, s25
	global_load_dwordx4 v[174:177], v216, s[60:61] nt
	global_load_dwordx4 v[166:169], v216, s[60:61] offset:1024 nt
	s_add_u32 s60, s58, s28
	s_addc_u32 s61, s59, s29
	global_load_dwordx4 v[62:65], v216, s[60:61] nt
	global_load_dwordx4 v[58:61], v216, s[60:61] offset:1024 nt
	s_add_u32 s60, s56, s28
	s_addc_u32 s61, s57, s29
	s_add_u32 s58, s58, s30
	s_addc_u32 s59, s59, s31
	s_add_u32 s56, s56, s30
	s_addc_u32 s57, s57, s31
	global_load_dwordx4 v[170:173], v216, s[60:61] nt
	global_load_dwordx4 v[158:161], v216, s[60:61] offset:1024 nt
	global_load_dwordx4 v[54:57], v216, s[58:59] nt
	global_load_dwordx4 v[50:53], v216, s[58:59] offset:1024 nt
	global_load_dwordx4 v[162:165], v216, s[56:57] nt
	global_load_dwordx4 v[154:157], v216, s[56:57] offset:1024 nt
	v_pk_fma_f32 v[80:81], v[80:81], v[82:83], v[88:89] op_sel_hi:[1,0,1]
	v_pk_fma_f32 v[78:79], v[78:79], v[82:83], v[86:87] op_sel_hi:[1,0,1]
	v_pk_fma_f32 v[74:75], v[74:75], v[84:85], v[208:209] op_sel_hi:[1,0,1]
	v_pk_fma_f32 v[76:77], v[76:77], v[84:85], v[206:207] op_sel_hi:[1,0,1]
	v_pk_fma_f32 v[78:79], v[12:13], v[210:211], v[78:79] op_sel_hi:[1,0,1]
	v_pk_fma_f32 v[80:81], v[10:11], v[210:211], v[80:81] op_sel_hi:[1,0,1]
	v_pk_fma_f32 v[76:77], v[20:21], v[212:213], v[76:77] op_sel_hi:[1,0,1]
	v_pk_fma_f32 v[74:75], v[18:19], v[212:213], v[74:75] op_sel_hi:[1,0,1]
	v_pk_fma_f32 v[80:81], v[14:15], v[230:231], v[80:81] op_sel_hi:[1,0,1]
	v_pk_fma_f32 v[78:79], v[16:17], v[230:231], v[78:79] op_sel_hi:[1,0,1]
	v_pk_fma_f32 v[74:75], v[22:23], v[232:233], v[74:75] op_sel_hi:[1,0,1]
	v_pk_fma_f32 v[76:77], v[24:25], v[232:233], v[76:77] op_sel_hi:[1,0,1]
	s_waitcnt vmcnt(36)
	v_pk_fma_f32 v[206:207], v[4:5], v[236:237], v[78:79] op_sel_hi:[1,0,1]
	v_pk_fma_f32 v[208:209], v[2:3], v[236:237], v[80:81] op_sel_hi:[1,0,1]
	s_waitcnt vmcnt(35)
	v_pk_fma_f32 v[210:211], v[8:9], v[240:241], v[76:77] op_sel_hi:[1,0,1]
	v_pk_fma_f32 v[212:213], v[6:7], v[240:241], v[74:75] op_sel_hi:[1,0,1]
	s_waitcnt vmcnt(31)
	v_mul_f32_e32 v41, v222, v183
	v_fmac_f32_e32 v41, v221, v182
	v_pk_mul_f32 v[74:75], v[184:185], v[200:201]
	s_waitcnt vmcnt(30)
	v_mul_f32_e32 v76, v220, v179
	v_add_f32_e32 v41, v74, v41
	v_add_f32_e32 v41, v75, v41
	v_fmac_f32_e32 v76, v219, v178
	v_pk_mul_f32 v[74:75], v[180:181], v[198:199]
	v_add_f32_dpp v41, v41, v41 quad_perm:[1,0,3,2] row_mask:0xf bank_mask:0xf bound_ctrl:1
	v_add_f32_e32 v74, v74, v76
	v_add_f32_e32 v74, v75, v74
	v_add_f32_dpp v41, v41, v41 quad_perm:[2,3,0,1] row_mask:0xf bank_mask:0xf bound_ctrl:1
	s_waitcnt vmcnt(26)
	v_mul_f32_e32 v80, v220, v123
	v_fmac_f32_e32 v80, v219, v122
	v_add_f32_dpp v41, v41, v41 row_ror:4 row_mask:0xf bank_mask:0xf bound_ctrl:1
	s_waitcnt vmcnt(22)
	v_mul_f32_e32 v86, v220, v107
	v_fmac_f32_e32 v86, v219, v106
	v_add_f32_dpp v76, v41, v41 row_ror:8 row_mask:0xf bank_mask:0xf bound_ctrl:1
	v_add_f32_dpp v41, v74, v74 quad_perm:[1,0,3,2] row_mask:0xf bank_mask:0xf bound_ctrl:1
	v_pk_mul_f32 v[74:75], v[128:129], v[200:201]
	s_waitcnt vmcnt(18)
	v_mul_f32_e32 v99, v220, v99
	v_add_f32_dpp v41, v41, v41 quad_perm:[2,3,0,1] row_mask:0xf bank_mask:0xf bound_ctrl:1
	v_fmac_f32_e32 v99, v219, v98
	v_mov_b32_e32 v78, v76
	v_add_f32_dpp v41, v41, v41 row_ror:4 row_mask:0xf bank_mask:0xf bound_ctrl:1
	s_nop 0
	v_permlane16_swap_b32_e32 v76, v78
	v_add_f32_dpp v77, v41, v41 row_ror:8 row_mask:0xf bank_mask:0xf bound_ctrl:1
	v_mul_f32_e32 v41, v222, v127
	v_fmac_f32_e32 v41, v221, v126
	v_add_f32_e32 v41, v74, v41
	v_add_f32_e32 v41, v75, v41
	v_pk_mul_f32 v[74:75], v[124:125], v[198:199]
	v_mov_b32_e32 v79, v77
	v_add_f32_dpp v41, v41, v41 quad_perm:[1,0,3,2] row_mask:0xf bank_mask:0xf bound_ctrl:1
	v_add_f32_e32 v74, v74, v80
	v_add_f32_e32 v74, v75, v74
	v_add_f32_dpp v41, v41, v41 quad_perm:[2,3,0,1] row_mask:0xf bank_mask:0xf bound_ctrl:1
	v_permlane16_swap_b32_e32 v77, v79
	s_nop 0
	v_add_f32_dpp v41, v41, v41 row_ror:4 row_mask:0xf bank_mask:0xf bound_ctrl:1
	s_nop 1
	v_add_f32_dpp v80, v41, v41 row_ror:8 row_mask:0xf bank_mask:0xf bound_ctrl:1
	v_add_f32_dpp v41, v74, v74 quad_perm:[1,0,3,2] row_mask:0xf bank_mask:0xf bound_ctrl:1
	v_pk_mul_f32 v[74:75], v[112:113], v[200:201]
	v_mov_b32_e32 v82, v80
	v_add_f32_dpp v41, v41, v41 quad_perm:[2,3,0,1] row_mask:0xf bank_mask:0xf bound_ctrl:1
	s_nop 0
	v_permlane16_swap_b32_e32 v80, v82
	v_add_f32_dpp v41, v41, v41 row_ror:4 row_mask:0xf bank_mask:0xf bound_ctrl:1
	s_nop 1
	v_add_f32_dpp v81, v41, v41 row_ror:8 row_mask:0xf bank_mask:0xf bound_ctrl:1
	v_mul_f32_e32 v41, v222, v111
	v_fmac_f32_e32 v41, v221, v110
	v_add_f32_e32 v41, v74, v41
	v_add_f32_e32 v41, v75, v41
	v_pk_mul_f32 v[74:75], v[108:109], v[198:199]
	v_mov_b32_e32 v84, v81
	v_add_f32_dpp v41, v41, v41 quad_perm:[1,0,3,2] row_mask:0xf bank_mask:0xf bound_ctrl:1
	v_add_f32_e32 v74, v74, v86
	v_add_f32_e32 v74, v75, v74
	v_add_f32_dpp v41, v41, v41 quad_perm:[2,3,0,1] row_mask:0xf bank_mask:0xf bound_ctrl:1
	v_permlane16_swap_b32_e32 v81, v84
	s_nop 0
	v_add_f32_dpp v41, v41, v41 row_ror:4 row_mask:0xf bank_mask:0xf bound_ctrl:1
	s_nop 1
	v_add_f32_dpp v86, v41, v41 row_ror:8 row_mask:0xf bank_mask:0xf bound_ctrl:1
	v_add_f32_dpp v41, v74, v74 quad_perm:[1,0,3,2] row_mask:0xf bank_mask:0xf bound_ctrl:1
	v_pk_mul_f32 v[74:75], v[104:105], v[200:201]
	v_mov_b32_e32 v88, v86
	v_add_f32_dpp v41, v41, v41 quad_perm:[2,3,0,1] row_mask:0xf bank_mask:0xf bound_ctrl:1
	s_nop 0
	v_permlane16_swap_b32_e32 v86, v88
	v_add_f32_dpp v41, v41, v41 row_ror:4 row_mask:0xf bank_mask:0xf bound_ctrl:1
	s_nop 1
	v_add_f32_dpp v87, v41, v41 row_ror:8 row_mask:0xf bank_mask:0xf bound_ctrl:1
	v_mul_f32_e32 v41, v222, v103
	v_fmac_f32_e32 v41, v221, v102
	v_add_f32_e32 v41, v74, v41
	v_add_f32_e32 v41, v75, v41
	v_pk_mul_f32 v[74:75], v[100:101], v[198:199]
	v_mov_b32_e32 v89, v87
	v_add_f32_dpp v41, v41, v41 quad_perm:[1,0,3,2] row_mask:0xf bank_mask:0xf bound_ctrl:1
	v_add_f32_e32 v74, v74, v99
	v_add_f32_e32 v74, v75, v74
	v_add_f32_dpp v41, v41, v41 quad_perm:[2,3,0,1] row_mask:0xf bank_mask:0xf bound_ctrl:1
	v_permlane16_swap_b32_e32 v87, v89
	s_nop 0
	v_add_f32_dpp v41, v41, v41 row_ror:4 row_mask:0xf bank_mask:0xf bound_ctrl:1
	s_nop 1
	v_add_f32_dpp v98, v41, v41 row_ror:8 row_mask:0xf bank_mask:0xf bound_ctrl:1
	v_add_f32_dpp v41, v74, v74 quad_perm:[1,0,3,2] row_mask:0xf bank_mask:0xf bound_ctrl:1
	v_mov_b32_e32 v100, v98
	s_nop 1
	v_permlane16_swap_b32_e32 v98, v100
	v_add_f32_dpp v41, v41, v41 quad_perm:[2,3,0,1] row_mask:0xf bank_mask:0xf bound_ctrl:1
	s_nop 1
	v_add_f32_dpp v41, v41, v41 row_ror:4 row_mask:0xf bank_mask:0xf bound_ctrl:1
	v_pk_fma_f32 v[74:75], v[204:205], v[40:41], v[226:227] op_sel_hi:[1,0,1]
	s_nop 0
	v_pk_fma_f32 v[18:19], v[18:19], v[228:229], v[74:75] op_sel_hi:[1,0,1]
	v_add_f32_dpp v99, v41, v41 row_ror:8 row_mask:0xf bank_mask:0xf bound_ctrl:1
	v_pk_fma_f32 v[40:41], v[202:203], v[40:41], v[224:225] op_sel_hi:[1,0,1]
	v_pk_fma_f32 v[18:19], v[22:23], v[234:235], v[18:19] op_sel_hi:[1,0,1]
	v_pk_fma_f32 v[20:21], v[20:21], v[228:229], v[40:41] op_sel_hi:[1,0,1]
	v_pk_fma_f32 v[6:7], v[6:7], v[242:243], v[18:19] op_sel_hi:[1,0,1]
	v_max3_f32 v18, v47, v76, v80
	v_max3_f32 v19, v49, v78, v82
	v_mov_b32_e32 v101, v99
	v_pk_fma_f32 v[20:21], v[24:25], v[234:235], v[20:21] op_sel_hi:[1,0,1]
	v_max3_f32 v225, v18, v86, v98
	v_max3_f32 v227, v19, v88, v100
	v_pk_fma_f32 v[18:19], v[34:35], v[38:39], v[44:45] op_sel_hi:[1,0,1]
	v_permlane16_swap_b32_e32 v99, v101
	v_pk_fma_f32 v[8:9], v[8:9], v[242:243], v[20:21] op_sel_hi:[1,0,1]
	v_max3_f32 v20, v223, v77, v81
	v_max3_f32 v21, v39, v79, v84
	v_pk_fma_f32 v[10:11], v[10:11], v[46:47], v[18:19] op_sel_hi:[1,0,1]
	v_max3_f32 v233, v20, v87, v99
	v_max3_f32 v235, v21, v89, v101
	v_pk_fma_f32 v[20:21], v[36:37], v[38:39], v[42:43] op_sel_hi:[1,0,1]
	v_pk_fma_f32 v[10:11], v[14:15], v[48:49], v[10:11] op_sel_hi:[1,0,1]
	v_pk_fma_f32 v[12:13], v[12:13], v[46:47], v[20:21] op_sel_hi:[1,0,1]
	v_pk_fma_f32 v[2:3], v[2:3], v[238:239], v[10:11] op_sel_hi:[1,0,1]
	v_sub_f32_e32 v11, v223, v233
	v_pk_fma_f32 v[12:13], v[16:17], v[48:49], v[12:13] op_sel_hi:[1,0,1]
	v_exp_f32_e32 v24, v11
	v_sub_f32_e32 v11, v39, v235
	v_pk_fma_f32 v[4:5], v[4:5], v[238:239], v[12:13] op_sel_hi:[1,0,1]
	v_exp_f32_e32 v12, v11
	v_sub_f32_e32 v11, v76, v225
	v_exp_f32_e32 v14, v11
	v_sub_f32_e32 v11, v78, v227
	v_exp_f32_e32 v16, v11
	v_sub_f32_e32 v11, v77, v233
	v_sub_f32_e32 v10, v47, v225
	v_exp_f32_e32 v20, v11
	v_exp_f32_e32 v22, v10
	v_sub_f32_e32 v10, v49, v227
	v_exp_f32_e32 v10, v10
	v_sub_f32_e32 v13, v79, v235
	v_exp_f32_e32 v18, v13
	v_mov_b32_e32 v21, v20
	v_mov_b32_e32 v19, v16
	v_fmac_f32_e32 v21, v229, v24
	v_sub_f32_e32 v23, v87, v233
	v_fmac_f32_e32 v19, v85, v10
	v_pk_mul_f32 v[182:183], v[92:93], v[20:21] op_sel_hi:[1,0]
	v_pk_mul_f32 v[184:185], v[90:91], v[20:21] op_sel_hi:[1,0]
	v_sub_f32_e32 v20, v81, v233
	v_exp_f32_e32 v232, v23
	v_sub_f32_e32 v23, v89, v235
	v_fma_f32 v11, v231, v12, v18
	v_pk_mul_f32 v[202:203], v[92:93], v[18:19] op_sel_hi:[1,0]
	v_pk_mul_f32 v[204:205], v[90:91], v[18:19] op_sel_hi:[1,0]
	v_sub_f32_e32 v18, v80, v225
	v_exp_f32_e32 v226, v20
	v_sub_f32_e32 v20, v84, v235
	v_exp_f32_e32 v234, v23
	v_sub_f32_e32 v23, v98, v225
	v_exp_f32_e32 v224, v18
	v_sub_f32_e32 v18, v82, v227
	v_exp_f32_e32 v228, v20
	v_sub_f32_e32 v20, v86, v225
	v_exp_f32_e32 v236, v23
	v_sub_f32_e32 v23, v100, v227
	v_exp_f32_e32 v18, v18
	v_exp_f32_e32 v230, v20
	v_sub_f32_e32 v20, v88, v227
	v_exp_f32_e32 v238, v23
	v_sub_f32_e32 v23, v99, v233
	v_exp_f32_e32 v20, v20
	v_exp_f32_e32 v240, v23
	v_sub_f32_e32 v23, v101, v235
	v_mov_b32_e32 v13, v14
	v_exp_f32_e32 v242, v23
	v_fmac_f32_e32 v13, v83, v22
	v_add_f32_e32 v13, v224, v13
	v_add_f32_e32 v19, v18, v19
	v_add_f32_e32 v21, v226, v21
	v_add_f32_e32 v11, v228, v11
	v_add_f32_e32 v13, v230, v13
	v_add_f32_e32 v19, v20, v19
	v_add_f32_e32 v21, v232, v21
	v_add_f32_e32 v11, v234, v11
	v_pk_mul_f32 v[178:179], v[96:97], v[14:15] op_sel_hi:[1,0]
	v_pk_mul_f32 v[180:181], v[94:95], v[14:15] op_sel_hi:[1,0]
	v_pk_mul_f32 v[14:15], v[96:97], v[16:17] op_sel_hi:[1,0]
	v_pk_mul_f32 v[16:17], v[94:95], v[16:17] op_sel_hi:[1,0]
	v_add_f32_e32 v13, v236, v13
	v_add_f32_e32 v19, v238, v19
	v_add_f32_e32 v21, v240, v21
	v_add_f32_e32 v11, v242, v11
	s_add_u32 s56, s0, s36
	s_addc_u32 s57, s1, s37
	global_load_dwordx4 v[126:129], v216, s[56:57] nt
	global_load_dwordx4 v[122:125], v216, s[56:57] offset:1024 nt
	s_add_u32 s56, s10, s36
	s_addc_u32 s57, s11, s37
	global_load_dwordx4 v[38:41], v216, s[56:57] nt
	global_load_dwordx4 v[86:89], v216, s[56:57] offset:1024 nt
	s_add_u32 s56, s0, s38
	s_addc_u32 s57, s1, s39
	global_load_dwordx4 v[110:113], v216, s[56:57] nt
	global_load_dwordx4 v[106:109], v216, s[56:57] offset:1024 nt
	s_add_u32 s56, s10, s38
	s_addc_u32 s57, s11, s39
	global_load_dwordx4 v[42:45], v216, s[56:57] nt
	global_load_dwordx4 v[82:85], v216, s[56:57] offset:1024 nt
	s_add_u32 s56, s0, s40
	s_addc_u32 s57, s1, s41
	global_load_dwordx4 v[102:105], v216, s[56:57] nt
	global_load_dwordx4 v[98:101], v216, s[56:57] offset:1024 nt
	s_add_u32 s56, s10, s40
	s_addc_u32 s57, s11, s41
	global_load_dwordx4 v[46:49], v216, s[56:57] nt
	global_load_dwordx4 v[78:81], v216, s[56:57] offset:1024 nt
	s_add_u32 s56, s0, s42
	s_addc_u32 s57, s1, s43
	global_load_dwordx4 v[94:97], v216, s[56:57] nt
	global_load_dwordx4 v[90:93], v216, s[56:57] offset:1024 nt
	s_add_u32 s56, s10, s42
	s_addc_u32 s57, s11, s43
	global_load_dwordx4 v[34:37], v216, s[56:57] nt
	global_load_dwordx4 v[74:77], v216, s[56:57] offset:1024 nt
	v_pk_fma_f32 v[180:181], v[208:209], v[22:23], v[180:181] op_sel_hi:[1,0,1]
	v_pk_fma_f32 v[22:23], v[206:207], v[22:23], v[178:179] op_sel_hi:[1,0,1]
	v_pk_fma_f32 v[178:179], v[212:213], v[24:25], v[184:185] op_sel_hi:[1,0,1]
	v_pk_fma_f32 v[24:25], v[210:211], v[24:25], v[182:183] op_sel_hi:[1,0,1]
	v_pk_fma_f32 v[22:23], v[132:133], v[224:225], v[22:23] op_sel_hi:[1,0,1]
	v_pk_fma_f32 v[180:181], v[130:131], v[224:225], v[180:181] op_sel_hi:[1,0,1]
	v_pk_fma_f32 v[24:25], v[144:145], v[226:227], v[24:25] op_sel_hi:[1,0,1]
	v_pk_fma_f32 v[178:179], v[142:143], v[226:227], v[178:179] op_sel_hi:[1,0,1]
	v_pk_fma_f32 v[182:183], v[134:135], v[230:231], v[180:181] op_sel_hi:[1,0,1]
	v_pk_fma_f32 v[22:23], v[136:137], v[230:231], v[22:23] op_sel_hi:[1,0,1]
	v_pk_fma_f32 v[206:207], v[146:147], v[232:233], v[178:179] op_sel_hi:[1,0,1]
	v_pk_fma_f32 v[24:25], v[148:149], v[232:233], v[24:25] op_sel_hi:[1,0,1]
	s_waitcnt vmcnt(33)
	v_pk_fma_f32 v[180:181], v[140:141], v[236:237], v[22:23] op_sel_hi:[1,0,1]
	v_pk_fma_f32 v[184:185], v[138:139], v[236:237], v[182:183] op_sel_hi:[1,0,1]
	s_waitcnt vmcnt(32)
	v_pk_fma_f32 v[178:179], v[152:153], v[240:241], v[24:25] op_sel_hi:[1,0,1]
	v_pk_fma_f32 v[182:183], v[150:151], v[240:241], v[206:207] op_sel_hi:[1,0,1]
	s_waitcnt vmcnt(31)
	v_mul_f32_e32 v24, v222, v119
	v_fmac_f32_e32 v24, v221, v118
	v_pk_mul_f32 v[22:23], v[120:121], v[200:201]
	s_waitcnt vmcnt(30)
	v_mul_f32_e32 v25, v220, v115
	v_add_f32_e32 v22, v22, v24
	v_add_f32_e32 v24, v23, v22
	v_fmac_f32_e32 v25, v219, v114
	v_pk_mul_f32 v[22:23], v[116:117], v[198:199]
	s_waitcnt vmcnt(27)
	v_mul_f32_e32 v71, v222, v71
	v_add_f32_e32 v22, v22, v25
	v_add_f32_e32 v22, v23, v22
	v_add_f32_dpp v23, v24, v24 quad_perm:[1,0,3,2] row_mask:0xf bank_mask:0xf bound_ctrl:1
	v_fmac_f32_e32 v71, v221, v70
	v_add_f32_dpp v22, v22, v22 quad_perm:[1,0,3,2] row_mask:0xf bank_mask:0xf bound_ctrl:1
	v_add_f32_dpp v23, v23, v23 quad_perm:[2,3,0,1] row_mask:0xf bank_mask:0xf bound_ctrl:1
	s_waitcnt vmcnt(26)
	v_mul_f32_e32 v67, v220, v67
	v_add_f32_dpp v22, v22, v22 quad_perm:[2,3,0,1] row_mask:0xf bank_mask:0xf bound_ctrl:1
	v_add_f32_dpp v23, v23, v23 row_ror:4 row_mask:0xf bank_mask:0xf bound_ctrl:1
	v_fmac_f32_e32 v67, v219, v66
	v_add_f32_dpp v22, v22, v22 row_ror:4 row_mask:0xf bank_mask:0xf bound_ctrl:1
	v_add_f32_dpp v24, v23, v23 row_ror:8 row_mask:0xf bank_mask:0xf bound_ctrl:1
	s_waitcnt vmcnt(23)
	v_mul_f32_e32 v63, v222, v63
	v_add_f32_dpp v25, v22, v22 row_ror:8 row_mask:0xf bank_mask:0xf bound_ctrl:1
	v_pk_mul_f32 v[22:23], v[72:73], v[200:201]
	v_fmac_f32_e32 v63, v221, v62
	v_add_f32_e32 v22, v22, v71
	v_add_f32_e32 v70, v23, v22
	v_pk_mul_f32 v[22:23], v[68:69], v[198:199]
	s_waitcnt vmcnt(22)
	v_mul_f32_e32 v59, v220, v59
	v_add_f32_e32 v22, v22, v67
	v_add_f32_e32 v22, v23, v22
	v_add_f32_dpp v23, v70, v70 quad_perm:[1,0,3,2] row_mask:0xf bank_mask:0xf bound_ctrl:1
	v_fmac_f32_e32 v59, v219, v58
	v_add_f32_dpp v22, v22, v22 quad_perm:[1,0,3,2] row_mask:0xf bank_mask:0xf bound_ctrl:1
	v_add_f32_dpp v23, v23, v23 quad_perm:[2,3,0,1] row_mask:0xf bank_mask:0xf bound_ctrl:1
	s_waitcnt vmcnt(19)
	v_mul_f32_e32 v55, v222, v55
	v_add_f32_dpp v22, v22, v22 quad_perm:[2,3,0,1] row_mask:0xf bank_mask:0xf bound_ctrl:1
	v_add_f32_dpp v23, v23, v23 row_ror:4 row_mask:0xf bank_mask:0xf bound_ctrl:1
	v_fmac_f32_e32 v55, v221, v54
	v_add_f32_dpp v22, v22, v22 row_ror:4 row_mask:0xf bank_mask:0xf bound_ctrl:1
	v_add_f32_dpp v66, v23, v23 row_ror:8 row_mask:0xf bank_mask:0xf bound_ctrl:1
	s_waitcnt vmcnt(18)
	v_mul_f32_e32 v51, v220, v51
	v_add_f32_dpp v67, v22, v22 row_ror:8 row_mask:0xf bank_mask:0xf bound_ctrl:1
	v_pk_mul_f32 v[22:23], v[64:65], v[200:201]
	v_fmac_f32_e32 v51, v219, v50
	v_add_f32_e32 v22, v22, v63
	v_add_f32_e32 v62, v23, v22
	v_pk_mul_f32 v[22:23], v[60:61], v[198:199]
	v_pk_fma_f32 v[6:7], v[6:7], v[12:13], v[204:205] op_sel_hi:[1,0,1]
	v_add_f32_e32 v22, v22, v59
	v_add_f32_e32 v22, v23, v22
	v_add_f32_dpp v23, v62, v62 quad_perm:[1,0,3,2] row_mask:0xf bank_mask:0xf bound_ctrl:1
	v_mov_b32_e32 v114, v24
	v_add_f32_dpp v22, v22, v22 quad_perm:[1,0,3,2] row_mask:0xf bank_mask:0xf bound_ctrl:1
	v_add_f32_dpp v23, v23, v23 quad_perm:[2,3,0,1] row_mask:0xf bank_mask:0xf bound_ctrl:1
	v_mov_b32_e32 v68, v66
	v_add_f32_dpp v22, v22, v22 quad_perm:[2,3,0,1] row_mask:0xf bank_mask:0xf bound_ctrl:1
	v_add_f32_dpp v23, v23, v23 row_ror:4 row_mask:0xf bank_mask:0xf bound_ctrl:1
	v_pk_fma_f32 v[8:9], v[8:9], v[12:13], v[202:203] op_sel_hi:[1,0,1]
	v_add_f32_dpp v22, v22, v22 row_ror:4 row_mask:0xf bank_mask:0xf bound_ctrl:1
	v_add_f32_dpp v58, v23, v23 row_ror:8 row_mask:0xf bank_mask:0xf bound_ctrl:1
	v_pk_fma_f32 v[6:7], v[142:143], v[228:229], v[6:7] op_sel_hi:[1,0,1]
	v_add_f32_dpp v59, v22, v22 row_ror:8 row_mask:0xf bank_mask:0xf bound_ctrl:1
	v_pk_mul_f32 v[22:23], v[56:57], v[200:201]
	v_permlane16_swap_b32_e32 v24, v114
	v_add_f32_e32 v22, v22, v55
	v_add_f32_e32 v54, v23, v22
	v_pk_mul_f32 v[22:23], v[52:53], v[198:199]
	v_permlane16_swap_b32_e32 v66, v68
	v_add_f32_e32 v22, v22, v51
	v_add_f32_e32 v22, v23, v22
	v_add_f32_dpp v23, v54, v54 quad_perm:[1,0,3,2] row_mask:0xf bank_mask:0xf bound_ctrl:1
	v_mov_b32_e32 v60, v58
	v_add_f32_dpp v22, v22, v22 quad_perm:[1,0,3,2] row_mask:0xf bank_mask:0xf bound_ctrl:1
	v_add_f32_dpp v23, v23, v23 quad_perm:[2,3,0,1] row_mask:0xf bank_mask:0xf bound_ctrl:1
	v_pk_fma_f32 v[8:9], v[144:145], v[228:229], v[8:9] op_sel_hi:[1,0,1]
	v_add_f32_dpp v22, v22, v22 quad_perm:[2,3,0,1] row_mask:0xf bank_mask:0xf bound_ctrl:1
	v_add_f32_dpp v23, v23, v23 row_ror:4 row_mask:0xf bank_mask:0xf bound_ctrl:1
	v_pk_fma_f32 v[6:7], v[146:147], v[234:235], v[6:7] op_sel_hi:[1,0,1]
	v_add_f32_dpp v22, v22, v22 row_ror:4 row_mask:0xf bank_mask:0xf bound_ctrl:1
	v_add_f32_dpp v23, v23, v23 row_ror:8 row_mask:0xf bank_mask:0xf bound_ctrl:1
	v_mov_b32_e32 v50, v23
	v_pk_fma_f32 v[2:3], v[2:3], v[10:11], v[16:17] op_sel_hi:[1,0,1]
	v_mov_b32_e32 v115, v25
	v_mov_b32_e32 v69, v67
	v_permlane16_swap_b32_e32 v58, v60
	v_add_f32_dpp v22, v22, v22 row_ror:8 row_mask:0xf bank_mask:0xf bound_ctrl:1
	v_permlane16_swap_b32_e32 v23, v50
	v_pk_fma_f32 v[8:9], v[148:149], v[234:235], v[8:9] op_sel_hi:[1,0,1]
	v_pk_fma_f32 v[148:149], v[150:151], v[242:243], v[6:7] op_sel_hi:[1,0,1]
	v_max3_f32 v6, v225, v24, v66
	v_pk_fma_f32 v[4:5], v[4:5], v[10:11], v[14:15] op_sel_hi:[1,0,1]
	v_pk_fma_f32 v[2:3], v[130:131], v[18:19], v[2:3] op_sel_hi:[1,0,1]
	v_permlane16_swap_b32_e32 v25, v115
	v_permlane16_swap_b32_e32 v67, v69
	v_mov_b32_e32 v61, v59
	v_mov_b32_e32 v51, v22
	v_max3_f32 v7, v227, v114, v68
	v_max3_f32 v142, v6, v58, v23
	v_pk_fma_f32 v[4:5], v[132:133], v[18:19], v[4:5] op_sel_hi:[1,0,1]
	v_pk_fma_f32 v[2:3], v[134:135], v[20:21], v[2:3] op_sel_hi:[1,0,1]
	v_permlane16_swap_b32_e32 v59, v61
	v_permlane16_swap_b32_e32 v22, v51
	v_pk_fma_f32 v[146:147], v[152:153], v[242:243], v[8:9] op_sel_hi:[1,0,1]
	v_max3_f32 v8, v233, v25, v67
	v_max3_f32 v144, v7, v60, v50
	v_pk_fma_f32 v[4:5], v[136:137], v[20:21], v[4:5] op_sel_hi:[1,0,1]
	v_pk_fma_f32 v[136:137], v[138:139], v[238:239], v[2:3] op_sel_hi:[1,0,1]
	v_sub_f32_e32 v2, v225, v142
	v_max3_f32 v9, v235, v115, v69
	v_max3_f32 v143, v8, v59, v22
	v_exp_f32_e32 v138, v2
	v_sub_f32_e32 v2, v227, v144
	v_max3_f32 v145, v9, v61, v51
	v_pk_fma_f32 v[134:135], v[140:141], v[238:239], v[4:5] op_sel_hi:[1,0,1]
	v_exp_f32_e32 v140, v2
	v_sub_f32_e32 v2, v233, v143
	v_exp_f32_e32 v150, v2
	v_sub_f32_e32 v2, v235, v145
	v_exp_f32_e32 v152, v2
	v_sub_f32_e32 v2, v24, v142
	v_exp_f32_e32 v2, v2
	v_sub_f32_e32 v4, v115, v145
	v_exp_f32_e32 v4, v4
	v_sub_f32_e32 v3, v114, v144
	v_mov_b32_e32 v5, v2
	v_exp_f32_e32 v6, v3
	v_sub_f32_e32 v3, v25, v143
	v_fmac_f32_e32 v5, v13, v138
	v_exp_f32_e32 v8, v3
	v_fma_f32 v3, v11, v152, v4
	v_pk_mul_f32 v[210:211], v[28:29], v[4:5] op_sel_hi:[1,0]
	v_pk_mul_f32 v[212:213], v[26:27], v[4:5] op_sel_hi:[1,0]
	v_sub_f32_e32 v4, v66, v142
	v_exp_f32_e32 v220, v4
	v_sub_f32_e32 v4, v68, v144
	v_exp_f32_e32 v222, v4
	v_sub_f32_e32 v4, v67, v143
	v_exp_f32_e32 v224, v4
	v_pk_mul_f32 v[198:199], v[32:33], v[2:3] op_sel_hi:[1,0]
	v_pk_mul_f32 v[200:201], v[30:31], v[2:3] op_sel_hi:[1,0]
	v_mov_b32_e32 v2, v6
	v_pk_mul_f32 v[202:203], v[32:33], v[6:7] op_sel_hi:[1,0]
	v_pk_mul_f32 v[204:205], v[30:31], v[6:7] op_sel_hi:[1,0]
	v_mov_b32_e32 v6, v8
	v_fmac_f32_e32 v6, v21, v150
	v_sub_f32_e32 v4, v69, v145
	v_exp_f32_e32 v226, v4
	v_add_f32_e32 v4, v220, v5
	v_add_f32_e32 v5, v224, v6
	v_sub_f32_e32 v6, v58, v142
	v_exp_f32_e32 v228, v6
	v_sub_f32_e32 v6, v60, v144
	v_exp_f32_e32 v230, v6
	v_sub_f32_e32 v6, v59, v143
	v_exp_f32_e32 v232, v6
	v_sub_f32_e32 v6, v61, v145
	v_exp_f32_e32 v234, v6
	v_sub_f32_e32 v6, v23, v142
	v_exp_f32_e32 v236, v6
	v_sub_f32_e32 v6, v50, v144
	v_exp_f32_e32 v238, v6
	v_sub_f32_e32 v6, v22, v143
	v_exp_f32_e32 v240, v6
	v_sub_f32_e32 v6, v51, v145
	v_exp_f32_e32 v242, v6
	v_fmac_f32_e32 v2, v19, v140
	v_add_f32_e32 v2, v222, v2
	v_add_f32_e32 v3, v226, v3
	v_add_f32_e32 v4, v228, v4
	v_add_f32_e32 v2, v230, v2
	v_add_f32_e32 v5, v232, v5
	v_add_f32_e32 v3, v234, v3
	v_add_f32_e32 v130, v236, v4
	v_add_f32_e32 v132, v238, v2
	v_add_f32_e32 v131, v240, v5
	v_add_f32_e32 v133, v242, v3
	v_pk_mul_f32 v[206:207], v[28:29], v[8:9] op_sel_hi:[1,0]
	v_pk_mul_f32 v[208:209], v[26:27], v[8:9] op_sel_hi:[1,0]
	s_add_u32 s56, s0, s44
	s_addc_u32 s57, s1, s45
	global_load_dwordx4 v[118:121], v216, s[56:57] nt
	global_load_dwordx4 v[114:117], v216, s[56:57] offset:1024 nt
	s_add_u32 s56, s10, s44
	s_addc_u32 s57, s11, s45
	global_load_dwordx4 v[70:73], v216, s[56:57] nt
	global_load_dwordx4 v[66:69], v216, s[56:57] offset:1024 nt
	s_add_u32 s56, s0, s46
	s_addc_u32 s57, s1, s47
	global_load_dwordx4 v[62:65], v216, s[56:57] nt
	global_load_dwordx4 v[58:61], v216, s[56:57] offset:1024 nt
	s_add_u32 s56, s10, s46
	s_addc_u32 s57, s11, s47
	global_load_dwordx4 v[10:13], v216, s[56:57] nt
	global_load_dwordx4 v[18:21], v216, s[56:57] offset:1024 nt
	s_add_u32 s56, s0, s48
	s_addc_u32 s57, s1, s49
	global_load_dwordx4 v[54:57], v216, s[56:57] nt
	global_load_dwordx4 v[50:53], v216, s[56:57] offset:1024 nt
	s_add_u32 s56, s10, s48
	s_addc_u32 s57, s11, s49
	global_load_dwordx4 v[14:17], v216, s[56:57] nt
	global_load_dwordx4 v[22:25], v216, s[56:57] offset:1024 nt
	s_add_u32 s56, s0, s50
	s_addc_u32 s57, s1, s51
	global_load_dwordx4 v[30:33], v216, s[56:57] nt
	global_load_dwordx4 v[26:29], v216, s[56:57] offset:1024 nt
	s_add_u32 s56, s10, s50
	s_addc_u32 s57, s11, s51
	global_load_dwordx4 v[2:5], v216, s[56:57] nt
	global_load_dwordx4 v[6:9], v216, s[56:57] offset:1024 nt
	v_pk_fma_f32 v[184:185], v[184:185], v[138:139], v[200:201] op_sel_hi:[1,0,1]
	v_pk_fma_f32 v[138:139], v[180:181], v[138:139], v[198:199] op_sel_hi:[1,0,1]
	v_pk_fma_f32 v[136:137], v[136:137], v[140:141], v[204:205] op_sel_hi:[1,0,1]
	v_pk_fma_f32 v[134:135], v[134:135], v[140:141], v[202:203] op_sel_hi:[1,0,1]
	v_pk_fma_f32 v[140:141], v[182:183], v[150:151], v[208:209] op_sel_hi:[1,0,1]
	v_pk_fma_f32 v[150:151], v[178:179], v[150:151], v[206:207] op_sel_hi:[1,0,1]
	v_pk_fma_f32 v[148:149], v[148:149], v[152:153], v[212:213] op_sel_hi:[1,0,1]
	v_pk_fma_f32 v[146:147], v[146:147], v[152:153], v[210:211] op_sel_hi:[1,0,1]
	v_pk_fma_f32 v[138:139], v[176:177], v[220:221], v[138:139] op_sel_hi:[1,0,1]
	v_pk_fma_f32 v[152:153], v[174:175], v[220:221], v[184:185] op_sel_hi:[1,0,1]
	v_pk_fma_f32 v[134:135], v[176:177], v[222:223], v[134:135] op_sel_hi:[1,0,1]
	v_pk_fma_f32 v[136:137], v[174:175], v[222:223], v[136:137] op_sel_hi:[1,0,1]
	v_pk_fma_f32 v[150:151], v[168:169], v[224:225], v[150:151] op_sel_hi:[1,0,1]
	v_pk_fma_f32 v[140:141], v[166:167], v[224:225], v[140:141] op_sel_hi:[1,0,1]
	v_pk_fma_f32 v[146:147], v[168:169], v[226:227], v[146:147] op_sel_hi:[1,0,1]
	v_pk_fma_f32 v[148:149], v[166:167], v[226:227], v[148:149] op_sel_hi:[1,0,1]
	v_pk_fma_f32 v[152:153], v[170:171], v[228:229], v[152:153] op_sel_hi:[1,0,1]
	v_pk_fma_f32 v[138:139], v[172:173], v[228:229], v[138:139] op_sel_hi:[1,0,1]
	v_pk_fma_f32 v[166:167], v[170:171], v[230:231], v[136:137] op_sel_hi:[1,0,1]
	v_pk_fma_f32 v[168:169], v[172:173], v[230:231], v[134:135] op_sel_hi:[1,0,1]
	v_pk_fma_f32 v[170:171], v[158:159], v[232:233], v[140:141] op_sel_hi:[1,0,1]
	v_pk_fma_f32 v[150:151], v[160:161], v[232:233], v[150:151] op_sel_hi:[1,0,1]
	v_pk_fma_f32 v[158:159], v[158:159], v[234:235], v[148:149] op_sel_hi:[1,0,1]
	v_pk_fma_f32 v[160:161], v[160:161], v[234:235], v[146:147] op_sel_hi:[1,0,1]
	s_waitcnt vmcnt(33)
	v_pk_fma_f32 v[136:137], v[164:165], v[236:237], v[138:139] op_sel_hi:[1,0,1]
	v_pk_fma_f32 v[134:135], v[162:163], v[236:237], v[152:153] op_sel_hi:[1,0,1]
	v_pk_fma_f32 v[140:141], v[164:165], v[238:239], v[168:169] op_sel_hi:[1,0,1]
	v_pk_fma_f32 v[138:139], v[162:163], v[238:239], v[166:167] op_sel_hi:[1,0,1]
	s_waitcnt vmcnt(32)
	v_pk_fma_f32 v[148:149], v[156:157], v[240:241], v[150:151] op_sel_hi:[1,0,1]
	v_pk_fma_f32 v[146:147], v[154:155], v[240:241], v[170:171] op_sel_hi:[1,0,1]
	v_pk_fma_f32 v[152:153], v[156:157], v[242:243], v[160:161] op_sel_hi:[1,0,1]
	v_pk_fma_f32 v[150:151], v[154:155], v[242:243], v[158:159] op_sel_hi:[1,0,1]
	ds_write_b128 v1, v[134:137]
	ds_write_b128 v1, v[146:149] offset:1024
	ds_write_b128 v1, v[138:141] offset:2048
	ds_write_b128 v1, v[150:153] offset:3072
	s_and_saveexec_b64 s[56:57], s[6:7]
	s_cbranch_execz .LBB0_630
	v_add_u32_e32 v134, 0x8000, v214
	ds_write2_b32 v134, v142, v144 offset1:1
	v_add_u32_e32 v134, 0x8010, v214
	ds_write2_b32 v134, v143, v145 offset1:1
	v_add_u32_e32 v134, 0x8100, v214
	ds_write2_b32 v134, v130, v132 offset1:1
	v_add_u32_e32 v130, 0x8110, v214
	ds_write2_b32 v130, v131, v133 offset1:1

.LBB0_882:
	v_readlane_b32 s0, v245, 2
	v_readlane_b32 s3, v245, 5
	s_bitcmp0_b32 s3, 5
	v_readlane_b32 s85, v245, 50
	v_readlane_b32 s92, v245, 43
	v_readlane_b32 s1, v245, 3
	v_readlane_b32 s2, v245, 4
	s_cbranch_scc1 .LBB0_893
	s_and_b32 s33, s95, -2
	s_ashr_i32 s1, s95, 31
	s_add_i32 s0, s33, s1
	s_xor_b32 s2, s0, s1
	v_cvt_f32_u32_e32 v1, s2
	v_readlane_b32 s0, v245, 54
	s_lshl_b32 s0, s0, 1
	s_sub_i32 s3, s33, s0
	v_rcp_iflag_f32_e32 v1, v1
	s_addk_i32 s3, 0x6ee
	s_ashr_i32 s4, s3, 31
	s_sub_i32 s5, 0, s2
	v_mul_f32_e32 v1, 0x4f7ffffe, v1
	v_cvt_u32_f32_e32 v1, v1
	s_xor_b32 s20, s4, s1
	s_abs_i32 s3, s3
	v_mov_b32_e32 v131, v0
	v_readfirstlane_b32 s1, v1
	s_mul_i32 s5, s5, s1
	s_mul_hi_u32 s4, s1, s5
	s_add_i32 s1, s1, s4
	s_mul_hi_u32 s1, s3, s1
	s_mul_i32 s4, s1, s2
	s_sub_i32 s3, s3, s4
	s_add_i32 s5, s1, 1
	s_sub_i32 s4, s3, s2
	s_cmp_ge_u32 s3, s2
	s_cselect_b32 s1, s5, s1
	s_cselect_b32 s3, s4, s3
	s_add_i32 s4, s1, 1
	s_cmp_ge_u32 s3, s2
	s_cselect_b32 s1, s4, s1
	s_xor_b32 s21, s1, s20
	s_sub_i32 s77, s21, s20
	s_cmp_lt_i32 s77, 1
	v_readfirstlane_b32 s1, v131
	s_cbranch_scc1 .LBB0_893
	s_add_u32 s10, s96, 0xce00000
	v_readlane_b32 s36, v245, 9
	s_addc_u32 s11, s97, 0
	s_ashr_i32 s16, s1, 6
	s_ashr_i32 s1, s0, 31
	v_readlane_b32 s38, v245, 11
	v_readlane_b32 s39, v245, 12
	s_add_i32 s4, s0, 0x111
	s_lshl_b64 s[0:1], s[0:1], 2
	s_mov_b64 s[14:15], s[38:39]
	s_add_u32 s0, s14, s0
	s_addc_u32 s1, s15, s1
	v_mov_b32_e32 v187, 0
	global_load_dword v1, v187, s[0:1] offset:1092
	s_cmp_lg_u32 s77, 1
	s_cselect_b32 s2, s33, 0
	s_ashr_i32 s3, s2, 31
	s_lshl_b64 s[2:3], s[2:3], 2
	s_add_u32 s0, s0, s2
	s_addc_u32 s1, s1, s3
	s_lshl_b32 s12, s16, 4
	s_ashr_i32 s2, s4, 4
	global_load_dword v22, v187, s[0:1] offset:1092
	s_or_b32 s18, s12, 1
	s_or_b32 s22, s12, 2
	s_or_b32 s24, s12, 3
	s_or_b32 s14, s12, 4
	s_or_b32 s6, s12, 5
	s_or_b32 s0, s12, 6
	s_or_b32 s4, s12, 7
	v_readlane_b32 s37, v245, 10
	v_readlane_b32 s40, v245, 13
	v_readlane_b32 s41, v245, 14
	v_readlane_b32 s42, v245, 15
	v_readlane_b32 s43, v245, 16
	v_readlane_b32 s44, v245, 17
	v_readlane_b32 s45, v245, 18
	v_readlane_b32 s46, v245, 19
	v_readlane_b32 s47, v245, 20
	v_readlane_b32 s48, v245, 21
	v_readlane_b32 s49, v245, 22
	s_ashr_i32 s13, s12, 31
	s_ashr_i32 s3, s2, 31
	s_ashr_i32 s19, s18, 31
	s_ashr_i32 s23, s22, 31
	s_ashr_i32 s25, s24, 31
	s_ashr_i32 s15, s14, 31
	s_ashr_i32 s7, s6, 31
	s_ashr_i32 s1, s0, 31
	s_ashr_i32 s5, s4, 31
	s_lshl_b64 s[30:31], s[12:13], 9
	s_lshl_b64 s[2:3], s[2:3], 10
	s_lshl_b64 s[36:37], s[18:19], 9
	s_lshl_b64 s[38:39], s[22:23], 9
	s_lshl_b64 s[40:41], s[24:25], 9
	s_lshl_b64 s[42:43], s[14:15], 9
	s_lshl_b64 s[44:45], s[6:7], 9
	s_lshl_b64 s[46:47], s[0:1], 9
	s_lshl_b64 s[48:49], s[4:5], 9
	v_and_b32_e32 v130, 63, v131
	s_add_u32 s2, s10, s2
	v_lshlrev_b32_e32 v186, 3, v130
	s_addc_u32 s3, s11, s3
	s_waitcnt vmcnt(0)
	v_lshl_add_u64 v[10:11], s[2:3], 0, v[186:187]
	v_readlane_b32 s50, v245, 23
	v_readlane_b32 s51, v245, 24
	v_lshlrev_b32_e32 v136, 4, v130
	s_mov_b32 s82, 0x1000000
	v_add_co_u32_e32 v12, vcc, s82, v10
	v_bfe_u32 v132, v131, 2, 4
	s_nop 0
	v_addc_co_u32_e32 v13, vcc, 0, v11, vcc
	v_ashrrev_i32_e32 v135, 6, v131
	v_bfe_u32 v138, v131, 5, 1
	v_ashrrev_i32_e32 v137, 7, v131
	v_and_b32_e32 v134, 31, v131
	v_lshl_add_u32 v216, v131, 2, 0
	v_lshl_add_u64 v[188:189], s[10:11], 0, v[186:187]
	v_lshlrev_b32_e32 v186, 4, v134
	v_lshl_add_u32 v139, v135, 10, 0
	s_mov_b64 s[10:11], 0x23201120
	v_mov_b32_e32 v133, v187
	s_mov_b32 s87, s85
	s_mov_b32 s68, 2
	s_mov_b32 s76, 0xff800000
	v_add_u32_e32 v217, v139, v136
	v_readfirstlane_b32 s2, v1
	s_ashr_i32 s3, s2, 31
	s_lshl_b64 s[2:3], s[2:3], 18
	s_add_u32 s50, s80, s2
	s_addc_u32 s51, s81, s3
	s_lshl_b64 s[4:5], s[4:5], 11
	s_add_u32 s8, s50, s4
	s_addc_u32 s9, s51, s5
	global_load_dwordx4 v[6:9], v136, s[8:9] offset:1024 nt
	global_load_dwordx4 v[2:5], v136, s[8:9] nt
	s_add_u32 s8, s78, s2
	s_addc_u32 s9, s79, s3
	s_add_u32 s28, s8, s4
	s_addc_u32 s29, s9, s5
	s_lshl_b64 s[4:5], s[12:13], 11
	s_add_u32 s2, s8, s4
	s_addc_u32 s3, s9, s5
	s_lshl_b64 s[18:19], s[18:19], 11
	global_load_dwordx4 v[66:69], v136, s[28:29] offset:1024 nt
	global_load_dwordx4 v[70:73], v136, s[28:29] nt
	s_add_u32 s28, s8, s18
	s_addc_u32 s29, s9, s19
	s_lshl_b64 s[22:23], s[22:23], 11
	s_add_u32 s56, s8, s22
	s_addc_u32 s57, s9, s23
	s_lshl_b64 s[24:25], s[24:25], 11
	s_add_u32 s58, s8, s24
	s_addc_u32 s59, s9, s25
	s_lshl_b64 s[14:15], s[14:15], 11
	s_add_u32 s72, s8, s14
	s_addc_u32 s73, s9, s15
	s_lshl_b64 s[6:7], s[6:7], 11
	s_add_u32 s74, s8, s6
	s_addc_u32 s75, s9, s7
	s_lshl_b64 s[0:1], s[0:1], 11
	s_add_u32 s52, s8, s0
	s_addc_u32 s53, s9, s1
	global_load_dwordx4 v[74:77], v136, s[52:53] nt
	global_load_dwordx4 v[78:81], v136, s[52:53] offset:1024 nt
	s_add_u32 s52, s50, s0
	s_addc_u32 s53, s51, s1
	s_mov_b64 s[0:1], 0x1000000
	v_lshl_add_u64 v[10:11], v[10:11], 0, s[0:1]
	global_load_dwordx2 v[14:15], v[10:11], off offset:512
	global_load_dwordx2 v[16:17], v[12:13], off
	s_add_u32 s6, s50, s6
	s_addc_u32 s7, s51, s7
	global_load_dwordx4 v[18:21], v136, s[52:53] offset:1024 nt
	global_load_dwordx4 v[10:13], v136, s[52:53] nt
	v_readfirstlane_b32 s26, v22
	s_movk_i32 s53, 0x88
	s_waitcnt vmcnt(3)
	v_lshlrev_b32_e32 v219, 16, v14
	v_and_b32_e32 v220, 0xffff0000, v14
	v_lshlrev_b32_e32 v198, 16, v15
	v_and_b32_e32 v199, 0xffff0000, v15
	s_waitcnt vmcnt(2)
	v_lshlrev_b32_e32 v221, 16, v16
	v_and_b32_e32 v222, 0xffff0000, v16
	v_lshlrev_b32_e32 v200, 16, v17
	v_and_b32_e32 v201, 0xffff0000, v17
	global_load_dwordx4 v[22:25], v136, s[6:7] offset:1024 nt
	global_load_dwordx4 v[14:17], v136, s[6:7] nt
	global_load_dwordx4 v[102:105], v136, s[74:75] nt
	global_load_dwordx4 v[98:101], v136, s[74:75] offset:1024 nt
	s_add_u32 s6, s50, s14
	s_addc_u32 s7, s51, s15
	global_load_dwordx4 v[58:61], v136, s[6:7] offset:1024 nt
	global_load_dwordx4 v[62:65], v136, s[6:7] nt
	global_load_dwordx4 v[118:121], v136, s[72:73] nt
	global_load_dwordx4 v[114:117], v136, s[72:73] offset:1024 nt
	s_add_u32 s6, s50, s24
	s_addc_u32 s7, s51, s25
	global_load_dwordx4 v[42:45], v136, s[6:7] offset:1024 nt
	global_load_dwordx4 v[26:29], v136, s[6:7] nt
	global_load_dwordx4 v[86:89], v136, s[58:59] nt
	global_load_dwordx4 v[82:85], v136, s[58:59] offset:1024 nt
	s_add_u32 s6, s50, s22
	s_addc_u32 s7, s51, s23
	global_load_dwordx4 v[46:49], v136, s[6:7] offset:1024 nt
	global_load_dwordx4 v[38:41], v136, s[6:7] nt
	global_load_dwordx4 v[94:97], v136, s[56:57] nt
	global_load_dwordx4 v[90:93], v136, s[56:57] offset:1024 nt
	s_add_u32 s6, s50, s18
	s_addc_u32 s7, s51, s19
	s_add_u32 s4, s50, s4
	s_addc_u32 s5, s51, s5
	global_load_dwordx4 v[50:53], v136, s[6:7] offset:1024 nt
	global_load_dwordx4 v[34:37], v136, s[6:7] nt
	global_load_dwordx4 v[110:113], v136, s[28:29] nt
	global_load_dwordx4 v[106:109], v136, s[28:29] offset:1024 nt
	global_load_dwordx4 v[54:57], v136, s[4:5] offset:1024 nt
	global_load_dwordx4 v[30:33], v136, s[4:5] nt
	global_load_dwordx4 v[126:129], v136, s[2:3] nt
	global_load_dwordx4 v[122:125], v136, s[2:3] offset:1024 nt
	s_lshl_b32 s2, s16, 12
	s_add_i32 s4, s2, 0
	s_mulk_i32 s16, 0xf020
	v_add_u32_e32 v1, s4, v136
	s_add_i32 s4, s4, s16
	v_add_u32_e32 v214, s4, v132
	v_lshlrev_b32_e32 v132, 1, v135
	v_and_or_b32 v132, v132, 2, v138
	v_lshl_add_u32 v132, v132, 1, v137
	s_movk_i32 s6, 0x100
	v_lshl_add_u32 v215, v132, 2, 0
	v_and_b32_e32 v132, -8, v131
	v_cmp_gt_i32_e64 s[4:5], s6, v131
	v_cmp_eq_u32_e64 s[6:7], s6, v132
	v_mul_lo_u32 v132, v131, s53
	v_lshlrev_b32_e32 v131, 2, v135
	v_cmp_eq_u32_e64 s[2:3], 0, v134
	v_and_b32_e32 v131, 4, v131
	v_lshlrev_b32_e32 v134, 1, v138
	v_add3_u32 v131, v137, v131, v134
	v_mul_lo_u32 v134, v131, s53
	v_ashrrev_i32_e32 v135, 31, v134
	v_lshl_add_u64 v[134:135], v[134:135], 2, v[186:187]
	v_lshl_add_u64 v[190:191], v[134:135], 0, s[10:11]
	v_readlane_b32 s10, v245, 51
	s_lshl_b32 s10, s10, 1
	v_readlane_b32 s11, v245, 52
	s_or_b32 s14, s12, 8
	s_or_b32 s22, s12, 12
	s_or_b32 s16, s12, 9
	s_or_b32 s18, s12, 10
	s_or_b32 s24, s12, 11
	s_or_b32 s28, s12, 13
	s_or_b32 s56, s12, 14
	s_or_b32 s12, s12, 15
	s_andn2_b32 s10, s10, 63
	s_lshl_b32 s11, s11, 1
	s_ashr_i32 s13, s12, 31
	s_or_b32 s10, s10, s11
	s_ashr_i32 s15, s14, 31
	s_ashr_i32 s17, s16, 31
	s_ashr_i32 s19, s18, 31
	s_ashr_i32 s25, s24, 31
	s_ashr_i32 s23, s22, 31
	s_ashr_i32 s29, s28, 31
	s_ashr_i32 s57, s56, 31
	s_lshl_b64 s[58:59], s[12:13], 9
	s_add_i32 s12, s10, 0x110
	s_lshl_b32 s69, s33, 1
	s_lshl_b64 s[14:15], s[14:15], 9
	s_lshl_b64 s[16:17], s[16:17], 9
	s_lshl_b64 s[18:19], s[18:19], 9
	s_lshl_b64 s[24:25], s[24:25], 9
	s_lshl_b64 s[22:23], s[22:23], 9
	s_lshl_b64 s[28:29], s[28:29], 9
	s_lshl_b64 s[56:57], s[56:57], 9
	s_ashr_i32 s72, s12, 31
	s_mul_i32 s10, s12, 0x1100
	v_add_u32_e32 v132, 0xffff7800, v132
	s_mul_hi_i32 s11, s12, 0x1100
	s_add_u32 s10, s96, s10
	s_addc_u32 s11, s97, s11
	s_ashr_i32 s73, s33, 31
	v_lshlrev_b64 v[192:193], 2, v[132:133]
	s_or_b32 s74, s12, 1
	s_sub_i32 s75, s20, s21
	s_lshl_b64 s[12:13], s[14:15], 2
	v_lshlrev_b32_e32 v186, 4, v130
	s_lshl_b64 s[14:15], s[16:17], 2
	s_lshl_b64 s[16:17], s[18:19], 2
	s_lshl_b64 s[18:19], s[24:25], 2
	s_lshl_b64 s[20:21], s[22:23], 2
	s_lshl_b64 s[22:23], s[28:29], 2
	s_lshl_b64 s[24:25], s[56:57], 2
	s_lshl_b64 s[28:29], s[58:59], 2
	s_lshl_b64 s[30:31], s[30:31], 2
	s_lshl_b64 s[36:37], s[36:37], 2
	s_lshl_b64 s[38:39], s[38:39], 2
	s_lshl_b64 s[40:41], s[40:41], 2
	s_lshl_b64 s[42:43], s[42:43], 2
	s_lshl_b64 s[44:45], s[44:45], 2
	s_lshl_b64 s[46:47], s[46:47], 2
	s_lshl_b64 s[48:49], s[48:49], 2
	s_waitcnt vmcnt(0)
	s_branch .LBB0_886

.LBB0_886:
	s_add_i32 s83, s68, -1
	s_add_i32 s86, s33, s74
	s_cmp_lt_i32 s68, s77
	s_cselect_b32 s56, s69, 0
	s_ashr_i32 s27, s26, 31
	s_ashr_i32 s57, s56, 31
	s_add_u32 s56, s74, s56
	s_addc_u32 s57, s72, s57
	s_lshl_b64 s[84:85], s[56:57], 2
	v_readlane_b32 s52, v245, 9
	v_readlane_b32 s54, v245, 11
	v_readlane_b32 s56, v245, 13
	v_readlane_b32 s55, v245, 12
	v_readlane_b32 s57, v245, 14
	s_add_u32 s56, s54, s84
	s_addc_u32 s57, s55, s85
	s_cmp_lt_i32 s83, s77
	v_readlane_b32 s53, v245, 10
	v_readlane_b32 s58, v245, 15
	global_load_dword v218, v187, s[56:57]
	s_cselect_b32 s56, s86, s74
	s_ashr_i32 s56, s56, 4
	s_ashr_i32 s57, s56, 31
	s_lshl_b64 s[56:57], s[56:57], 10
	v_lshl_add_u64 v[130:131], v[188:189], 0, s[56:57]
	v_lshl_add_u64 v[132:133], v[130:131], 0, s[0:1]
	v_add_co_u32_e32 v130, vcc, s82, v130
	v_readlane_b32 s59, v245, 16
	s_nop 0
	v_addc_co_u32_e32 v131, vcc, 0, v131, vcc
	global_load_dwordx2 v[196:197], v[130:131], off
	global_load_dwordx2 v[194:195], v[132:133], off offset:512
	v_readlane_b32 s60, v245, 17
	v_readlane_b32 s61, v245, 18
	v_readlane_b32 s62, v245, 19
	v_readlane_b32 s63, v245, 20
	v_readlane_b32 s64, v245, 21
	v_readlane_b32 s65, v245, 22
	v_readlane_b32 s66, v245, 23
	v_readlane_b32 s67, v245, 24
	s_mov_b64 s[56:57], s[50:51]
	s_mov_b64 s[58:59], s[8:9]
	s_waitcnt vmcnt(34)
	v_mul_f32_e32 v130, v222, v127
	v_fmac_f32_e32 v130, v221, v126
	v_pk_mul_f32 v[126:127], v[200:201], v[128:129]
	s_lshl_b64 s[50:51], s[26:27], 18
	v_add_f32_e32 v126, v126, v130
	v_add_f32_e32 v126, v127, v126
	s_waitcnt vmcnt(33)
	v_mul_f32_e32 v127, v123, v220
	v_fmac_f32_e32 v127, v122, v219
	v_pk_mul_f32 v[122:123], v[124:125], v[198:199]
	s_add_u32 s8, s78, s50
	v_add_f32_e32 v122, v122, v127
	v_add_f32_e32 v122, v123, v122
	v_add_f32_dpp v123, v126, v126 quad_perm:[1,0,3,2] row_mask:0xf bank_mask:0xf bound_ctrl:1
	s_waitcnt vmcnt(30)
	v_mul_f32_e32 v126, v222, v111
	v_fmac_f32_e32 v126, v221, v110
	v_pk_mul_f32 v[110:111], v[200:201], v[112:113]
	v_add_f32_dpp v123, v123, v123 quad_perm:[2,3,0,1] row_mask:0xf bank_mask:0xf bound_ctrl:1
	v_add_f32_e32 v110, v110, v126
	v_add_f32_e32 v110, v111, v110
	s_waitcnt vmcnt(29)
	v_mul_f32_e32 v111, v107, v220
	v_fmac_f32_e32 v111, v106, v219
	v_pk_mul_f32 v[106:107], v[108:109], v[198:199]
	v_add_f32_dpp v122, v122, v122 quad_perm:[1,0,3,2] row_mask:0xf bank_mask:0xf bound_ctrl:1
	v_add_f32_e32 v106, v106, v111
	v_add_f32_e32 v106, v107, v106
	v_add_f32_dpp v107, v110, v110 quad_perm:[1,0,3,2] row_mask:0xf bank_mask:0xf bound_ctrl:1
	s_waitcnt vmcnt(26)
	v_mul_f32_e32 v110, v222, v95
	v_fmac_f32_e32 v110, v221, v94
	v_pk_mul_f32 v[94:95], v[200:201], v[96:97]
	v_add_f32_dpp v107, v107, v107 quad_perm:[2,3,0,1] row_mask:0xf bank_mask:0xf bound_ctrl:1
	v_add_f32_e32 v94, v94, v110
	v_add_f32_e32 v94, v95, v94
	s_waitcnt vmcnt(25)
	v_mul_f32_e32 v95, v91, v220
	v_fmac_f32_e32 v95, v90, v219
	v_pk_mul_f32 v[90:91], v[92:93], v[198:199]
	v_add_f32_dpp v106, v106, v106 quad_perm:[1,0,3,2] row_mask:0xf bank_mask:0xf bound_ctrl:1
	v_add_f32_e32 v90, v90, v95
	v_add_f32_e32 v90, v91, v90
	v_add_f32_dpp v91, v94, v94 quad_perm:[1,0,3,2] row_mask:0xf bank_mask:0xf bound_ctrl:1
	s_waitcnt vmcnt(22)
	v_mul_f32_e32 v94, v222, v87
	v_fmac_f32_e32 v94, v221, v86
	v_pk_mul_f32 v[86:87], v[200:201], v[88:89]
	v_add_f32_dpp v123, v123, v123 row_ror:4 row_mask:0xf bank_mask:0xf bound_ctrl:1
	v_add_f32_e32 v86, v86, v94
	v_add_f32_e32 v86, v87, v86
	s_waitcnt vmcnt(21)
	v_mul_f32_e32 v87, v83, v220
	v_fmac_f32_e32 v87, v82, v219
	v_pk_mul_f32 v[82:83], v[84:85], v[198:199]
	v_add_f32_dpp v122, v122, v122 quad_perm:[2,3,0,1] row_mask:0xf bank_mask:0xf bound_ctrl:1
	v_add_f32_e32 v82, v82, v87
	v_add_f32_e32 v82, v83, v82
	v_add_f32_dpp v83, v86, v86 quad_perm:[1,0,3,2] row_mask:0xf bank_mask:0xf bound_ctrl:1
	v_add_f32_dpp v107, v107, v107 row_ror:4 row_mask:0xf bank_mask:0xf bound_ctrl:1
	v_add_f32_dpp v106, v106, v106 quad_perm:[2,3,0,1] row_mask:0xf bank_mask:0xf bound_ctrl:1
	v_add_f32_dpp v91, v91, v91 quad_perm:[2,3,0,1] row_mask:0xf bank_mask:0xf bound_ctrl:1
	v_add_f32_dpp v90, v90, v90 quad_perm:[1,0,3,2] row_mask:0xf bank_mask:0xf bound_ctrl:1
	v_add_f32_dpp v83, v83, v83 quad_perm:[2,3,0,1] row_mask:0xf bank_mask:0xf bound_ctrl:1
	v_add_f32_dpp v82, v82, v82 quad_perm:[1,0,3,2] row_mask:0xf bank_mask:0xf bound_ctrl:1
	v_add_f32_dpp v123, v123, v123 row_ror:8 row_mask:0xf bank_mask:0xf bound_ctrl:1
	v_add_f32_dpp v122, v122, v122 row_ror:4 row_mask:0xf bank_mask:0xf bound_ctrl:1
	v_add_f32_dpp v107, v107, v107 row_ror:8 row_mask:0xf bank_mask:0xf bound_ctrl:1
	v_add_f32_dpp v106, v106, v106 row_ror:4 row_mask:0xf bank_mask:0xf bound_ctrl:1
	v_add_f32_dpp v91, v91, v91 row_ror:4 row_mask:0xf bank_mask:0xf bound_ctrl:1
	v_add_f32_dpp v90, v90, v90 quad_perm:[2,3,0,1] row_mask:0xf bank_mask:0xf bound_ctrl:1
	v_add_f32_dpp v83, v83, v83 row_ror:4 row_mask:0xf bank_mask:0xf bound_ctrl:1
	v_add_f32_dpp v82, v82, v82 quad_perm:[2,3,0,1] row_mask:0xf bank_mask:0xf bound_ctrl:1
	v_add_f32_dpp v122, v122, v122 row_ror:8 row_mask:0xf bank_mask:0xf bound_ctrl:1
	v_mov_b32_e32 v124, v123
	v_add_f32_dpp v106, v106, v106 row_ror:8 row_mask:0xf bank_mask:0xf bound_ctrl:1
	v_mov_b32_e32 v108, v107
	v_add_f32_dpp v91, v91, v91 row_ror:8 row_mask:0xf bank_mask:0xf bound_ctrl:1
	v_add_f32_dpp v90, v90, v90 row_ror:4 row_mask:0xf bank_mask:0xf bound_ctrl:1
	v_add_f32_dpp v88, v83, v83 row_ror:8 row_mask:0xf bank_mask:0xf bound_ctrl:1
	v_add_f32_dpp v82, v82, v82 row_ror:4 row_mask:0xf bank_mask:0xf bound_ctrl:1
	v_permlane16_swap_b32_e32 v123, v124
	v_mov_b32_e32 v125, v122
	v_permlane16_swap_b32_e32 v107, v108
	v_mov_b32_e32 v109, v106
	v_add_f32_dpp v90, v90, v90 row_ror:8 row_mask:0xf bank_mask:0xf bound_ctrl:1
	v_mov_b32_e32 v92, v91
	v_add_f32_dpp v89, v82, v82 row_ror:8 row_mask:0xf bank_mask:0xf bound_ctrl:1
	v_mov_b32_e32 v94, v88
	v_permlane16_swap_b32_e32 v122, v125
	v_permlane16_swap_b32_e32 v106, v109
	v_permlane16_swap_b32_e32 v91, v92
	v_mov_b32_e32 v93, v90
	v_permlane16_swap_b32_e32 v88, v94
	v_mov_b32_e32 v95, v89
	v_max3_f32 v82, v123, s76, v107
	v_permlane16_swap_b32_e32 v90, v93
	v_permlane16_swap_b32_e32 v89, v95
	v_max3_f32 v83, v124, s76, v108
	v_max3_f32 v84, v122, s76, v106
	v_max3_f32 v155, v82, v91, v88
	v_max3_f32 v157, v83, v92, v94
	v_max3_f32 v159, v84, v90, v89
	v_sub_f32_e32 v82, 0xff800000, v155
	v_sub_f32_e32 v84, v123, v155
	v_max3_f32 v85, v125, s76, v109
	v_exp_f32_e32 v83, v82
	v_sub_f32_e32 v82, 0xff800000, v157
	v_exp_f32_e32 v164, v84
	v_sub_f32_e32 v84, v124, v157
	v_max3_f32 v165, v85, v93, v95
	v_exp_f32_e32 v85, v82
	v_sub_f32_e32 v82, 0xff800000, v159
	v_exp_f32_e32 v156, v84
	v_sub_f32_e32 v84, v122, v159
	v_exp_f32_e32 v86, v82
	v_sub_f32_e32 v82, 0xff800000, v165
	v_exp_f32_e32 v166, v84
	v_sub_f32_e32 v84, v125, v165
	v_exp_f32_e32 v87, v82
	v_exp_f32_e32 v84, v84
	v_mul_f32_e32 v154, 0, v85
	v_fma_f32 v85, 0, v85, v156
	v_mul_f32_e32 v82, 0, v87
	v_mov_b32_e32 v110, v84
	v_mul_f32_e32 v160, 0, v83
	v_mul_f32_e32 v162, 0, v86
	v_fma_f32 v96, 0, v83, v164
	v_fma_f32 v97, 0, v86, v166
	v_fmac_f32_e32 v110, 0, v87
	v_pk_fma_f32 v[86:87], v[54:55], v[84:85], v[82:83] op_sel_hi:[1,0,0]
	v_pk_fma_f32 v[82:83], v[56:57], v[84:85], v[82:83] op_sel_hi:[1,0,0]
	v_sub_f32_e32 v84, v107, v155
	v_exp_f32_e32 v168, v84
	v_sub_f32_e32 v84, v108, v157
	v_exp_f32_e32 v158, v84
	v_sub_f32_e32 v84, v106, v159
	v_exp_f32_e32 v170, v84
	v_sub_f32_e32 v84, v109, v165
	v_exp_f32_e32 v84, v84
	v_add_f32_e32 v106, v158, v85
	v_add_f32_e32 v96, v168, v96
	v_add_f32_e32 v97, v170, v97
	v_add_f32_e32 v107, v84, v110
	v_pk_fma_f32 v[82:83], v[52:53], v[84:85], v[82:83] op_sel_hi:[1,0,1]
	v_pk_fma_f32 v[84:85], v[50:51], v[84:85], v[86:87] op_sel_hi:[1,0,1]
	v_sub_f32_e32 v86, v91, v155
	v_exp_f32_e32 v172, v86
	v_sub_f32_e32 v86, v92, v157
	v_exp_f32_e32 v174, v86
	v_sub_f32_e32 v86, v90, v159
	v_exp_f32_e32 v176, v86
	v_sub_f32_e32 v86, v93, v165
	v_exp_f32_e32 v86, v86
	v_add_f32_e32 v87, v172, v96
	v_add_f32_e32 v90, v174, v106
	v_add_f32_e32 v91, v176, v97
	v_add_f32_e32 v92, v86, v107
	v_pk_fma_f32 v[84:85], v[46:47], v[86:87], v[84:85] op_sel_hi:[1,0,1]
	v_pk_fma_f32 v[82:83], v[48:49], v[86:87], v[82:83] op_sel_hi:[1,0,1]
	v_sub_f32_e32 v86, v88, v155
	v_exp_f32_e32 v206, v86
	v_sub_f32_e32 v86, v94, v157
	v_exp_f32_e32 v208, v86
	v_sub_f32_e32 v86, v89, v159
	v_exp_f32_e32 v210, v86
	v_sub_f32_e32 v86, v95, v165
	v_exp_f32_e32 v86, v86
	s_addc_u32 s9, s79, s51
	v_add_f32_e32 v167, v206, v87
	v_add_f32_e32 v169, v208, v90
	v_add_f32_e32 v171, v210, v91
	v_add_f32_e32 v173, v86, v92
	s_waitcnt vmcnt(19)
	v_pk_fma_f32 v[202:203], v[44:45], v[86:87], v[82:83] op_sel_hi:[1,0,1]
	v_pk_fma_f32 v[204:205], v[42:43], v[86:87], v[84:85] op_sel_hi:[1,0,1]
	s_add_u32 s52, s58, s12
	s_addc_u32 s53, s59, s13
	global_load_dwordx4 v[182:185], v186, s[52:53] nt
	global_load_dwordx4 v[178:181], v186, s[52:53] offset:1024 nt
	s_add_u32 s52, s56, s12
	s_addc_u32 s53, s57, s13
	global_load_dwordx4 v[86:89], v186, s[52:53] nt
	global_load_dwordx4 v[82:85], v186, s[52:53] offset:1024 nt
	s_add_u32 s52, s58, s14
	s_addc_u32 s53, s59, s15
	global_load_dwordx4 v[126:129], v186, s[52:53] nt
	global_load_dwordx4 v[122:125], v186, s[52:53] offset:1024 nt
	s_add_u32 s52, s56, s14
	s_addc_u32 s53, s57, s15
	global_load_dwordx4 v[130:133], v186, s[52:53] nt
	global_load_dwordx4 v[142:145], v186, s[52:53] offset:1024 nt
	s_add_u32 s52, s58, s16
	s_addc_u32 s53, s59, s17
	global_load_dwordx4 v[110:113], v186, s[52:53] nt
	global_load_dwordx4 v[106:109], v186, s[52:53] offset:1024 nt
	s_add_u32 s52, s56, s16
	s_addc_u32 s53, s57, s17
	global_load_dwordx4 v[134:137], v186, s[52:53] nt
	global_load_dwordx4 v[146:149], v186, s[52:53] offset:1024 nt
	s_add_u32 s52, s58, s18
	s_addc_u32 s53, s59, s19
	global_load_dwordx4 v[94:97], v186, s[52:53] nt
	global_load_dwordx4 v[90:93], v186, s[52:53] offset:1024 nt
	s_add_u32 s52, s56, s18
	s_addc_u32 s53, s57, s19
	global_load_dwordx4 v[138:141], v186, s[52:53] nt
	global_load_dwordx4 v[150:153], v186, s[52:53] offset:1024 nt
	v_pk_fma_f32 v[212:213], v[30:31], v[164:165], v[160:161] op_sel_hi:[1,0,0]
	v_pk_fma_f32 v[160:161], v[32:33], v[164:165], v[160:161] op_sel_hi:[1,0,0]
	v_pk_fma_f32 v[54:55], v[54:55], v[166:167], v[162:163] op_sel_hi:[1,0,0]
	v_pk_fma_f32 v[56:57], v[56:57], v[166:167], v[162:163] op_sel_hi:[1,0,0]
	v_pk_fma_f32 v[160:161], v[36:37], v[168:169], v[160:161] op_sel_hi:[1,0,1]
	v_pk_fma_f32 v[162:163], v[34:35], v[168:169], v[212:213] op_sel_hi:[1,0,1]
	v_pk_fma_f32 v[52:53], v[52:53], v[170:171], v[56:57] op_sel_hi:[1,0,1]
	v_pk_fma_f32 v[50:51], v[50:51], v[170:171], v[54:55] op_sel_hi:[1,0,1]
	v_pk_fma_f32 v[54:55], v[38:39], v[172:173], v[162:163] op_sel_hi:[1,0,1]
	v_pk_fma_f32 v[56:57], v[40:41], v[172:173], v[160:161] op_sel_hi:[1,0,1]
	v_pk_fma_f32 v[50:51], v[46:47], v[176:177], v[50:51] op_sel_hi:[1,0,1]
	v_pk_fma_f32 v[52:53], v[48:49], v[176:177], v[52:53] op_sel_hi:[1,0,1]
	v_pk_fma_f32 v[46:47], v[28:29], v[206:207], v[56:57] op_sel_hi:[1,0,1]
	v_pk_fma_f32 v[48:49], v[26:27], v[206:207], v[54:55] op_sel_hi:[1,0,1]
	v_pk_fma_f32 v[44:45], v[44:45], v[210:211], v[52:53] op_sel_hi:[1,0,1]
	v_pk_fma_f32 v[42:43], v[42:43], v[210:211], v[50:51] op_sel_hi:[1,0,1]
	s_waitcnt vmcnt(34)
	v_mul_f32_e32 v52, v222, v119
	v_fmac_f32_e32 v52, v221, v118
	v_pk_mul_f32 v[50:51], v[200:201], v[120:121]
	s_waitcnt vmcnt(33)
	v_mul_f32_e32 v53, v115, v220
	v_add_f32_e32 v50, v50, v52
	v_add_f32_e32 v52, v51, v50
	v_fmac_f32_e32 v53, v114, v219
	v_pk_mul_f32 v[50:51], v[116:117], v[198:199]
	s_waitcnt vmcnt(29)
	v_mul_f32_e32 v57, v99, v220
	v_add_f32_e32 v50, v50, v53
	v_add_f32_e32 v50, v51, v50
	v_add_f32_dpp v51, v52, v52 quad_perm:[1,0,3,2] row_mask:0xf bank_mask:0xf bound_ctrl:1
	v_mul_f32_e32 v52, v222, v103
	v_add_f32_dpp v50, v50, v50 quad_perm:[1,0,3,2] row_mask:0xf bank_mask:0xf bound_ctrl:1
	v_add_f32_dpp v51, v51, v51 quad_perm:[2,3,0,1] row_mask:0xf bank_mask:0xf bound_ctrl:1
	v_fmac_f32_e32 v52, v221, v102
	v_add_f32_dpp v50, v50, v50 quad_perm:[2,3,0,1] row_mask:0xf bank_mask:0xf bound_ctrl:1
	v_add_f32_dpp v51, v51, v51 row_ror:4 row_mask:0xf bank_mask:0xf bound_ctrl:1
	v_fmac_f32_e32 v57, v98, v219
	v_add_f32_dpp v50, v50, v50 row_ror:4 row_mask:0xf bank_mask:0xf bound_ctrl:1
	v_add_f32_dpp v53, v51, v51 row_ror:8 row_mask:0xf bank_mask:0xf bound_ctrl:1
	v_pk_fma_f32 v[30:31], v[30:31], v[156:157], v[154:155] op_sel_hi:[1,0,0]
	v_add_f32_dpp v54, v50, v50 row_ror:8 row_mask:0xf bank_mask:0xf bound_ctrl:1
	v_pk_mul_f32 v[50:51], v[200:201], v[104:105]
	v_mov_b32_e32 v56, v54
	v_add_f32_e32 v50, v50, v52
	v_add_f32_e32 v52, v51, v50
	v_pk_mul_f32 v[50:51], v[100:101], v[198:199]
	v_permlane16_swap_b32_e32 v54, v56
	v_add_f32_e32 v50, v50, v57
	v_add_f32_e32 v50, v51, v50
	v_add_f32_dpp v51, v52, v52 quad_perm:[1,0,3,2] row_mask:0xf bank_mask:0xf bound_ctrl:1
	s_waitcnt vmcnt(26)
	v_mul_f32_e32 v52, v222, v75
	v_add_f32_dpp v50, v50, v50 quad_perm:[1,0,3,2] row_mask:0xf bank_mask:0xf bound_ctrl:1
	v_add_f32_dpp v51, v51, v51 quad_perm:[2,3,0,1] row_mask:0xf bank_mask:0xf bound_ctrl:1
	v_fmac_f32_e32 v52, v221, v74
	v_add_f32_dpp v50, v50, v50 quad_perm:[2,3,0,1] row_mask:0xf bank_mask:0xf bound_ctrl:1
	v_add_f32_dpp v51, v51, v51 row_ror:4 row_mask:0xf bank_mask:0xf bound_ctrl:1
	s_waitcnt vmcnt(25)
	v_mul_f32_e32 v57, v79, v220
	v_add_f32_dpp v50, v50, v50 row_ror:4 row_mask:0xf bank_mask:0xf bound_ctrl:1
	v_add_f32_dpp v98, v51, v51 row_ror:8 row_mask:0xf bank_mask:0xf bound_ctrl:1
	v_fmac_f32_e32 v57, v78, v219
	v_add_f32_dpp v99, v50, v50 row_ror:8 row_mask:0xf bank_mask:0xf bound_ctrl:1
	v_pk_mul_f32 v[50:51], v[200:201], v[76:77]
	v_mov_b32_e32 v101, v99
	v_add_f32_e32 v50, v50, v52
	v_add_f32_e32 v52, v51, v50
	v_pk_mul_f32 v[50:51], v[80:81], v[198:199]
	v_permlane16_swap_b32_e32 v99, v101
	v_add_f32_e32 v50, v50, v57
	v_add_f32_e32 v50, v51, v50
	v_add_f32_dpp v51, v52, v52 quad_perm:[1,0,3,2] row_mask:0xf bank_mask:0xf bound_ctrl:1
	s_waitcnt vmcnt(22)
	v_mul_f32_e32 v52, v222, v71
	v_add_f32_dpp v50, v50, v50 quad_perm:[1,0,3,2] row_mask:0xf bank_mask:0xf bound_ctrl:1
	v_add_f32_dpp v51, v51, v51 quad_perm:[2,3,0,1] row_mask:0xf bank_mask:0xf bound_ctrl:1
	v_fmac_f32_e32 v52, v221, v70
	v_add_f32_dpp v50, v50, v50 quad_perm:[2,3,0,1] row_mask:0xf bank_mask:0xf bound_ctrl:1
	v_add_f32_dpp v51, v51, v51 row_ror:4 row_mask:0xf bank_mask:0xf bound_ctrl:1
	s_waitcnt vmcnt(21)
	v_mul_f32_e32 v57, v67, v220
	v_add_f32_dpp v50, v50, v50 row_ror:4 row_mask:0xf bank_mask:0xf bound_ctrl:1
	v_add_f32_dpp v74, v51, v51 row_ror:8 row_mask:0xf bank_mask:0xf bound_ctrl:1
	v_fmac_f32_e32 v57, v66, v219
	v_add_f32_dpp v75, v50, v50 row_ror:8 row_mask:0xf bank_mask:0xf bound_ctrl:1
	v_pk_mul_f32 v[50:51], v[200:201], v[72:73]
	v_mov_b32_e32 v77, v75
	v_add_f32_e32 v50, v50, v52
	v_add_f32_e32 v52, v51, v50
	v_pk_mul_f32 v[50:51], v[68:69], v[198:199]
	v_pk_fma_f32 v[32:33], v[32:33], v[156:157], v[154:155] op_sel_hi:[1,0,0]
	v_add_f32_e32 v50, v50, v57
	v_add_f32_e32 v50, v51, v50
	v_add_f32_dpp v51, v52, v52 quad_perm:[1,0,3,2] row_mask:0xf bank_mask:0xf bound_ctrl:1
	v_mov_b32_e32 v55, v53
	v_add_f32_dpp v50, v50, v50 quad_perm:[1,0,3,2] row_mask:0xf bank_mask:0xf bound_ctrl:1
	v_add_f32_dpp v51, v51, v51 quad_perm:[2,3,0,1] row_mask:0xf bank_mask:0xf bound_ctrl:1
	v_mov_b32_e32 v100, v98
	v_add_f32_dpp v50, v50, v50 quad_perm:[2,3,0,1] row_mask:0xf bank_mask:0xf bound_ctrl:1
	v_add_f32_dpp v51, v51, v51 row_ror:4 row_mask:0xf bank_mask:0xf bound_ctrl:1
	v_permlane16_swap_b32_e32 v75, v77
	v_add_f32_dpp v50, v50, v50 row_ror:4 row_mask:0xf bank_mask:0xf bound_ctrl:1
	v_add_f32_dpp v51, v51, v51 row_ror:8 row_mask:0xf bank_mask:0xf bound_ctrl:1
	v_pk_fma_f32 v[32:33], v[36:37], v[158:159], v[32:33] op_sel_hi:[1,0,1]
	v_add_f32_dpp v66, v50, v50 row_ror:8 row_mask:0xf bank_mask:0xf bound_ctrl:1
	v_mov_b32_e32 v68, v66
	s_nop 1
	v_permlane16_swap_b32_e32 v66, v68
	v_pk_fma_f32 v[30:31], v[34:35], v[158:159], v[30:31] op_sel_hi:[1,0,1]
	v_max3_f32 v36, v159, v54, v99
	v_permlane16_swap_b32_e32 v53, v55
	v_permlane16_swap_b32_e32 v98, v100
	v_mov_b32_e32 v76, v74
	v_mov_b32_e32 v67, v51
	v_pk_fma_f32 v[30:31], v[38:39], v[174:175], v[30:31] op_sel_hi:[1,0,1]
	v_max3_f32 v37, v165, v56, v101
	v_max3_f32 v223, v36, v75, v66
	v_permlane16_swap_b32_e32 v74, v76
	v_permlane16_swap_b32_e32 v51, v67
	v_max3_f32 v34, v155, v53, v98
	v_max3_f32 v229, v37, v77, v68
	v_pk_fma_f32 v[26:27], v[26:27], v[208:209], v[30:31] op_sel_hi:[1,0,1]
	v_sub_f32_e32 v31, v159, v223
	v_pk_fma_f32 v[32:33], v[40:41], v[174:175], v[32:33] op_sel_hi:[1,0,1]
	v_max3_f32 v35, v157, v55, v100
	v_max3_f32 v39, v34, v74, v51
	v_exp_f32_e32 v52, v31
	v_sub_f32_e32 v31, v165, v229
	v_max3_f32 v41, v35, v76, v67
	v_pk_fma_f32 v[28:29], v[28:29], v[208:209], v[32:33] op_sel_hi:[1,0,1]
	v_exp_f32_e32 v32, v31
	v_sub_f32_e32 v31, v53, v39
	v_exp_f32_e32 v34, v31
	v_sub_f32_e32 v31, v55, v41
	v_exp_f32_e32 v36, v31
	v_sub_f32_e32 v31, v54, v223
	v_sub_f32_e32 v33, v56, v229
	v_exp_f32_e32 v40, v31
	v_exp_f32_e32 v38, v33
	v_sub_f32_e32 v30, v155, v39
	v_mov_b32_e32 v33, v34
	v_pk_mul_f32 v[54:55], v[64:65], v[34:35] op_sel_hi:[1,0]
	v_pk_mul_f32 v[56:57], v[62:63], v[34:35] op_sel_hi:[1,0]
	v_mov_b32_e32 v53, v36
	v_pk_mul_f32 v[34:35], v[64:65], v[36:37] op_sel_hi:[1,0]
	v_pk_mul_f32 v[36:37], v[62:63], v[36:37] op_sel_hi:[1,0]
	v_mov_b32_e32 v62, v40
	v_pk_mul_f32 v[206:207], v[60:61], v[40:41] op_sel_hi:[1,0]
	v_pk_mul_f32 v[208:209], v[58:59], v[40:41] op_sel_hi:[1,0]
	v_sub_f32_e32 v40, v99, v223
	v_exp_f32_e32 v50, v30
	v_sub_f32_e32 v30, v157, v41
	v_fma_f32 v31, v173, v32, v38
	v_pk_mul_f32 v[224:225], v[60:61], v[38:39] op_sel_hi:[1,0]
	v_pk_mul_f32 v[226:227], v[58:59], v[38:39] op_sel_hi:[1,0]
	v_sub_f32_e32 v38, v98, v39
	v_exp_f32_e32 v212, v40
	v_sub_f32_e32 v40, v101, v229
	v_sub_f32_e32 v51, v51, v39
	v_exp_f32_e32 v30, v30
	v_exp_f32_e32 v210, v38
	v_sub_f32_e32 v38, v100, v41
	v_exp_f32_e32 v228, v40
	v_sub_f32_e32 v40, v74, v39
	v_sub_f32_e32 v59, v75, v223
	v_exp_f32_e32 v236, v51
	v_sub_f32_e32 v51, v67, v41
	v_exp_f32_e32 v38, v38
	v_exp_f32_e32 v230, v40
	v_sub_f32_e32 v40, v76, v41
	v_exp_f32_e32 v232, v59
	v_sub_f32_e32 v59, v77, v229
	v_exp_f32_e32 v238, v51
	v_sub_f32_e32 v51, v66, v223
	v_exp_f32_e32 v40, v40
	v_exp_f32_e32 v234, v59
	v_exp_f32_e32 v240, v51
	v_sub_f32_e32 v51, v68, v229
	v_exp_f32_e32 v242, v51
	v_fmac_f32_e32 v33, v167, v50
	v_fmac_f32_e32 v53, v169, v30
	v_fmac_f32_e32 v62, v171, v52
	v_add_f32_e32 v33, v210, v33
	v_add_f32_e32 v53, v38, v53
	v_add_f32_e32 v58, v212, v62
	v_add_f32_e32 v31, v228, v31
	s_add_u32 s50, s80, s50
	v_add_f32_e32 v33, v230, v33
	v_add_f32_e32 v53, v40, v53
	v_add_f32_e32 v58, v232, v58
	v_add_f32_e32 v31, v234, v31
	s_addc_u32 s51, s81, s51
	v_add_f32_e32 v51, v236, v33
	v_add_f32_e32 v53, v238, v53
	v_add_f32_e32 v231, v240, v58
	v_add_f32_e32 v31, v242, v31
	s_add_u32 s52, s58, s20
	s_addc_u32 s53, s59, s21
	global_load_dwordx4 v[118:121], v186, s[52:53] nt
	global_load_dwordx4 v[114:117], v186, s[52:53] offset:1024 nt
	s_add_u32 s52, s56, s20
	s_addc_u32 s53, s57, s21
	global_load_dwordx4 v[62:65], v186, s[52:53] nt
	global_load_dwordx4 v[58:61], v186, s[52:53] offset:1024 nt
	s_add_u32 s52, s58, s22
	s_addc_u32 s53, s59, s23
	global_load_dwordx4 v[102:105], v186, s[52:53] nt
	global_load_dwordx4 v[98:101], v186, s[52:53] offset:1024 nt
	s_add_u32 s52, s56, s22
	s_addc_u32 s53, s57, s23
	global_load_dwordx4 v[174:177], v186, s[52:53] nt
	global_load_dwordx4 v[166:169], v186, s[52:53] offset:1024 nt
	s_add_u32 s52, s58, s24
	s_addc_u32 s53, s59, s25
	global_load_dwordx4 v[78:81], v186, s[52:53] nt
	global_load_dwordx4 v[74:77], v186, s[52:53] offset:1024 nt
	s_add_u32 s52, s56, s24
	s_addc_u32 s53, s57, s25
	global_load_dwordx4 v[170:173], v186, s[52:53] nt
	global_load_dwordx4 v[158:161], v186, s[52:53] offset:1024 nt
	s_add_u32 s52, s58, s28
	s_addc_u32 s53, s59, s29
	global_load_dwordx4 v[70:73], v186, s[52:53] nt
	global_load_dwordx4 v[66:69], v186, s[52:53] offset:1024 nt
	s_add_u32 s52, s56, s28
	s_addc_u32 s53, s57, s29
	global_load_dwordx4 v[162:165], v186, s[52:53] nt
	global_load_dwordx4 v[154:157], v186, s[52:53] offset:1024 nt
	v_pk_fma_f32 v[48:49], v[48:49], v[50:51], v[56:57] op_sel_hi:[1,0,1]
	v_pk_fma_f32 v[46:47], v[46:47], v[50:51], v[54:55] op_sel_hi:[1,0,1]
	v_pk_fma_f32 v[42:43], v[42:43], v[52:53], v[208:209] op_sel_hi:[1,0,1]
	v_pk_fma_f32 v[44:45], v[44:45], v[52:53], v[206:207] op_sel_hi:[1,0,1]
	v_pk_fma_f32 v[46:47], v[16:17], v[210:211], v[46:47] op_sel_hi:[1,0,1]
	v_pk_fma_f32 v[48:49], v[14:15], v[210:211], v[48:49] op_sel_hi:[1,0,1]
	v_pk_fma_f32 v[44:45], v[24:25], v[212:213], v[44:45] op_sel_hi:[1,0,1]
	v_pk_fma_f32 v[42:43], v[22:23], v[212:213], v[42:43] op_sel_hi:[1,0,1]
	v_pk_fma_f32 v[48:49], v[10:11], v[230:231], v[48:49] op_sel_hi:[1,0,1]
	v_pk_fma_f32 v[46:47], v[12:13], v[230:231], v[46:47] op_sel_hi:[1,0,1]
	v_pk_fma_f32 v[42:43], v[18:19], v[232:233], v[42:43] op_sel_hi:[1,0,1]
	v_pk_fma_f32 v[44:45], v[20:21], v[232:233], v[44:45] op_sel_hi:[1,0,1]
	s_waitcnt vmcnt(36)
	v_pk_fma_f32 v[206:207], v[4:5], v[236:237], v[46:47] op_sel_hi:[1,0,1]
	v_pk_fma_f32 v[208:209], v[2:3], v[236:237], v[48:49] op_sel_hi:[1,0,1]
	s_waitcnt vmcnt(35)
	v_pk_fma_f32 v[210:211], v[8:9], v[240:241], v[44:45] op_sel_hi:[1,0,1]
	v_pk_fma_f32 v[212:213], v[6:7], v[240:241], v[42:43] op_sel_hi:[1,0,1]
	s_waitcnt vmcnt(31)
	v_mul_f32_e32 v33, v222, v183
	v_fmac_f32_e32 v33, v221, v182
	v_pk_mul_f32 v[42:43], v[184:185], v[200:201]
	s_waitcnt vmcnt(30)
	v_mul_f32_e32 v44, v220, v179
	v_add_f32_e32 v33, v42, v33
	v_add_f32_e32 v33, v43, v33
	v_fmac_f32_e32 v44, v219, v178
	v_pk_mul_f32 v[42:43], v[180:181], v[198:199]
	v_add_f32_dpp v33, v33, v33 quad_perm:[1,0,3,2] row_mask:0xf bank_mask:0xf bound_ctrl:1
	v_add_f32_e32 v42, v42, v44
	v_add_f32_e32 v42, v43, v42
	v_add_f32_dpp v33, v33, v33 quad_perm:[2,3,0,1] row_mask:0xf bank_mask:0xf bound_ctrl:1
	s_waitcnt vmcnt(26)
	v_mul_f32_e32 v48, v220, v123
	v_fmac_f32_e32 v48, v219, v122
	v_add_f32_dpp v33, v33, v33 row_ror:4 row_mask:0xf bank_mask:0xf bound_ctrl:1
	s_waitcnt vmcnt(22)
	v_mul_f32_e32 v54, v220, v107
	v_fmac_f32_e32 v54, v219, v106
	v_add_f32_dpp v44, v33, v33 row_ror:8 row_mask:0xf bank_mask:0xf bound_ctrl:1
	v_add_f32_dpp v33, v42, v42 quad_perm:[1,0,3,2] row_mask:0xf bank_mask:0xf bound_ctrl:1
	v_pk_mul_f32 v[42:43], v[128:129], v[200:201]
	s_waitcnt vmcnt(18)
	v_mul_f32_e32 v91, v220, v91
	v_add_f32_dpp v33, v33, v33 quad_perm:[2,3,0,1] row_mask:0xf bank_mask:0xf bound_ctrl:1
	v_fmac_f32_e32 v91, v219, v90
	v_mov_b32_e32 v46, v44
	v_add_f32_dpp v33, v33, v33 row_ror:4 row_mask:0xf bank_mask:0xf bound_ctrl:1
	s_nop 0
	v_permlane16_swap_b32_e32 v44, v46
	v_add_f32_dpp v45, v33, v33 row_ror:8 row_mask:0xf bank_mask:0xf bound_ctrl:1
	v_mul_f32_e32 v33, v222, v127
	v_fmac_f32_e32 v33, v221, v126
	v_add_f32_e32 v33, v42, v33
	v_add_f32_e32 v33, v43, v33
	v_pk_mul_f32 v[42:43], v[124:125], v[198:199]
	v_mov_b32_e32 v47, v45
	v_add_f32_dpp v33, v33, v33 quad_perm:[1,0,3,2] row_mask:0xf bank_mask:0xf bound_ctrl:1
	v_add_f32_e32 v42, v42, v48
	v_add_f32_e32 v42, v43, v42
	v_add_f32_dpp v33, v33, v33 quad_perm:[2,3,0,1] row_mask:0xf bank_mask:0xf bound_ctrl:1
	v_permlane16_swap_b32_e32 v45, v47
	s_nop 0
	v_add_f32_dpp v33, v33, v33 row_ror:4 row_mask:0xf bank_mask:0xf bound_ctrl:1
	s_nop 1
	v_add_f32_dpp v48, v33, v33 row_ror:8 row_mask:0xf bank_mask:0xf bound_ctrl:1
	v_add_f32_dpp v33, v42, v42 quad_perm:[1,0,3,2] row_mask:0xf bank_mask:0xf bound_ctrl:1
	v_pk_mul_f32 v[42:43], v[112:113], v[200:201]
	v_mov_b32_e32 v50, v48
	v_add_f32_dpp v33, v33, v33 quad_perm:[2,3,0,1] row_mask:0xf bank_mask:0xf bound_ctrl:1
	s_nop 0
	v_permlane16_swap_b32_e32 v48, v50
	v_add_f32_dpp v33, v33, v33 row_ror:4 row_mask:0xf bank_mask:0xf bound_ctrl:1
	s_nop 1
	v_add_f32_dpp v49, v33, v33 row_ror:8 row_mask:0xf bank_mask:0xf bound_ctrl:1
	v_mul_f32_e32 v33, v222, v111
	v_fmac_f32_e32 v33, v221, v110
	v_add_f32_e32 v33, v42, v33
	v_add_f32_e32 v33, v43, v33
	v_pk_mul_f32 v[42:43], v[108:109], v[198:199]
	v_mov_b32_e32 v52, v49
	v_add_f32_dpp v33, v33, v33 quad_perm:[1,0,3,2] row_mask:0xf bank_mask:0xf bound_ctrl:1
	v_add_f32_e32 v42, v42, v54
	v_add_f32_e32 v42, v43, v42
	v_add_f32_dpp v33, v33, v33 quad_perm:[2,3,0,1] row_mask:0xf bank_mask:0xf bound_ctrl:1
	v_permlane16_swap_b32_e32 v49, v52
	s_nop 0
	v_add_f32_dpp v33, v33, v33 row_ror:4 row_mask:0xf bank_mask:0xf bound_ctrl:1
	s_nop 1
	v_add_f32_dpp v54, v33, v33 row_ror:8 row_mask:0xf bank_mask:0xf bound_ctrl:1
	v_add_f32_dpp v33, v42, v42 quad_perm:[1,0,3,2] row_mask:0xf bank_mask:0xf bound_ctrl:1
	v_pk_mul_f32 v[42:43], v[96:97], v[200:201]
	v_mov_b32_e32 v56, v54
	v_add_f32_dpp v33, v33, v33 quad_perm:[2,3,0,1] row_mask:0xf bank_mask:0xf bound_ctrl:1
	s_nop 0
	v_permlane16_swap_b32_e32 v54, v56
	v_add_f32_dpp v33, v33, v33 row_ror:4 row_mask:0xf bank_mask:0xf bound_ctrl:1
	s_nop 1
	v_add_f32_dpp v55, v33, v33 row_ror:8 row_mask:0xf bank_mask:0xf bound_ctrl:1
	v_mul_f32_e32 v33, v222, v95
	v_fmac_f32_e32 v33, v221, v94
	v_add_f32_e32 v33, v42, v33
	v_add_f32_e32 v33, v43, v33
	v_pk_mul_f32 v[42:43], v[92:93], v[198:199]
	v_mov_b32_e32 v57, v55
	v_add_f32_dpp v33, v33, v33 quad_perm:[1,0,3,2] row_mask:0xf bank_mask:0xf bound_ctrl:1
	v_add_f32_e32 v42, v42, v91
	v_add_f32_e32 v42, v43, v42
	v_add_f32_dpp v33, v33, v33 quad_perm:[2,3,0,1] row_mask:0xf bank_mask:0xf bound_ctrl:1
	v_permlane16_swap_b32_e32 v55, v57
	s_nop 0
	v_add_f32_dpp v33, v33, v33 row_ror:4 row_mask:0xf bank_mask:0xf bound_ctrl:1
	s_nop 1
	v_add_f32_dpp v90, v33, v33 row_ror:8 row_mask:0xf bank_mask:0xf bound_ctrl:1
	v_add_f32_dpp v33, v42, v42 quad_perm:[1,0,3,2] row_mask:0xf bank_mask:0xf bound_ctrl:1
	v_mov_b32_e32 v92, v90
	s_nop 1
	v_permlane16_swap_b32_e32 v90, v92
	v_add_f32_dpp v33, v33, v33 quad_perm:[2,3,0,1] row_mask:0xf bank_mask:0xf bound_ctrl:1
	s_nop 1
	v_add_f32_dpp v33, v33, v33 row_ror:4 row_mask:0xf bank_mask:0xf bound_ctrl:1
	v_pk_fma_f32 v[42:43], v[204:205], v[32:33], v[226:227] op_sel_hi:[1,0,1]
	s_nop 0
	v_pk_fma_f32 v[22:23], v[22:23], v[228:229], v[42:43] op_sel_hi:[1,0,1]
	v_add_f32_dpp v91, v33, v33 row_ror:8 row_mask:0xf bank_mask:0xf bound_ctrl:1
	v_pk_fma_f32 v[32:33], v[202:203], v[32:33], v[224:225] op_sel_hi:[1,0,1]
	v_pk_fma_f32 v[18:19], v[18:19], v[234:235], v[22:23] op_sel_hi:[1,0,1]
	v_pk_fma_f32 v[24:25], v[24:25], v[228:229], v[32:33] op_sel_hi:[1,0,1]
	v_pk_fma_f32 v[6:7], v[6:7], v[242:243], v[18:19] op_sel_hi:[1,0,1]
	v_max3_f32 v18, v39, v44, v48
	v_max3_f32 v19, v41, v46, v50
	v_mov_b32_e32 v93, v91
	v_pk_fma_f32 v[20:21], v[20:21], v[234:235], v[24:25] op_sel_hi:[1,0,1]
	v_max3_f32 v225, v18, v54, v90
	v_max3_f32 v227, v19, v56, v92
	v_pk_fma_f32 v[18:19], v[26:27], v[30:31], v[36:37] op_sel_hi:[1,0,1]
	v_permlane16_swap_b32_e32 v91, v93
	v_pk_fma_f32 v[8:9], v[8:9], v[242:243], v[20:21] op_sel_hi:[1,0,1]
	v_max3_f32 v20, v223, v45, v49
	v_max3_f32 v21, v229, v47, v52
	v_pk_fma_f32 v[14:15], v[14:15], v[38:39], v[18:19] op_sel_hi:[1,0,1]
	v_max3_f32 v233, v20, v55, v91
	v_max3_f32 v235, v21, v57, v93
	v_pk_fma_f32 v[20:21], v[28:29], v[30:31], v[34:35] op_sel_hi:[1,0,1]
	v_pk_fma_f32 v[10:11], v[10:11], v[40:41], v[14:15] op_sel_hi:[1,0,1]
	v_pk_fma_f32 v[16:17], v[16:17], v[38:39], v[20:21] op_sel_hi:[1,0,1]
	v_pk_fma_f32 v[2:3], v[2:3], v[238:239], v[10:11] op_sel_hi:[1,0,1]
	v_sub_f32_e32 v11, v223, v233
	v_pk_fma_f32 v[12:13], v[12:13], v[40:41], v[16:17] op_sel_hi:[1,0,1]
	v_exp_f32_e32 v24, v11
	v_sub_f32_e32 v11, v229, v235
	v_pk_fma_f32 v[4:5], v[4:5], v[238:239], v[12:13] op_sel_hi:[1,0,1]
	v_exp_f32_e32 v12, v11
	v_sub_f32_e32 v11, v44, v225
	v_exp_f32_e32 v14, v11
	v_sub_f32_e32 v11, v46, v227
	v_exp_f32_e32 v16, v11
	v_sub_f32_e32 v11, v45, v233
	v_sub_f32_e32 v10, v39, v225
	v_exp_f32_e32 v20, v11
	v_exp_f32_e32 v22, v10
	v_sub_f32_e32 v10, v41, v227
	v_exp_f32_e32 v10, v10
	v_sub_f32_e32 v13, v47, v235
	v_exp_f32_e32 v18, v13
	v_mov_b32_e32 v21, v20
	v_mov_b32_e32 v19, v16
	v_fmac_f32_e32 v21, v231, v24
	v_sub_f32_e32 v23, v55, v233
	v_fmac_f32_e32 v19, v53, v10
	v_pk_mul_f32 v[182:183], v[84:85], v[20:21] op_sel_hi:[1,0]
	v_pk_mul_f32 v[184:185], v[82:83], v[20:21] op_sel_hi:[1,0]
	v_sub_f32_e32 v20, v49, v233
	v_exp_f32_e32 v232, v23
	v_sub_f32_e32 v23, v57, v235
	v_fma_f32 v11, v31, v12, v18
	v_pk_mul_f32 v[202:203], v[84:85], v[18:19] op_sel_hi:[1,0]
	v_pk_mul_f32 v[204:205], v[82:83], v[18:19] op_sel_hi:[1,0]
	v_sub_f32_e32 v18, v48, v225
	v_exp_f32_e32 v226, v20
	v_sub_f32_e32 v20, v52, v235
	v_exp_f32_e32 v234, v23
	v_sub_f32_e32 v23, v90, v225
	v_exp_f32_e32 v224, v18
	v_sub_f32_e32 v18, v50, v227
	v_exp_f32_e32 v228, v20
	v_sub_f32_e32 v20, v54, v225
	v_exp_f32_e32 v236, v23
	v_sub_f32_e32 v23, v92, v227
	v_exp_f32_e32 v18, v18
	v_exp_f32_e32 v230, v20
	v_sub_f32_e32 v20, v56, v227
	v_exp_f32_e32 v238, v23
	v_sub_f32_e32 v23, v91, v233
	v_exp_f32_e32 v20, v20
	v_exp_f32_e32 v240, v23
	v_sub_f32_e32 v23, v93, v235
	v_mov_b32_e32 v13, v14
	v_exp_f32_e32 v242, v23
	v_fmac_f32_e32 v13, v51, v22
	v_add_f32_e32 v13, v224, v13
	v_add_f32_e32 v19, v18, v19
	v_add_f32_e32 v21, v226, v21
	v_add_f32_e32 v11, v228, v11
	v_add_f32_e32 v13, v230, v13
	v_add_f32_e32 v19, v20, v19
	v_add_f32_e32 v21, v232, v21
	v_add_f32_e32 v11, v234, v11
	v_pk_mul_f32 v[178:179], v[88:89], v[14:15] op_sel_hi:[1,0]
	v_pk_mul_f32 v[180:181], v[86:87], v[14:15] op_sel_hi:[1,0]
	v_pk_mul_f32 v[14:15], v[88:89], v[16:17] op_sel_hi:[1,0]
	v_pk_mul_f32 v[16:17], v[86:87], v[16:17] op_sel_hi:[1,0]
	v_add_f32_e32 v13, v236, v13
	v_add_f32_e32 v19, v238, v19
	v_add_f32_e32 v21, v240, v21
	v_add_f32_e32 v11, v242, v11
	s_add_u32 s52, s8, s30
	s_addc_u32 s53, s9, s31
	global_load_dwordx4 v[126:129], v186, s[52:53] nt
	global_load_dwordx4 v[122:125], v186, s[52:53] offset:1024 nt
	s_add_u32 s52, s50, s30
	s_addc_u32 s53, s51, s31
	global_load_dwordx4 v[30:33], v186, s[52:53] nt
	global_load_dwordx4 v[54:57], v186, s[52:53] offset:1024 nt
	s_add_u32 s52, s8, s36
	s_addc_u32 s53, s9, s37
	global_load_dwordx4 v[110:113], v186, s[52:53] nt
	global_load_dwordx4 v[106:109], v186, s[52:53] offset:1024 nt
	s_add_u32 s52, s50, s36
	s_addc_u32 s53, s51, s37
	global_load_dwordx4 v[34:37], v186, s[52:53] nt
	global_load_dwordx4 v[50:53], v186, s[52:53] offset:1024 nt
	s_add_u32 s52, s8, s38
	s_addc_u32 s53, s9, s39
	global_load_dwordx4 v[94:97], v186, s[52:53] nt
	global_load_dwordx4 v[90:93], v186, s[52:53] offset:1024 nt
	s_add_u32 s52, s50, s38
	s_addc_u32 s53, s51, s39
	global_load_dwordx4 v[38:41], v186, s[52:53] nt
	global_load_dwordx4 v[46:49], v186, s[52:53] offset:1024 nt
	s_add_u32 s52, s8, s40
	s_addc_u32 s53, s9, s41
	global_load_dwordx4 v[86:89], v186, s[52:53] nt
	global_load_dwordx4 v[82:85], v186, s[52:53] offset:1024 nt
	s_add_u32 s52, s50, s40
	s_addc_u32 s53, s51, s41
	global_load_dwordx4 v[26:29], v186, s[52:53] nt
	global_load_dwordx4 v[42:45], v186, s[52:53] offset:1024 nt
	v_pk_fma_f32 v[180:181], v[208:209], v[22:23], v[180:181] op_sel_hi:[1,0,1]
	v_pk_fma_f32 v[22:23], v[206:207], v[22:23], v[178:179] op_sel_hi:[1,0,1]
	v_pk_fma_f32 v[178:179], v[212:213], v[24:25], v[184:185] op_sel_hi:[1,0,1]
	v_pk_fma_f32 v[24:25], v[210:211], v[24:25], v[182:183] op_sel_hi:[1,0,1]
	v_pk_fma_f32 v[22:23], v[132:133], v[224:225], v[22:23] op_sel_hi:[1,0,1]
	v_pk_fma_f32 v[180:181], v[130:131], v[224:225], v[180:181] op_sel_hi:[1,0,1]
	v_pk_fma_f32 v[24:25], v[144:145], v[226:227], v[24:25] op_sel_hi:[1,0,1]
	v_pk_fma_f32 v[178:179], v[142:143], v[226:227], v[178:179] op_sel_hi:[1,0,1]
	v_pk_fma_f32 v[182:183], v[134:135], v[230:231], v[180:181] op_sel_hi:[1,0,1]
	v_pk_fma_f32 v[22:23], v[136:137], v[230:231], v[22:23] op_sel_hi:[1,0,1]
	v_pk_fma_f32 v[206:207], v[146:147], v[232:233], v[178:179] op_sel_hi:[1,0,1]
	v_pk_fma_f32 v[24:25], v[148:149], v[232:233], v[24:25] op_sel_hi:[1,0,1]
	s_waitcnt vmcnt(33)
	v_pk_fma_f32 v[180:181], v[140:141], v[236:237], v[22:23] op_sel_hi:[1,0,1]
	v_pk_fma_f32 v[184:185], v[138:139], v[236:237], v[182:183] op_sel_hi:[1,0,1]
	s_waitcnt vmcnt(32)
	v_pk_fma_f32 v[178:179], v[152:153], v[240:241], v[24:25] op_sel_hi:[1,0,1]
	v_pk_fma_f32 v[182:183], v[150:151], v[240:241], v[206:207] op_sel_hi:[1,0,1]
	s_waitcnt vmcnt(31)
	v_mul_f32_e32 v24, v222, v119
	v_fmac_f32_e32 v24, v221, v118
	v_pk_mul_f32 v[22:23], v[120:121], v[200:201]
	s_waitcnt vmcnt(30)
	v_mul_f32_e32 v25, v220, v115
	v_add_f32_e32 v22, v22, v24
	v_add_f32_e32 v24, v23, v22
	v_fmac_f32_e32 v25, v219, v114
	v_pk_mul_f32 v[22:23], v[116:117], v[198:199]
	s_waitcnt vmcnt(27)
	v_mul_f32_e32 v103, v222, v103
	v_add_f32_e32 v22, v22, v25
	v_add_f32_e32 v22, v23, v22
	v_add_f32_dpp v23, v24, v24 quad_perm:[1,0,3,2] row_mask:0xf bank_mask:0xf bound_ctrl:1
	v_fmac_f32_e32 v103, v221, v102
	v_add_f32_dpp v22, v22, v22 quad_perm:[1,0,3,2] row_mask:0xf bank_mask:0xf bound_ctrl:1
	v_add_f32_dpp v23, v23, v23 quad_perm:[2,3,0,1] row_mask:0xf bank_mask:0xf bound_ctrl:1
	s_waitcnt vmcnt(26)
	v_mul_f32_e32 v99, v220, v99
	v_add_f32_dpp v22, v22, v22 quad_perm:[2,3,0,1] row_mask:0xf bank_mask:0xf bound_ctrl:1
	v_add_f32_dpp v23, v23, v23 row_ror:4 row_mask:0xf bank_mask:0xf bound_ctrl:1
	v_fmac_f32_e32 v99, v219, v98
	v_add_f32_dpp v22, v22, v22 row_ror:4 row_mask:0xf bank_mask:0xf bound_ctrl:1
	v_add_f32_dpp v24, v23, v23 row_ror:8 row_mask:0xf bank_mask:0xf bound_ctrl:1
	s_waitcnt vmcnt(23)
	v_mul_f32_e32 v79, v222, v79
	v_add_f32_dpp v25, v22, v22 row_ror:8 row_mask:0xf bank_mask:0xf bound_ctrl:1
	v_pk_mul_f32 v[22:23], v[104:105], v[200:201]
	v_fmac_f32_e32 v79, v221, v78
	v_add_f32_e32 v22, v22, v103
	v_add_f32_e32 v102, v23, v22
	v_pk_mul_f32 v[22:23], v[100:101], v[198:199]
	s_waitcnt vmcnt(22)
	v_mul_f32_e32 v75, v220, v75
	v_add_f32_e32 v22, v22, v99
	v_add_f32_e32 v22, v23, v22
	v_add_f32_dpp v23, v102, v102 quad_perm:[1,0,3,2] row_mask:0xf bank_mask:0xf bound_ctrl:1
	v_fmac_f32_e32 v75, v219, v74
	v_add_f32_dpp v22, v22, v22 quad_perm:[1,0,3,2] row_mask:0xf bank_mask:0xf bound_ctrl:1
	v_add_f32_dpp v23, v23, v23 quad_perm:[2,3,0,1] row_mask:0xf bank_mask:0xf bound_ctrl:1
	s_waitcnt vmcnt(19)
	v_mul_f32_e32 v71, v222, v71
	v_add_f32_dpp v22, v22, v22 quad_perm:[2,3,0,1] row_mask:0xf bank_mask:0xf bound_ctrl:1
	v_add_f32_dpp v23, v23, v23 row_ror:4 row_mask:0xf bank_mask:0xf bound_ctrl:1
	v_fmac_f32_e32 v71, v221, v70
	v_add_f32_dpp v22, v22, v22 row_ror:4 row_mask:0xf bank_mask:0xf bound_ctrl:1
	v_add_f32_dpp v98, v23, v23 row_ror:8 row_mask:0xf bank_mask:0xf bound_ctrl:1
	s_waitcnt vmcnt(18)
	v_mul_f32_e32 v67, v220, v67
	v_add_f32_dpp v99, v22, v22 row_ror:8 row_mask:0xf bank_mask:0xf bound_ctrl:1
	v_pk_mul_f32 v[22:23], v[80:81], v[200:201]
	v_fmac_f32_e32 v67, v219, v66
	v_add_f32_e32 v22, v22, v79
	v_add_f32_e32 v78, v23, v22
	v_pk_mul_f32 v[22:23], v[76:77], v[198:199]
	v_pk_fma_f32 v[6:7], v[6:7], v[12:13], v[204:205] op_sel_hi:[1,0,1]
	v_add_f32_e32 v22, v22, v75
	v_add_f32_e32 v22, v23, v22
	v_add_f32_dpp v23, v78, v78 quad_perm:[1,0,3,2] row_mask:0xf bank_mask:0xf bound_ctrl:1
	v_mov_b32_e32 v114, v24
	v_add_f32_dpp v22, v22, v22 quad_perm:[1,0,3,2] row_mask:0xf bank_mask:0xf bound_ctrl:1
	v_add_f32_dpp v23, v23, v23 quad_perm:[2,3,0,1] row_mask:0xf bank_mask:0xf bound_ctrl:1
	v_mov_b32_e32 v100, v98
	v_add_f32_dpp v22, v22, v22 quad_perm:[2,3,0,1] row_mask:0xf bank_mask:0xf bound_ctrl:1
	v_add_f32_dpp v23, v23, v23 row_ror:4 row_mask:0xf bank_mask:0xf bound_ctrl:1
	v_pk_fma_f32 v[8:9], v[8:9], v[12:13], v[202:203] op_sel_hi:[1,0,1]
	v_add_f32_dpp v22, v22, v22 row_ror:4 row_mask:0xf bank_mask:0xf bound_ctrl:1
	v_add_f32_dpp v74, v23, v23 row_ror:8 row_mask:0xf bank_mask:0xf bound_ctrl:1
	v_pk_fma_f32 v[6:7], v[142:143], v[228:229], v[6:7] op_sel_hi:[1,0,1]
	v_add_f32_dpp v75, v22, v22 row_ror:8 row_mask:0xf bank_mask:0xf bound_ctrl:1
	v_pk_mul_f32 v[22:23], v[72:73], v[200:201]
	v_permlane16_swap_b32_e32 v24, v114
	v_add_f32_e32 v22, v22, v71
	v_add_f32_e32 v70, v23, v22
	v_pk_mul_f32 v[22:23], v[68:69], v[198:199]
	v_permlane16_swap_b32_e32 v98, v100
	v_add_f32_e32 v22, v22, v67
	v_add_f32_e32 v22, v23, v22
	v_add_f32_dpp v23, v70, v70 quad_perm:[1,0,3,2] row_mask:0xf bank_mask:0xf bound_ctrl:1
	v_mov_b32_e32 v76, v74
	v_add_f32_dpp v22, v22, v22 quad_perm:[1,0,3,2] row_mask:0xf bank_mask:0xf bound_ctrl:1
	v_add_f32_dpp v23, v23, v23 quad_perm:[2,3,0,1] row_mask:0xf bank_mask:0xf bound_ctrl:1
	v_pk_fma_f32 v[8:9], v[144:145], v[228:229], v[8:9] op_sel_hi:[1,0,1]
	v_add_f32_dpp v22, v22, v22 quad_perm:[2,3,0,1] row_mask:0xf bank_mask:0xf bound_ctrl:1
	v_add_f32_dpp v23, v23, v23 row_ror:4 row_mask:0xf bank_mask:0xf bound_ctrl:1
	v_pk_fma_f32 v[6:7], v[146:147], v[234:235], v[6:7] op_sel_hi:[1,0,1]
	v_add_f32_dpp v22, v22, v22 row_ror:4 row_mask:0xf bank_mask:0xf bound_ctrl:1
	v_add_f32_dpp v23, v23, v23 row_ror:8 row_mask:0xf bank_mask:0xf bound_ctrl:1
	v_mov_b32_e32 v66, v23
	v_pk_fma_f32 v[2:3], v[2:3], v[10:11], v[16:17] op_sel_hi:[1,0,1]
	v_mov_b32_e32 v115, v25
	v_mov_b32_e32 v101, v99
	v_permlane16_swap_b32_e32 v74, v76
	v_add_f32_dpp v22, v22, v22 row_ror:8 row_mask:0xf bank_mask:0xf bound_ctrl:1
	v_permlane16_swap_b32_e32 v23, v66
	v_pk_fma_f32 v[8:9], v[148:149], v[234:235], v[8:9] op_sel_hi:[1,0,1]
	v_pk_fma_f32 v[148:149], v[150:151], v[242:243], v[6:7] op_sel_hi:[1,0,1]
	v_max3_f32 v6, v225, v24, v98
	v_pk_fma_f32 v[4:5], v[4:5], v[10:11], v[14:15] op_sel_hi:[1,0,1]
	v_pk_fma_f32 v[2:3], v[130:131], v[18:19], v[2:3] op_sel_hi:[1,0,1]
	v_permlane16_swap_b32_e32 v25, v115
	v_permlane16_swap_b32_e32 v99, v101
	v_mov_b32_e32 v77, v75
	v_mov_b32_e32 v67, v22
	v_max3_f32 v7, v227, v114, v100
	v_max3_f32 v142, v6, v74, v23
	v_pk_fma_f32 v[4:5], v[132:133], v[18:19], v[4:5] op_sel_hi:[1,0,1]
	v_pk_fma_f32 v[2:3], v[134:135], v[20:21], v[2:3] op_sel_hi:[1,0,1]
	v_permlane16_swap_b32_e32 v75, v77
	v_permlane16_swap_b32_e32 v22, v67
	v_pk_fma_f32 v[146:147], v[152:153], v[242:243], v[8:9] op_sel_hi:[1,0,1]
	v_max3_f32 v8, v233, v25, v99
	v_max3_f32 v144, v7, v76, v66
	v_pk_fma_f32 v[4:5], v[136:137], v[20:21], v[4:5] op_sel_hi:[1,0,1]
	v_pk_fma_f32 v[136:137], v[138:139], v[238:239], v[2:3] op_sel_hi:[1,0,1]
	v_sub_f32_e32 v2, v225, v142
	v_max3_f32 v9, v235, v115, v101
	v_max3_f32 v143, v8, v75, v22
	v_exp_f32_e32 v138, v2
	v_sub_f32_e32 v2, v227, v144
	v_max3_f32 v145, v9, v77, v67
	v_pk_fma_f32 v[134:135], v[140:141], v[238:239], v[4:5] op_sel_hi:[1,0,1]
	v_exp_f32_e32 v140, v2
	v_sub_f32_e32 v2, v233, v143
	v_exp_f32_e32 v150, v2
	v_sub_f32_e32 v2, v235, v145
	v_exp_f32_e32 v152, v2
	v_sub_f32_e32 v2, v24, v142
	v_exp_f32_e32 v2, v2
	v_sub_f32_e32 v4, v115, v145
	v_exp_f32_e32 v4, v4
	v_sub_f32_e32 v3, v114, v144
	v_mov_b32_e32 v5, v2
	v_exp_f32_e32 v6, v3
	v_sub_f32_e32 v3, v25, v143
	v_fmac_f32_e32 v5, v13, v138
	v_exp_f32_e32 v8, v3
	v_fma_f32 v3, v11, v152, v4
	v_pk_mul_f32 v[210:211], v[60:61], v[4:5] op_sel_hi:[1,0]
	v_pk_mul_f32 v[212:213], v[58:59], v[4:5] op_sel_hi:[1,0]
	v_sub_f32_e32 v4, v98, v142
	v_exp_f32_e32 v220, v4
	v_sub_f32_e32 v4, v100, v144
	v_exp_f32_e32 v222, v4
	v_sub_f32_e32 v4, v99, v143
	v_exp_f32_e32 v224, v4
	v_pk_mul_f32 v[198:199], v[64:65], v[2:3] op_sel_hi:[1,0]
	v_pk_mul_f32 v[200:201], v[62:63], v[2:3] op_sel_hi:[1,0]
	v_mov_b32_e32 v2, v6
	v_pk_mul_f32 v[202:203], v[64:65], v[6:7] op_sel_hi:[1,0]
	v_pk_mul_f32 v[204:205], v[62:63], v[6:7] op_sel_hi:[1,0]
	v_mov_b32_e32 v6, v8
	v_fmac_f32_e32 v6, v21, v150
	v_sub_f32_e32 v4, v101, v145
	v_exp_f32_e32 v226, v4
	v_add_f32_e32 v4, v220, v5
	v_add_f32_e32 v5, v224, v6
	v_sub_f32_e32 v6, v74, v142
	v_exp_f32_e32 v228, v6
	v_sub_f32_e32 v6, v76, v144
	v_exp_f32_e32 v230, v6
	v_sub_f32_e32 v6, v75, v143
	v_exp_f32_e32 v232, v6
	v_sub_f32_e32 v6, v77, v145
	v_exp_f32_e32 v234, v6
	v_sub_f32_e32 v6, v23, v142
	v_exp_f32_e32 v236, v6
	v_sub_f32_e32 v6, v66, v144
	v_exp_f32_e32 v238, v6
	v_sub_f32_e32 v6, v22, v143
	v_exp_f32_e32 v240, v6
	v_sub_f32_e32 v6, v67, v145
	v_exp_f32_e32 v242, v6
	v_fmac_f32_e32 v2, v19, v140
	v_add_f32_e32 v2, v222, v2
	v_add_f32_e32 v3, v226, v3
	v_add_f32_e32 v4, v228, v4
	v_add_f32_e32 v2, v230, v2
	v_add_f32_e32 v5, v232, v5
	v_add_f32_e32 v3, v234, v3
	v_add_f32_e32 v130, v236, v4
	v_add_f32_e32 v132, v238, v2
	v_add_f32_e32 v131, v240, v5
	v_add_f32_e32 v133, v242, v3
	v_pk_mul_f32 v[206:207], v[60:61], v[8:9] op_sel_hi:[1,0]
	v_pk_mul_f32 v[208:209], v[58:59], v[8:9] op_sel_hi:[1,0]
	s_add_u32 s52, s8, s42
	s_addc_u32 s53, s9, s43
	global_load_dwordx4 v[118:121], v186, s[52:53] nt
	global_load_dwordx4 v[114:117], v186, s[52:53] offset:1024 nt
	s_add_u32 s52, s50, s42
	s_addc_u32 s53, s51, s43
	global_load_dwordx4 v[62:65], v186, s[52:53] nt
	global_load_dwordx4 v[58:61], v186, s[52:53] offset:1024 nt
	s_add_u32 s52, s8, s44
	s_addc_u32 s53, s9, s45
	global_load_dwordx4 v[102:105], v186, s[52:53] nt
	global_load_dwordx4 v[98:101], v186, s[52:53] offset:1024 nt
	s_add_u32 s52, s50, s44
	s_addc_u32 s53, s51, s45
	global_load_dwordx4 v[14:17], v186, s[52:53] nt
	global_load_dwordx4 v[22:25], v186, s[52:53] offset:1024 nt
	s_add_u32 s52, s8, s46
	s_addc_u32 s53, s9, s47
	global_load_dwordx4 v[74:77], v186, s[52:53] nt
	global_load_dwordx4 v[78:81], v186, s[52:53] offset:1024 nt
	s_add_u32 s52, s50, s46
	s_addc_u32 s53, s51, s47
	global_load_dwordx4 v[10:13], v186, s[52:53] nt
	global_load_dwordx4 v[18:21], v186, s[52:53] offset:1024 nt
	s_add_u32 s52, s8, s48
	s_addc_u32 s53, s9, s49
	global_load_dwordx4 v[70:73], v186, s[52:53] nt
	global_load_dwordx4 v[66:69], v186, s[52:53] offset:1024 nt
	s_add_u32 s52, s50, s48
	s_addc_u32 s53, s51, s49
	global_load_dwordx4 v[2:5], v186, s[52:53] nt
	global_load_dwordx4 v[6:9], v186, s[52:53] offset:1024 nt
	v_pk_fma_f32 v[184:185], v[184:185], v[138:139], v[200:201] op_sel_hi:[1,0,1]
	v_pk_fma_f32 v[138:139], v[180:181], v[138:139], v[198:199] op_sel_hi:[1,0,1]
	v_pk_fma_f32 v[136:137], v[136:137], v[140:141], v[204:205] op_sel_hi:[1,0,1]
	v_pk_fma_f32 v[134:135], v[134:135], v[140:141], v[202:203] op_sel_hi:[1,0,1]
	v_pk_fma_f32 v[140:141], v[182:183], v[150:151], v[208:209] op_sel_hi:[1,0,1]
	v_pk_fma_f32 v[150:151], v[178:179], v[150:151], v[206:207] op_sel_hi:[1,0,1]
	v_pk_fma_f32 v[148:149], v[148:149], v[152:153], v[212:213] op_sel_hi:[1,0,1]
	v_pk_fma_f32 v[146:147], v[146:147], v[152:153], v[210:211] op_sel_hi:[1,0,1]
	v_pk_fma_f32 v[138:139], v[176:177], v[220:221], v[138:139] op_sel_hi:[1,0,1]
	v_pk_fma_f32 v[152:153], v[174:175], v[220:221], v[184:185] op_sel_hi:[1,0,1]
	v_pk_fma_f32 v[134:135], v[176:177], v[222:223], v[134:135] op_sel_hi:[1,0,1]
	v_pk_fma_f32 v[136:137], v[174:175], v[222:223], v[136:137] op_sel_hi:[1,0,1]
	v_pk_fma_f32 v[150:151], v[168:169], v[224:225], v[150:151] op_sel_hi:[1,0,1]
	v_pk_fma_f32 v[140:141], v[166:167], v[224:225], v[140:141] op_sel_hi:[1,0,1]
	v_pk_fma_f32 v[146:147], v[168:169], v[226:227], v[146:147] op_sel_hi:[1,0,1]
	v_pk_fma_f32 v[148:149], v[166:167], v[226:227], v[148:149] op_sel_hi:[1,0,1]
	v_pk_fma_f32 v[152:153], v[170:171], v[228:229], v[152:153] op_sel_hi:[1,0,1]
	v_pk_fma_f32 v[138:139], v[172:173], v[228:229], v[138:139] op_sel_hi:[1,0,1]
	v_pk_fma_f32 v[166:167], v[170:171], v[230:231], v[136:137] op_sel_hi:[1,0,1]
	v_pk_fma_f32 v[168:169], v[172:173], v[230:231], v[134:135] op_sel_hi:[1,0,1]
	v_pk_fma_f32 v[170:171], v[158:159], v[232:233], v[140:141] op_sel_hi:[1,0,1]
	v_pk_fma_f32 v[150:151], v[160:161], v[232:233], v[150:151] op_sel_hi:[1,0,1]
	v_pk_fma_f32 v[158:159], v[158:159], v[234:235], v[148:149] op_sel_hi:[1,0,1]
	v_pk_fma_f32 v[160:161], v[160:161], v[234:235], v[146:147] op_sel_hi:[1,0,1]
	s_waitcnt vmcnt(33)
	v_pk_fma_f32 v[136:137], v[164:165], v[236:237], v[138:139] op_sel_hi:[1,0,1]
	v_pk_fma_f32 v[134:135], v[162:163], v[236:237], v[152:153] op_sel_hi:[1,0,1]
	v_pk_fma_f32 v[140:141], v[164:165], v[238:239], v[168:169] op_sel_hi:[1,0,1]
	v_pk_fma_f32 v[138:139], v[162:163], v[238:239], v[166:167] op_sel_hi:[1,0,1]
	s_waitcnt vmcnt(32)
	v_pk_fma_f32 v[148:149], v[156:157], v[240:241], v[150:151] op_sel_hi:[1,0,1]
	v_pk_fma_f32 v[146:147], v[154:155], v[240:241], v[170:171] op_sel_hi:[1,0,1]
	v_pk_fma_f32 v[152:153], v[156:157], v[242:243], v[160:161] op_sel_hi:[1,0,1]
	v_pk_fma_f32 v[150:151], v[154:155], v[242:243], v[158:159] op_sel_hi:[1,0,1]
	ds_write_b128 v1, v[134:137]
	ds_write_b128 v1, v[146:149] offset:1024
	ds_write_b128 v1, v[138:141] offset:2048
	ds_write_b128 v1, v[150:153] offset:3072
	s_and_saveexec_b64 s[52:53], s[2:3]
	s_cbranch_execz .LBB0_888
	v_add_u32_e32 v134, 0x8000, v214
	ds_write2_b32 v134, v142, v144 offset1:1
	v_add_u32_e32 v134, 0x8010, v214
	ds_write2_b32 v134, v143, v145 offset1:1
	v_add_u32_e32 v134, 0x8100, v214
	ds_write2_b32 v134, v130, v132 offset1:1
	v_add_u32_e32 v130, 0x8110, v214
	ds_write2_b32 v130, v131, v133 offset1:1
